# GEMM compute segments: the mid-segment s_setprio 0/1 flip pair between the two 16-MFMA runs removed (68 sites)
# baseline (speedup 1.0000x reference)
.LBB0_372:
	s_ashr_i32 s21, s20, 31
	s_lshl_b64 s[22:23], s[20:21], 19
	s_add_u32 s22, s96, s22
	s_addc_u32 s23, s97, s23
	s_and_b64 s[24:25], s[4:5], exec
	s_cselect_b32 s21, s23, s29
	s_cselect_b32 s27, s22, s28
	s_ashr_i32 s13, s12, 31
	s_lshl_b64 s[24:25], s[12:13], 19
	s_add_u32 s24, s14, s24
	s_addc_u32 s25, s15, s25
	s_and_b64 s[36:37], s[4:5], exec
	s_cselect_b32 s13, s25, s31
	s_cselect_b32 s48, s24, s30
	s_add_u32 s49, s30, 0x100
	s_addc_u32 s50, s31, 0
	s_mov_b32 s51, -2
	ds_read_b128 v[150:153], v180
	ds_read_b128 v[154:157], v180 offset:1024
	ds_read_b128 v[158:161], v180 offset:2048
	ds_read_b128 v[162:165], v180 offset:3072
	ds_read_b128 v[184:187], v181
	ds_read_b128 v[188:191], v181 offset:1024
	ds_read_b128 v[192:195], v181 offset:2048
	ds_read_b128 v[196:199], v181 offset:3072
	s_add_u32 s30, s28, 0x100
	s_addc_u32 s31, s29, 0
	s_cmp_eq_u32 s51, 12
	s_cselect_b32 s39, s21, s31
	s_cselect_b32 s38, s27, s30
	s_cselect_b32 s37, s13, s50
	s_cselect_b32 s36, s48, s49
	v_lshl_add_u64 v[166:167], s[28:29], 0, v[142:143]
	s_add_i32 m0, s17, 0xc000
	ds_read_b128 v[200:203], v182
	ds_read_b128 v[204:207], v182 offset:1024
	ds_read_b128 v[208:211], v182 offset:2048
	ds_read_b128 v[212:215], v182 offset:3072
	ds_read_b128 v[216:219], v182 offset:4096
	ds_read_b128 v[220:223], v182 offset:5120
	ds_read_b128 v[224:227], v182 offset:6144
	ds_read_b128 v[228:231], v182 offset:7168
	global_load_lds_dwordx4 v[166:167], off
	v_lshl_add_u64 v[166:167], s[28:29], 0, v[144:145]
	s_add_i32 m0, s17, 0xe000
	s_nop 0
	global_load_lds_dwordx4 v[166:167], off
	s_waitcnt vmcnt(8)
	s_waitcnt lgkmcnt(0)
	s_barrier
	s_setprio 1
	s_waitcnt lgkmcnt(0)
	v_mfma_f32_16x16x32_bf16 v[82:85], v[150:153], v[200:203], 0
	v_mfma_f32_16x16x32_bf16 v[78:81], v[158:161], v[200:203], 0
	v_mfma_f32_16x16x32_bf16 v[70:73], v[150:153], v[208:211], 0
	v_mfma_f32_16x16x32_bf16 v[66:69], v[158:161], v[208:211], 0
	v_mfma_f32_16x16x32_bf16 v[62:65], v[150:153], v[216:219], 0
	v_mfma_f32_16x16x32_bf16 v[58:61], v[158:161], v[216:219], 0
	v_mfma_f32_16x16x32_bf16 v[54:57], v[150:153], v[224:227], 0
	v_mfma_f32_16x16x32_bf16 v[50:53], v[158:161], v[224:227], 0
	v_mfma_f32_16x16x32_bf16 v[82:85], v[154:157], v[204:207], v[82:85]
	v_mfma_f32_16x16x32_bf16 v[78:81], v[162:165], v[204:207], v[78:81]
	v_mfma_f32_16x16x32_bf16 v[70:73], v[154:157], v[212:215], v[70:73]
	v_mfma_f32_16x16x32_bf16 v[66:69], v[162:165], v[212:215], v[66:69]
	v_mfma_f32_16x16x32_bf16 v[62:65], v[154:157], v[220:223], v[62:65]
	v_mfma_f32_16x16x32_bf16 v[58:61], v[162:165], v[220:223], v[58:61]
	v_mfma_f32_16x16x32_bf16 v[54:57], v[154:157], v[228:231], v[54:57]
	v_mfma_f32_16x16x32_bf16 v[50:53], v[162:165], v[228:231], v[50:53]
	v_mfma_f32_16x16x32_bf16 v[126:129], v[184:187], v[200:203], 0
	v_mfma_f32_16x16x32_bf16 v[122:125], v[192:195], v[200:203], 0
	v_mfma_f32_16x16x32_bf16 v[118:121], v[184:187], v[208:211], 0
	v_mfma_f32_16x16x32_bf16 v[114:117], v[192:195], v[208:211], 0
	v_mfma_f32_16x16x32_bf16 v[110:113], v[184:187], v[216:219], 0
	v_mfma_f32_16x16x32_bf16 v[106:109], v[192:195], v[216:219], 0
	v_mfma_f32_16x16x32_bf16 v[102:105], v[184:187], v[224:227], 0
	v_mfma_f32_16x16x32_bf16 v[98:101], v[192:195], v[224:227], 0
	v_mfma_f32_16x16x32_bf16 v[126:129], v[188:191], v[204:207], v[126:129]
	v_mfma_f32_16x16x32_bf16 v[122:125], v[196:199], v[204:207], v[122:125]
	v_mfma_f32_16x16x32_bf16 v[118:121], v[188:191], v[212:215], v[118:121]
	v_mfma_f32_16x16x32_bf16 v[114:117], v[196:199], v[212:215], v[114:117]
	v_mfma_f32_16x16x32_bf16 v[110:113], v[188:191], v[220:223], v[110:113]
	v_mfma_f32_16x16x32_bf16 v[106:109], v[196:199], v[220:223], v[106:109]
	v_mfma_f32_16x16x32_bf16 v[102:105], v[188:191], v[228:231], v[102:105]
	v_mfma_f32_16x16x32_bf16 v[98:101], v[196:199], v[228:231], v[98:101]
	s_setprio 0
	s_barrier
	s_add_i32 s28, s45, s16
	v_lshl_add_u64 v[166:167], s[36:37], 0, v[134:135]
	s_mov_b32 m0, s28
	ds_read_b128 v[200:203], v182 offset:16384
	ds_read_b128 v[204:207], v182 offset:17408
	ds_read_b128 v[208:211], v182 offset:18432
	ds_read_b128 v[212:215], v182 offset:19456
	ds_read_b128 v[216:219], v182 offset:20480
	ds_read_b128 v[220:223], v182 offset:21504
	ds_read_b128 v[224:227], v182 offset:22528
	ds_read_b128 v[228:231], v182 offset:23552
	global_load_lds_dwordx4 v[166:167], off
	s_add_i32 m0, s28, 0x2000
	s_add_u32 s28, s36, 0x40000
	v_lshl_add_u64 v[232:233], s[36:37], 0, v[136:137]
	s_addc_u32 s29, s37, 0
	s_add_i32 s52, s46, s16
	global_load_lds_dwordx4 v[232:233], off
	v_lshl_add_u64 v[234:235], s[28:29], 0, v[134:135]
	s_mov_b32 m0, s52
	v_lshl_add_u64 v[236:237], s[38:39], 0, v[130:131]
	global_load_lds_dwordx4 v[234:235], off
	v_lshl_add_u64 v[234:235], s[28:29], 0, v[136:137]
	s_add_i32 m0, s52, 0x2000
	s_nop 0
	global_load_lds_dwordx4 v[234:235], off
	v_lshl_add_u64 v[234:235], s[38:39], 0, v[132:133]
	s_mov_b32 m0, s17
	s_nop 0
	global_load_lds_dwordx4 v[234:235], off
	s_mov_b32 m0, s34
	s_nop 0
	global_load_lds_dwordx4 v[236:237], off
	s_waitcnt vmcnt(8)
	s_waitcnt lgkmcnt(0)
	s_barrier
	s_setprio 1
	s_waitcnt lgkmcnt(0)
	v_mfma_f32_16x16x32_bf16 v[38:41], v[150:153], v[200:203], 0
	v_mfma_f32_16x16x32_bf16 v[34:37], v[158:161], v[200:203], 0
	v_mfma_f32_16x16x32_bf16 v[26:29], v[150:153], v[208:211], 0
	v_mfma_f32_16x16x32_bf16 v[22:25], v[158:161], v[208:211], 0
	v_mfma_f32_16x16x32_bf16 v[14:17], v[150:153], v[216:219], 0
	v_mfma_f32_16x16x32_bf16 v[10:13], v[158:161], v[216:219], 0
	v_mfma_f32_16x16x32_bf16 v[6:9], v[150:153], v[224:227], 0
	v_mfma_f32_16x16x32_bf16 v[2:5], v[158:161], v[224:227], 0
	v_mfma_f32_16x16x32_bf16 v[38:41], v[154:157], v[204:207], v[38:41]
	v_mfma_f32_16x16x32_bf16 v[34:37], v[162:165], v[204:207], v[34:37]
	v_mfma_f32_16x16x32_bf16 v[26:29], v[154:157], v[212:215], v[26:29]
	v_mfma_f32_16x16x32_bf16 v[22:25], v[162:165], v[212:215], v[22:25]
	v_mfma_f32_16x16x32_bf16 v[14:17], v[154:157], v[220:223], v[14:17]
	v_mfma_f32_16x16x32_bf16 v[10:13], v[162:165], v[220:223], v[10:13]
	v_mfma_f32_16x16x32_bf16 v[6:9], v[154:157], v[228:231], v[6:9]
	v_mfma_f32_16x16x32_bf16 v[2:5], v[162:165], v[228:231], v[2:5]
	v_mfma_f32_16x16x32_bf16 v[94:97], v[184:187], v[200:203], 0
	v_mfma_f32_16x16x32_bf16 v[90:93], v[192:195], v[200:203], 0
	v_mfma_f32_16x16x32_bf16 v[86:89], v[184:187], v[208:211], 0
	v_mfma_f32_16x16x32_bf16 v[74:77], v[192:195], v[208:211], 0
	v_mfma_f32_16x16x32_bf16 v[46:49], v[184:187], v[216:219], 0
	v_mfma_f32_16x16x32_bf16 v[42:45], v[192:195], v[216:219], 0
	v_mfma_f32_16x16x32_bf16 v[30:33], v[184:187], v[224:227], 0
	v_mfma_f32_16x16x32_bf16 v[18:21], v[192:195], v[224:227], 0
	v_mfma_f32_16x16x32_bf16 v[94:97], v[188:191], v[204:207], v[94:97]
	v_mfma_f32_16x16x32_bf16 v[90:93], v[196:199], v[204:207], v[90:93]
	v_mfma_f32_16x16x32_bf16 v[86:89], v[188:191], v[212:215], v[86:89]
	v_mfma_f32_16x16x32_bf16 v[74:77], v[196:199], v[212:215], v[74:77]
	v_mfma_f32_16x16x32_bf16 v[46:49], v[188:191], v[220:223], v[46:49]
	v_mfma_f32_16x16x32_bf16 v[42:45], v[196:199], v[220:223], v[42:45]
	v_mfma_f32_16x16x32_bf16 v[30:33], v[188:191], v[228:231], v[30:33]
	v_mfma_f32_16x16x32_bf16 v[18:21], v[196:199], v[228:231], v[18:21]
	s_setprio 0
	s_barrier
	s_add_i32 s52, 0, 0x18000
	v_add_u32_e32 v138, s52, v178
	s_add_i32 s53, 0, 0x1c000
	ds_read_b128 v[150:153], v138
	ds_read_b128 v[154:157], v138 offset:1024
	ds_read_b128 v[158:161], v138 offset:2048
	ds_read_b128 v[162:165], v138 offset:3072
	v_add_u32_e32 v138, s53, v178
	ds_read_b128 v[184:187], v138
	ds_read_b128 v[188:191], v138 offset:1024
	ds_read_b128 v[192:195], v138 offset:2048
	ds_read_b128 v[196:199], v138 offset:3072
	s_add_u32 s28, s38, 0x40000
	s_addc_u32 s29, s39, 0
	s_mov_b32 m0, s35
	v_lshl_add_u64 v[238:239], s[28:29], 0, v[132:133]
	ds_read_b128 v[200:203], v182 offset:32768
	ds_read_b128 v[204:207], v182 offset:33792
	ds_read_b128 v[208:211], v182 offset:34816
	ds_read_b128 v[212:215], v182 offset:35840
	ds_read_b128 v[216:219], v182 offset:36864
	ds_read_b128 v[220:223], v182 offset:37888
	ds_read_b128 v[224:227], v182 offset:38912
	ds_read_b128 v[228:231], v182 offset:39936
	global_load_lds_dwordx4 v[238:239], off
	v_lshl_add_u64 v[238:239], s[28:29], 0, v[130:131]
	s_mov_b32 m0, s40
	s_nop 0
	global_load_lds_dwordx4 v[238:239], off
	s_waitcnt vmcnt(8)
	s_waitcnt lgkmcnt(0)
	s_barrier
	s_setprio 1
	s_waitcnt lgkmcnt(0)
	v_mfma_f32_16x16x32_bf16 v[82:85], v[150:153], v[200:203], v[82:85]
	v_mfma_f32_16x16x32_bf16 v[78:81], v[158:161], v[200:203], v[78:81]
	v_mfma_f32_16x16x32_bf16 v[70:73], v[150:153], v[208:211], v[70:73]
	v_mfma_f32_16x16x32_bf16 v[66:69], v[158:161], v[208:211], v[66:69]
	v_mfma_f32_16x16x32_bf16 v[62:65], v[150:153], v[216:219], v[62:65]
	v_mfma_f32_16x16x32_bf16 v[58:61], v[158:161], v[216:219], v[58:61]
	v_mfma_f32_16x16x32_bf16 v[54:57], v[150:153], v[224:227], v[54:57]
	v_mfma_f32_16x16x32_bf16 v[50:53], v[158:161], v[224:227], v[50:53]
	v_mfma_f32_16x16x32_bf16 v[82:85], v[154:157], v[204:207], v[82:85]
	v_mfma_f32_16x16x32_bf16 v[78:81], v[162:165], v[204:207], v[78:81]
	v_mfma_f32_16x16x32_bf16 v[70:73], v[154:157], v[212:215], v[70:73]
	v_mfma_f32_16x16x32_bf16 v[66:69], v[162:165], v[212:215], v[66:69]
	v_mfma_f32_16x16x32_bf16 v[62:65], v[154:157], v[220:223], v[62:65]
	v_mfma_f32_16x16x32_bf16 v[58:61], v[162:165], v[220:223], v[58:61]
	v_mfma_f32_16x16x32_bf16 v[54:57], v[154:157], v[228:231], v[54:57]
	v_mfma_f32_16x16x32_bf16 v[50:53], v[162:165], v[228:231], v[50:53]
	v_mfma_f32_16x16x32_bf16 v[126:129], v[184:187], v[200:203], v[126:129]
	v_mfma_f32_16x16x32_bf16 v[122:125], v[192:195], v[200:203], v[122:125]
	v_mfma_f32_16x16x32_bf16 v[118:121], v[184:187], v[208:211], v[118:121]
	v_mfma_f32_16x16x32_bf16 v[114:117], v[192:195], v[208:211], v[114:117]
	v_mfma_f32_16x16x32_bf16 v[110:113], v[184:187], v[216:219], v[110:113]
	v_mfma_f32_16x16x32_bf16 v[106:109], v[192:195], v[216:219], v[106:109]
	v_mfma_f32_16x16x32_bf16 v[102:105], v[184:187], v[224:227], v[102:105]
	v_mfma_f32_16x16x32_bf16 v[98:101], v[192:195], v[224:227], v[98:101]
	v_mfma_f32_16x16x32_bf16 v[126:129], v[188:191], v[204:207], v[126:129]
	v_mfma_f32_16x16x32_bf16 v[122:125], v[196:199], v[204:207], v[122:125]
	v_mfma_f32_16x16x32_bf16 v[118:121], v[188:191], v[212:215], v[118:121]
	v_mfma_f32_16x16x32_bf16 v[114:117], v[196:199], v[212:215], v[114:117]
	v_mfma_f32_16x16x32_bf16 v[110:113], v[188:191], v[220:223], v[110:113]
	v_mfma_f32_16x16x32_bf16 v[106:109], v[196:199], v[220:223], v[106:109]
	v_mfma_f32_16x16x32_bf16 v[102:105], v[188:191], v[228:231], v[102:105]
	v_mfma_f32_16x16x32_bf16 v[98:101], v[196:199], v[228:231], v[98:101]
	s_setprio 0
	s_barrier
	s_add_i32 s28, s52, s16
	v_lshl_add_u64 v[166:167], v[166:167], 0, s[6:7]
	s_mov_b32 m0, s28
	ds_read_b128 v[200:203], v182 offset:49152
	ds_read_b128 v[204:207], v182 offset:50176
	ds_read_b128 v[208:211], v182 offset:51200
	ds_read_b128 v[212:215], v182 offset:52224
	ds_read_b128 v[216:219], v182 offset:53248
	ds_read_b128 v[220:223], v182 offset:54272
	ds_read_b128 v[224:227], v182 offset:55296
	ds_read_b128 v[228:231], v182 offset:56320
	global_load_lds_dwordx4 v[166:167], off
	s_add_i32 m0, s28, 0x2000
	s_add_u32 s28, s36, 0x40080
	v_lshl_add_u64 v[166:167], v[232:233], 0, s[6:7]
	s_addc_u32 s29, s37, 0
	s_add_i32 s36, s53, s16
	global_load_lds_dwordx4 v[166:167], off
	v_lshl_add_u64 v[166:167], s[28:29], 0, v[134:135]
	s_mov_b32 m0, s36
	s_nop 0
	global_load_lds_dwordx4 v[166:167], off
	v_lshl_add_u64 v[166:167], s[28:29], 0, v[136:137]
	s_add_i32 m0, s36, 0x2000
	s_nop 0
	global_load_lds_dwordx4 v[166:167], off
	v_lshl_add_u64 v[166:167], v[234:235], 0, s[6:7]
	s_mov_b32 m0, s42
	s_nop 0
	global_load_lds_dwordx4 v[166:167], off
	v_lshl_add_u64 v[166:167], v[236:237], 0, s[6:7]
	s_mov_b32 m0, s43
	s_nop 0
	global_load_lds_dwordx4 v[166:167], off
	s_waitcnt vmcnt(8)
	s_waitcnt lgkmcnt(0)
	s_barrier
	s_setprio 1
	s_waitcnt lgkmcnt(0)
	v_mfma_f32_16x16x32_bf16 v[38:41], v[150:153], v[200:203], v[38:41]
	v_mfma_f32_16x16x32_bf16 v[34:37], v[158:161], v[200:203], v[34:37]
	v_mfma_f32_16x16x32_bf16 v[26:29], v[150:153], v[208:211], v[26:29]
	v_mfma_f32_16x16x32_bf16 v[22:25], v[158:161], v[208:211], v[22:25]
	v_mfma_f32_16x16x32_bf16 v[14:17], v[150:153], v[216:219], v[14:17]
	v_mfma_f32_16x16x32_bf16 v[10:13], v[158:161], v[216:219], v[10:13]
	v_mfma_f32_16x16x32_bf16 v[6:9], v[150:153], v[224:227], v[6:9]
	v_mfma_f32_16x16x32_bf16 v[2:5], v[158:161], v[224:227], v[2:5]
	v_mfma_f32_16x16x32_bf16 v[38:41], v[154:157], v[204:207], v[38:41]
	v_mfma_f32_16x16x32_bf16 v[34:37], v[162:165], v[204:207], v[34:37]
	v_mfma_f32_16x16x32_bf16 v[26:29], v[154:157], v[212:215], v[26:29]
	v_mfma_f32_16x16x32_bf16 v[22:25], v[162:165], v[212:215], v[22:25]
	v_mfma_f32_16x16x32_bf16 v[14:17], v[154:157], v[220:223], v[14:17]
	v_mfma_f32_16x16x32_bf16 v[10:13], v[162:165], v[220:223], v[10:13]
	v_mfma_f32_16x16x32_bf16 v[6:9], v[154:157], v[228:231], v[6:9]
	v_mfma_f32_16x16x32_bf16 v[2:5], v[162:165], v[228:231], v[2:5]
	v_mfma_f32_16x16x32_bf16 v[94:97], v[184:187], v[200:203], v[94:97]
	v_mfma_f32_16x16x32_bf16 v[90:93], v[192:195], v[200:203], v[90:93]
	v_mfma_f32_16x16x32_bf16 v[86:89], v[184:187], v[208:211], v[86:89]
	v_mfma_f32_16x16x32_bf16 v[74:77], v[192:195], v[208:211], v[74:77]
	v_mfma_f32_16x16x32_bf16 v[46:49], v[184:187], v[216:219], v[46:49]
	v_mfma_f32_16x16x32_bf16 v[42:45], v[192:195], v[216:219], v[42:45]
	v_mfma_f32_16x16x32_bf16 v[30:33], v[184:187], v[224:227], v[30:33]
	v_mfma_f32_16x16x32_bf16 v[18:21], v[192:195], v[224:227], v[18:21]
	v_mfma_f32_16x16x32_bf16 v[94:97], v[188:191], v[204:207], v[94:97]
	v_mfma_f32_16x16x32_bf16 v[90:93], v[196:199], v[204:207], v[90:93]
	v_mfma_f32_16x16x32_bf16 v[86:89], v[188:191], v[212:215], v[86:89]
	v_mfma_f32_16x16x32_bf16 v[74:77], v[196:199], v[212:215], v[74:77]
	v_mfma_f32_16x16x32_bf16 v[46:49], v[188:191], v[220:223], v[46:49]
	v_mfma_f32_16x16x32_bf16 v[42:45], v[196:199], v[220:223], v[42:45]
	v_mfma_f32_16x16x32_bf16 v[30:33], v[188:191], v[228:231], v[30:33]
	v_mfma_f32_16x16x32_bf16 v[18:21], v[196:199], v[228:231], v[18:21]
	s_setprio 0
	s_barrier
	s_add_i32 s51, s51, 2
	s_add_u32 s49, s49, 0x100
	s_addc_u32 s50, s50, 0
	s_cmp_gt_u32 s51, 13
	s_mov_b64 s[28:29], s[30:31]
	s_cbranch_scc0 .LBB0_373
	s_branch .Lpeel_exit_373
.LBB0_373:
	ds_read_b128 v[150:153], v180
	ds_read_b128 v[154:157], v180 offset:1024
	ds_read_b128 v[158:161], v180 offset:2048
	ds_read_b128 v[162:165], v180 offset:3072
	ds_read_b128 v[184:187], v181
	ds_read_b128 v[188:191], v181 offset:1024
	ds_read_b128 v[192:195], v181 offset:2048
	ds_read_b128 v[196:199], v181 offset:3072
	s_add_u32 s30, s28, 0x100
	s_addc_u32 s31, s29, 0
	s_cmp_eq_u32 s51, 12
	s_cselect_b32 s39, s21, s31
	s_cselect_b32 s38, s27, s30
	s_cselect_b32 s37, s13, s50
	s_cselect_b32 s36, s48, s49
	v_lshl_add_u64 v[166:167], s[28:29], 0, v[142:143]
	s_add_i32 m0, s17, 0xc000
	ds_read_b128 v[200:203], v182
	ds_read_b128 v[204:207], v182 offset:1024
	ds_read_b128 v[208:211], v182 offset:2048
	ds_read_b128 v[212:215], v182 offset:3072
	ds_read_b128 v[216:219], v182 offset:4096
	ds_read_b128 v[220:223], v182 offset:5120
	ds_read_b128 v[224:227], v182 offset:6144
	ds_read_b128 v[228:231], v182 offset:7168
	global_load_lds_dwordx4 v[166:167], off
	v_lshl_add_u64 v[166:167], s[28:29], 0, v[144:145]
	s_add_i32 m0, s17, 0xe000
	s_nop 0
	global_load_lds_dwordx4 v[166:167], off
	s_waitcnt vmcnt(8)
	s_waitcnt lgkmcnt(0)
	s_barrier
	s_setprio 1
	s_waitcnt lgkmcnt(0)
	v_mfma_f32_16x16x32_bf16 v[82:85], v[150:153], v[200:203], v[82:85]
	v_mfma_f32_16x16x32_bf16 v[78:81], v[158:161], v[200:203], v[78:81]
	v_mfma_f32_16x16x32_bf16 v[70:73], v[150:153], v[208:211], v[70:73]
	v_mfma_f32_16x16x32_bf16 v[66:69], v[158:161], v[208:211], v[66:69]
	v_mfma_f32_16x16x32_bf16 v[62:65], v[150:153], v[216:219], v[62:65]
	v_mfma_f32_16x16x32_bf16 v[58:61], v[158:161], v[216:219], v[58:61]
	v_mfma_f32_16x16x32_bf16 v[54:57], v[150:153], v[224:227], v[54:57]
	v_mfma_f32_16x16x32_bf16 v[50:53], v[158:161], v[224:227], v[50:53]
	v_mfma_f32_16x16x32_bf16 v[82:85], v[154:157], v[204:207], v[82:85]
	v_mfma_f32_16x16x32_bf16 v[78:81], v[162:165], v[204:207], v[78:81]
	v_mfma_f32_16x16x32_bf16 v[70:73], v[154:157], v[212:215], v[70:73]
	v_mfma_f32_16x16x32_bf16 v[66:69], v[162:165], v[212:215], v[66:69]
	v_mfma_f32_16x16x32_bf16 v[62:65], v[154:157], v[220:223], v[62:65]
	v_mfma_f32_16x16x32_bf16 v[58:61], v[162:165], v[220:223], v[58:61]
	v_mfma_f32_16x16x32_bf16 v[54:57], v[154:157], v[228:231], v[54:57]
	v_mfma_f32_16x16x32_bf16 v[50:53], v[162:165], v[228:231], v[50:53]
	v_mfma_f32_16x16x32_bf16 v[126:129], v[184:187], v[200:203], v[126:129]
	v_mfma_f32_16x16x32_bf16 v[122:125], v[192:195], v[200:203], v[122:125]
	v_mfma_f32_16x16x32_bf16 v[118:121], v[184:187], v[208:211], v[118:121]
	v_mfma_f32_16x16x32_bf16 v[114:117], v[192:195], v[208:211], v[114:117]
	v_mfma_f32_16x16x32_bf16 v[110:113], v[184:187], v[216:219], v[110:113]
	v_mfma_f32_16x16x32_bf16 v[106:109], v[192:195], v[216:219], v[106:109]
	v_mfma_f32_16x16x32_bf16 v[102:105], v[184:187], v[224:227], v[102:105]
	v_mfma_f32_16x16x32_bf16 v[98:101], v[192:195], v[224:227], v[98:101]
	v_mfma_f32_16x16x32_bf16 v[126:129], v[188:191], v[204:207], v[126:129]
	v_mfma_f32_16x16x32_bf16 v[122:125], v[196:199], v[204:207], v[122:125]
	v_mfma_f32_16x16x32_bf16 v[118:121], v[188:191], v[212:215], v[118:121]
	v_mfma_f32_16x16x32_bf16 v[114:117], v[196:199], v[212:215], v[114:117]
	v_mfma_f32_16x16x32_bf16 v[110:113], v[188:191], v[220:223], v[110:113]
	v_mfma_f32_16x16x32_bf16 v[106:109], v[196:199], v[220:223], v[106:109]
	v_mfma_f32_16x16x32_bf16 v[102:105], v[188:191], v[228:231], v[102:105]
	v_mfma_f32_16x16x32_bf16 v[98:101], v[196:199], v[228:231], v[98:101]
	s_setprio 0
	s_barrier
	s_add_i32 s28, s45, s16
	v_lshl_add_u64 v[166:167], s[36:37], 0, v[134:135]
	s_mov_b32 m0, s28
	ds_read_b128 v[200:203], v182 offset:16384
	ds_read_b128 v[204:207], v182 offset:17408
	ds_read_b128 v[208:211], v182 offset:18432
	ds_read_b128 v[212:215], v182 offset:19456
	ds_read_b128 v[216:219], v182 offset:20480
	ds_read_b128 v[220:223], v182 offset:21504
	ds_read_b128 v[224:227], v182 offset:22528
	ds_read_b128 v[228:231], v182 offset:23552
	global_load_lds_dwordx4 v[166:167], off
	s_add_i32 m0, s28, 0x2000
	s_add_u32 s28, s36, 0x40000
	v_lshl_add_u64 v[232:233], s[36:37], 0, v[136:137]
	s_addc_u32 s29, s37, 0
	s_add_i32 s52, s46, s16
	global_load_lds_dwordx4 v[232:233], off
	v_lshl_add_u64 v[234:235], s[28:29], 0, v[134:135]
	s_mov_b32 m0, s52
	v_lshl_add_u64 v[236:237], s[38:39], 0, v[130:131]
	global_load_lds_dwordx4 v[234:235], off
	v_lshl_add_u64 v[234:235], s[28:29], 0, v[136:137]
	s_add_i32 m0, s52, 0x2000
	s_nop 0
	global_load_lds_dwordx4 v[234:235], off
	v_lshl_add_u64 v[234:235], s[38:39], 0, v[132:133]
	s_mov_b32 m0, s17
	s_nop 0
	global_load_lds_dwordx4 v[234:235], off
	s_mov_b32 m0, s34
	s_nop 0
	global_load_lds_dwordx4 v[236:237], off
	s_waitcnt vmcnt(8)
	s_waitcnt lgkmcnt(0)
	s_barrier
	s_setprio 1
	s_waitcnt lgkmcnt(0)
	v_mfma_f32_16x16x32_bf16 v[38:41], v[150:153], v[200:203], v[38:41]
	v_mfma_f32_16x16x32_bf16 v[34:37], v[158:161], v[200:203], v[34:37]
	v_mfma_f32_16x16x32_bf16 v[26:29], v[150:153], v[208:211], v[26:29]
	v_mfma_f32_16x16x32_bf16 v[22:25], v[158:161], v[208:211], v[22:25]
	v_mfma_f32_16x16x32_bf16 v[14:17], v[150:153], v[216:219], v[14:17]
	v_mfma_f32_16x16x32_bf16 v[10:13], v[158:161], v[216:219], v[10:13]
	v_mfma_f32_16x16x32_bf16 v[6:9], v[150:153], v[224:227], v[6:9]
	v_mfma_f32_16x16x32_bf16 v[2:5], v[158:161], v[224:227], v[2:5]
	v_mfma_f32_16x16x32_bf16 v[38:41], v[154:157], v[204:207], v[38:41]
	v_mfma_f32_16x16x32_bf16 v[34:37], v[162:165], v[204:207], v[34:37]
	v_mfma_f32_16x16x32_bf16 v[26:29], v[154:157], v[212:215], v[26:29]
	v_mfma_f32_16x16x32_bf16 v[22:25], v[162:165], v[212:215], v[22:25]
	v_mfma_f32_16x16x32_bf16 v[14:17], v[154:157], v[220:223], v[14:17]
	v_mfma_f32_16x16x32_bf16 v[10:13], v[162:165], v[220:223], v[10:13]
	v_mfma_f32_16x16x32_bf16 v[6:9], v[154:157], v[228:231], v[6:9]
	v_mfma_f32_16x16x32_bf16 v[2:5], v[162:165], v[228:231], v[2:5]
	v_mfma_f32_16x16x32_bf16 v[94:97], v[184:187], v[200:203], v[94:97]
	v_mfma_f32_16x16x32_bf16 v[90:93], v[192:195], v[200:203], v[90:93]
	v_mfma_f32_16x16x32_bf16 v[86:89], v[184:187], v[208:211], v[86:89]
	v_mfma_f32_16x16x32_bf16 v[74:77], v[192:195], v[208:211], v[74:77]
	v_mfma_f32_16x16x32_bf16 v[46:49], v[184:187], v[216:219], v[46:49]
	v_mfma_f32_16x16x32_bf16 v[42:45], v[192:195], v[216:219], v[42:45]
	v_mfma_f32_16x16x32_bf16 v[30:33], v[184:187], v[224:227], v[30:33]
	v_mfma_f32_16x16x32_bf16 v[18:21], v[192:195], v[224:227], v[18:21]
	v_mfma_f32_16x16x32_bf16 v[94:97], v[188:191], v[204:207], v[94:97]
	v_mfma_f32_16x16x32_bf16 v[90:93], v[196:199], v[204:207], v[90:93]
	v_mfma_f32_16x16x32_bf16 v[86:89], v[188:191], v[212:215], v[86:89]
	v_mfma_f32_16x16x32_bf16 v[74:77], v[196:199], v[212:215], v[74:77]
	v_mfma_f32_16x16x32_bf16 v[46:49], v[188:191], v[220:223], v[46:49]
	v_mfma_f32_16x16x32_bf16 v[42:45], v[196:199], v[220:223], v[42:45]
	v_mfma_f32_16x16x32_bf16 v[30:33], v[188:191], v[228:231], v[30:33]
	v_mfma_f32_16x16x32_bf16 v[18:21], v[196:199], v[228:231], v[18:21]
	s_setprio 0
	s_barrier
	s_add_i32 s52, 0, 0x18000
	v_add_u32_e32 v138, s52, v178
	s_add_i32 s53, 0, 0x1c000
	ds_read_b128 v[150:153], v138
	ds_read_b128 v[154:157], v138 offset:1024
	ds_read_b128 v[158:161], v138 offset:2048
	ds_read_b128 v[162:165], v138 offset:3072
	v_add_u32_e32 v138, s53, v178
	ds_read_b128 v[184:187], v138
	ds_read_b128 v[188:191], v138 offset:1024
	ds_read_b128 v[192:195], v138 offset:2048
	ds_read_b128 v[196:199], v138 offset:3072
	s_add_u32 s28, s38, 0x40000
	s_addc_u32 s29, s39, 0
	s_mov_b32 m0, s35
	v_lshl_add_u64 v[238:239], s[28:29], 0, v[132:133]
	ds_read_b128 v[200:203], v182 offset:32768
	ds_read_b128 v[204:207], v182 offset:33792
	ds_read_b128 v[208:211], v182 offset:34816
	ds_read_b128 v[212:215], v182 offset:35840
	ds_read_b128 v[216:219], v182 offset:36864
	ds_read_b128 v[220:223], v182 offset:37888
	ds_read_b128 v[224:227], v182 offset:38912
	ds_read_b128 v[228:231], v182 offset:39936
	global_load_lds_dwordx4 v[238:239], off
	v_lshl_add_u64 v[238:239], s[28:29], 0, v[130:131]
	s_mov_b32 m0, s40
	s_nop 0
	global_load_lds_dwordx4 v[238:239], off
	s_waitcnt vmcnt(8)
	s_waitcnt lgkmcnt(0)
	s_barrier
	s_setprio 1
	s_waitcnt lgkmcnt(0)
	v_mfma_f32_16x16x32_bf16 v[82:85], v[150:153], v[200:203], v[82:85]
	v_mfma_f32_16x16x32_bf16 v[78:81], v[158:161], v[200:203], v[78:81]
	v_mfma_f32_16x16x32_bf16 v[70:73], v[150:153], v[208:211], v[70:73]
	v_mfma_f32_16x16x32_bf16 v[66:69], v[158:161], v[208:211], v[66:69]
	v_mfma_f32_16x16x32_bf16 v[62:65], v[150:153], v[216:219], v[62:65]
	v_mfma_f32_16x16x32_bf16 v[58:61], v[158:161], v[216:219], v[58:61]
	v_mfma_f32_16x16x32_bf16 v[54:57], v[150:153], v[224:227], v[54:57]
	v_mfma_f32_16x16x32_bf16 v[50:53], v[158:161], v[224:227], v[50:53]
	v_mfma_f32_16x16x32_bf16 v[82:85], v[154:157], v[204:207], v[82:85]
	v_mfma_f32_16x16x32_bf16 v[78:81], v[162:165], v[204:207], v[78:81]
	v_mfma_f32_16x16x32_bf16 v[70:73], v[154:157], v[212:215], v[70:73]
	v_mfma_f32_16x16x32_bf16 v[66:69], v[162:165], v[212:215], v[66:69]
	v_mfma_f32_16x16x32_bf16 v[62:65], v[154:157], v[220:223], v[62:65]
	v_mfma_f32_16x16x32_bf16 v[58:61], v[162:165], v[220:223], v[58:61]
	v_mfma_f32_16x16x32_bf16 v[54:57], v[154:157], v[228:231], v[54:57]
	v_mfma_f32_16x16x32_bf16 v[50:53], v[162:165], v[228:231], v[50:53]
	v_mfma_f32_16x16x32_bf16 v[126:129], v[184:187], v[200:203], v[126:129]
	v_mfma_f32_16x16x32_bf16 v[122:125], v[192:195], v[200:203], v[122:125]
	v_mfma_f32_16x16x32_bf16 v[118:121], v[184:187], v[208:211], v[118:121]
	v_mfma_f32_16x16x32_bf16 v[114:117], v[192:195], v[208:211], v[114:117]
	v_mfma_f32_16x16x32_bf16 v[110:113], v[184:187], v[216:219], v[110:113]
	v_mfma_f32_16x16x32_bf16 v[106:109], v[192:195], v[216:219], v[106:109]
	v_mfma_f32_16x16x32_bf16 v[102:105], v[184:187], v[224:227], v[102:105]
	v_mfma_f32_16x16x32_bf16 v[98:101], v[192:195], v[224:227], v[98:101]
	v_mfma_f32_16x16x32_bf16 v[126:129], v[188:191], v[204:207], v[126:129]
	v_mfma_f32_16x16x32_bf16 v[122:125], v[196:199], v[204:207], v[122:125]
	v_mfma_f32_16x16x32_bf16 v[118:121], v[188:191], v[212:215], v[118:121]
	v_mfma_f32_16x16x32_bf16 v[114:117], v[196:199], v[212:215], v[114:117]
	v_mfma_f32_16x16x32_bf16 v[110:113], v[188:191], v[220:223], v[110:113]
	v_mfma_f32_16x16x32_bf16 v[106:109], v[196:199], v[220:223], v[106:109]
	v_mfma_f32_16x16x32_bf16 v[102:105], v[188:191], v[228:231], v[102:105]
	v_mfma_f32_16x16x32_bf16 v[98:101], v[196:199], v[228:231], v[98:101]
	s_setprio 0
	s_barrier
	s_add_i32 s28, s52, s16
	v_lshl_add_u64 v[166:167], v[166:167], 0, s[6:7]
	s_mov_b32 m0, s28
	ds_read_b128 v[200:203], v182 offset:49152
	ds_read_b128 v[204:207], v182 offset:50176
	ds_read_b128 v[208:211], v182 offset:51200
	ds_read_b128 v[212:215], v182 offset:52224
	ds_read_b128 v[216:219], v182 offset:53248
	ds_read_b128 v[220:223], v182 offset:54272
	ds_read_b128 v[224:227], v182 offset:55296
	ds_read_b128 v[228:231], v182 offset:56320
	global_load_lds_dwordx4 v[166:167], off
	s_add_i32 m0, s28, 0x2000
	s_add_u32 s28, s36, 0x40080
	v_lshl_add_u64 v[166:167], v[232:233], 0, s[6:7]
	s_addc_u32 s29, s37, 0
	s_add_i32 s36, s53, s16
	global_load_lds_dwordx4 v[166:167], off
	v_lshl_add_u64 v[166:167], s[28:29], 0, v[134:135]
	s_mov_b32 m0, s36
	s_nop 0
	global_load_lds_dwordx4 v[166:167], off
	v_lshl_add_u64 v[166:167], s[28:29], 0, v[136:137]
	s_add_i32 m0, s36, 0x2000
	s_nop 0
	global_load_lds_dwordx4 v[166:167], off
	v_lshl_add_u64 v[166:167], v[234:235], 0, s[6:7]
	s_mov_b32 m0, s42
	s_nop 0
	global_load_lds_dwordx4 v[166:167], off
	v_lshl_add_u64 v[166:167], v[236:237], 0, s[6:7]
	s_mov_b32 m0, s43
	s_nop 0
	global_load_lds_dwordx4 v[166:167], off
	s_waitcnt vmcnt(8)
	s_waitcnt lgkmcnt(0)
	s_barrier
	s_setprio 1
	s_waitcnt lgkmcnt(0)
	v_mfma_f32_16x16x32_bf16 v[38:41], v[150:153], v[200:203], v[38:41]
	v_mfma_f32_16x16x32_bf16 v[34:37], v[158:161], v[200:203], v[34:37]
	v_mfma_f32_16x16x32_bf16 v[26:29], v[150:153], v[208:211], v[26:29]
	v_mfma_f32_16x16x32_bf16 v[22:25], v[158:161], v[208:211], v[22:25]
	v_mfma_f32_16x16x32_bf16 v[14:17], v[150:153], v[216:219], v[14:17]
	v_mfma_f32_16x16x32_bf16 v[10:13], v[158:161], v[216:219], v[10:13]
	v_mfma_f32_16x16x32_bf16 v[6:9], v[150:153], v[224:227], v[6:9]
	v_mfma_f32_16x16x32_bf16 v[2:5], v[158:161], v[224:227], v[2:5]
	v_mfma_f32_16x16x32_bf16 v[38:41], v[154:157], v[204:207], v[38:41]
	v_mfma_f32_16x16x32_bf16 v[34:37], v[162:165], v[204:207], v[34:37]
	v_mfma_f32_16x16x32_bf16 v[26:29], v[154:157], v[212:215], v[26:29]
	v_mfma_f32_16x16x32_bf16 v[22:25], v[162:165], v[212:215], v[22:25]
	v_mfma_f32_16x16x32_bf16 v[14:17], v[154:157], v[220:223], v[14:17]
	v_mfma_f32_16x16x32_bf16 v[10:13], v[162:165], v[220:223], v[10:13]
	v_mfma_f32_16x16x32_bf16 v[6:9], v[154:157], v[228:231], v[6:9]
	v_mfma_f32_16x16x32_bf16 v[2:5], v[162:165], v[228:231], v[2:5]
	v_mfma_f32_16x16x32_bf16 v[94:97], v[184:187], v[200:203], v[94:97]
	v_mfma_f32_16x16x32_bf16 v[90:93], v[192:195], v[200:203], v[90:93]
	v_mfma_f32_16x16x32_bf16 v[86:89], v[184:187], v[208:211], v[86:89]
	v_mfma_f32_16x16x32_bf16 v[74:77], v[192:195], v[208:211], v[74:77]
	v_mfma_f32_16x16x32_bf16 v[46:49], v[184:187], v[216:219], v[46:49]
	v_mfma_f32_16x16x32_bf16 v[42:45], v[192:195], v[216:219], v[42:45]
	v_mfma_f32_16x16x32_bf16 v[30:33], v[184:187], v[224:227], v[30:33]
	v_mfma_f32_16x16x32_bf16 v[18:21], v[192:195], v[224:227], v[18:21]
	v_mfma_f32_16x16x32_bf16 v[94:97], v[188:191], v[204:207], v[94:97]
	v_mfma_f32_16x16x32_bf16 v[90:93], v[196:199], v[204:207], v[90:93]
	v_mfma_f32_16x16x32_bf16 v[86:89], v[188:191], v[212:215], v[86:89]
	v_mfma_f32_16x16x32_bf16 v[74:77], v[196:199], v[212:215], v[74:77]
	v_mfma_f32_16x16x32_bf16 v[46:49], v[188:191], v[220:223], v[46:49]
	v_mfma_f32_16x16x32_bf16 v[42:45], v[196:199], v[220:223], v[42:45]
	v_mfma_f32_16x16x32_bf16 v[30:33], v[188:191], v[228:231], v[30:33]
	v_mfma_f32_16x16x32_bf16 v[18:21], v[196:199], v[228:231], v[18:21]
	s_setprio 0
	s_barrier
	s_add_i32 s51, s51, 2
	s_add_u32 s49, s49, 0x100
	s_addc_u32 s50, s50, 0
	s_cmp_gt_u32 s51, 13
	s_mov_b64 s[28:29], s[30:31]
	s_cbranch_scc0 .LBB0_373

.LBB0_404:
	s_ashr_i32 s29, s28, 31
	s_lshl_b64 s[30:31], s[28:29], 19
	s_add_u32 s30, s14, s30
	s_addc_u32 s31, s15, s31
	s_and_b64 s[34:35], s[24:25], exec
	s_cselect_b32 s5, s31, s41
	s_cselect_b32 s29, s30, s40
	s_ashr_i32 s27, s26, 31
	s_lshl_b64 s[34:35], s[26:27], 19
	s_add_u32 s36, s16, s34
	s_addc_u32 s37, s17, s35
	s_and_b64 s[34:35], s[24:25], exec
	s_cselect_b32 s27, s37, s43
	s_cselect_b32 s34, s36, s42
	s_add_u32 s35, s42, 0x100
	s_addc_u32 s39, s43, 0
	s_mov_b32 s61, -2
	ds_read_b128 v[140:143], v156
	ds_read_b128 v[144:147], v156 offset:1024
	ds_read_b128 v[148:151], v156 offset:2048
	ds_read_b128 v[164:167], v156 offset:3072
	ds_read_b128 v[168:171], v157
	ds_read_b128 v[178:181], v157 offset:1024
	ds_read_b128 v[182:185], v157 offset:2048
	ds_read_b128 v[186:189], v157 offset:3072
	s_add_u32 s42, s40, 0x100
	s_addc_u32 s43, s41, 0
	s_cmp_eq_u32 s61, 12
	s_cselect_b32 s47, s5, s43
	s_cselect_b32 s46, s29, s42
	s_cselect_b32 s45, s27, s39
	s_cselect_b32 s44, s34, s35
	v_lshl_add_u64 v[152:153], s[40:41], 0, v[136:137]
	s_add_i32 m0, s49, 0xc000
	ds_read_b128 v[190:193], v158
	ds_read_b128 v[194:197], v158 offset:1024
	ds_read_b128 v[198:201], v158 offset:2048
	ds_read_b128 v[202:205], v158 offset:3072
	ds_read_b128 v[206:209], v158 offset:4096
	ds_read_b128 v[210:213], v158 offset:5120
	ds_read_b128 v[214:217], v158 offset:6144
	ds_read_b128 v[218:221], v158 offset:7168
	global_load_lds_dwordx4 v[152:153], off
	v_lshl_add_u64 v[152:153], s[40:41], 0, v[138:139]
	s_add_i32 m0, s49, 0xe000
	s_nop 0
	global_load_lds_dwordx4 v[152:153], off
	s_waitcnt vmcnt(8)
	s_waitcnt lgkmcnt(0)
	s_barrier
	s_setprio 1
	s_waitcnt lgkmcnt(0)
	v_mfma_f32_16x16x32_bf16 v[126:129], v[140:143], v[190:193], 0
	v_mfma_f32_16x16x32_bf16 v[122:125], v[148:151], v[190:193], 0
	v_mfma_f32_16x16x32_bf16 v[110:113], v[140:143], v[198:201], 0
	v_mfma_f32_16x16x32_bf16 v[106:109], v[148:151], v[198:201], 0
	v_mfma_f32_16x16x32_bf16 v[94:97], v[140:143], v[206:209], 0
	v_mfma_f32_16x16x32_bf16 v[90:93], v[148:151], v[206:209], 0
	v_mfma_f32_16x16x32_bf16 v[78:81], v[140:143], v[214:217], 0
	v_mfma_f32_16x16x32_bf16 v[74:77], v[148:151], v[214:217], 0
	v_mfma_f32_16x16x32_bf16 v[126:129], v[144:147], v[194:197], v[126:129]
	v_mfma_f32_16x16x32_bf16 v[122:125], v[164:167], v[194:197], v[122:125]
	v_mfma_f32_16x16x32_bf16 v[110:113], v[144:147], v[202:205], v[110:113]
	v_mfma_f32_16x16x32_bf16 v[106:109], v[164:167], v[202:205], v[106:109]
	v_mfma_f32_16x16x32_bf16 v[94:97], v[144:147], v[210:213], v[94:97]
	v_mfma_f32_16x16x32_bf16 v[90:93], v[164:167], v[210:213], v[90:93]
	v_mfma_f32_16x16x32_bf16 v[78:81], v[144:147], v[218:221], v[78:81]
	v_mfma_f32_16x16x32_bf16 v[74:77], v[164:167], v[218:221], v[74:77]
	v_mfma_f32_16x16x32_bf16 v[118:121], v[168:171], v[190:193], 0
	v_mfma_f32_16x16x32_bf16 v[114:117], v[182:185], v[190:193], 0
	v_mfma_f32_16x16x32_bf16 v[102:105], v[168:171], v[198:201], 0
	v_mfma_f32_16x16x32_bf16 v[98:101], v[182:185], v[198:201], 0
	v_mfma_f32_16x16x32_bf16 v[86:89], v[168:171], v[206:209], 0
	v_mfma_f32_16x16x32_bf16 v[82:85], v[182:185], v[206:209], 0
	v_mfma_f32_16x16x32_bf16 v[70:73], v[168:171], v[214:217], 0
	v_mfma_f32_16x16x32_bf16 v[66:69], v[182:185], v[214:217], 0
	v_mfma_f32_16x16x32_bf16 v[118:121], v[178:181], v[194:197], v[118:121]
	v_mfma_f32_16x16x32_bf16 v[114:117], v[186:189], v[194:197], v[114:117]
	v_mfma_f32_16x16x32_bf16 v[102:105], v[178:181], v[202:205], v[102:105]
	v_mfma_f32_16x16x32_bf16 v[98:101], v[186:189], v[202:205], v[98:101]
	v_mfma_f32_16x16x32_bf16 v[86:89], v[178:181], v[210:213], v[86:89]
	v_mfma_f32_16x16x32_bf16 v[82:85], v[186:189], v[210:213], v[82:85]
	v_mfma_f32_16x16x32_bf16 v[70:73], v[178:181], v[218:221], v[70:73]
	v_mfma_f32_16x16x32_bf16 v[66:69], v[186:189], v[218:221], v[66:69]
	s_setprio 0
	s_barrier
	s_add_i32 s40, s59, s48
	v_lshl_add_u64 v[152:153], s[44:45], 0, v[132:133]
	s_mov_b32 m0, s40
	ds_read_b128 v[190:193], v158 offset:16384
	ds_read_b128 v[194:197], v158 offset:17408
	ds_read_b128 v[198:201], v158 offset:18432
	ds_read_b128 v[202:205], v158 offset:19456
	ds_read_b128 v[206:209], v158 offset:20480
	ds_read_b128 v[210:213], v158 offset:21504
	ds_read_b128 v[214:217], v158 offset:22528
	ds_read_b128 v[218:221], v158 offset:23552
	global_load_lds_dwordx4 v[152:153], off
	s_add_i32 m0, s40, 0x2000
	s_add_u32 s40, s44, 0x40000
	v_lshl_add_u64 v[172:173], s[44:45], 0, v[130:131]
	s_addc_u32 s41, s45, 0
	s_add_i32 s62, s60, s48
	global_load_lds_dwordx4 v[172:173], off
	v_lshl_add_u64 v[222:223], s[40:41], 0, v[132:133]
	s_mov_b32 m0, s62
	v_lshl_add_u64 v[224:225], s[46:47], 0, v[130:131]
	global_load_lds_dwordx4 v[222:223], off
	v_lshl_add_u64 v[222:223], s[40:41], 0, v[130:131]
	s_add_i32 m0, s62, 0x2000
	s_nop 0
	global_load_lds_dwordx4 v[222:223], off
	v_lshl_add_u64 v[222:223], s[46:47], 0, v[132:133]
	s_mov_b32 m0, s49
	s_nop 0
	global_load_lds_dwordx4 v[222:223], off
	s_mov_b32 m0, s50
	s_nop 0
	global_load_lds_dwordx4 v[224:225], off
	s_waitcnt vmcnt(8)
	s_waitcnt lgkmcnt(0)
	s_barrier
	s_setprio 1
	s_waitcnt lgkmcnt(0)
	v_mfma_f32_16x16x32_bf16 v[62:65], v[140:143], v[190:193], 0
	v_mfma_f32_16x16x32_bf16 v[58:61], v[148:151], v[190:193], 0
	v_mfma_f32_16x16x32_bf16 v[46:49], v[140:143], v[198:201], 0
	v_mfma_f32_16x16x32_bf16 v[42:45], v[148:151], v[198:201], 0
	v_mfma_f32_16x16x32_bf16 v[30:33], v[140:143], v[206:209], 0
	v_mfma_f32_16x16x32_bf16 v[26:29], v[148:151], v[206:209], 0
	v_mfma_f32_16x16x32_bf16 v[14:17], v[140:143], v[214:217], 0
	v_mfma_f32_16x16x32_bf16 v[10:13], v[148:151], v[214:217], 0
	v_mfma_f32_16x16x32_bf16 v[62:65], v[144:147], v[194:197], v[62:65]
	v_mfma_f32_16x16x32_bf16 v[58:61], v[164:167], v[194:197], v[58:61]
	v_mfma_f32_16x16x32_bf16 v[46:49], v[144:147], v[202:205], v[46:49]
	v_mfma_f32_16x16x32_bf16 v[42:45], v[164:167], v[202:205], v[42:45]
	v_mfma_f32_16x16x32_bf16 v[30:33], v[144:147], v[210:213], v[30:33]
	v_mfma_f32_16x16x32_bf16 v[26:29], v[164:167], v[210:213], v[26:29]
	v_mfma_f32_16x16x32_bf16 v[14:17], v[144:147], v[218:221], v[14:17]
	v_mfma_f32_16x16x32_bf16 v[10:13], v[164:167], v[218:221], v[10:13]
	v_mfma_f32_16x16x32_bf16 v[54:57], v[168:171], v[190:193], 0
	v_mfma_f32_16x16x32_bf16 v[50:53], v[182:185], v[190:193], 0
	v_mfma_f32_16x16x32_bf16 v[38:41], v[168:171], v[198:201], 0
	v_mfma_f32_16x16x32_bf16 v[34:37], v[182:185], v[198:201], 0
	v_mfma_f32_16x16x32_bf16 v[22:25], v[168:171], v[206:209], 0
	v_mfma_f32_16x16x32_bf16 v[18:21], v[182:185], v[206:209], 0
	v_mfma_f32_16x16x32_bf16 v[6:9], v[168:171], v[214:217], 0
	v_mfma_f32_16x16x32_bf16 v[2:5], v[182:185], v[214:217], 0
	v_mfma_f32_16x16x32_bf16 v[54:57], v[178:181], v[194:197], v[54:57]
	v_mfma_f32_16x16x32_bf16 v[50:53], v[186:189], v[194:197], v[50:53]
	v_mfma_f32_16x16x32_bf16 v[38:41], v[178:181], v[202:205], v[38:41]
	v_mfma_f32_16x16x32_bf16 v[34:37], v[186:189], v[202:205], v[34:37]
	v_mfma_f32_16x16x32_bf16 v[22:25], v[178:181], v[210:213], v[22:25]
	v_mfma_f32_16x16x32_bf16 v[18:21], v[186:189], v[210:213], v[18:21]
	v_mfma_f32_16x16x32_bf16 v[6:9], v[178:181], v[218:221], v[6:9]
	v_mfma_f32_16x16x32_bf16 v[2:5], v[186:189], v[218:221], v[2:5]
	s_setprio 0
	s_barrier
	s_add_i32 s62, 0, 0x18000
	v_add_u32_e32 v134, s62, v154
	s_add_i32 s63, 0, 0x1c000
	ds_read_b128 v[140:143], v134
	ds_read_b128 v[144:147], v134 offset:1024
	ds_read_b128 v[148:151], v134 offset:2048
	ds_read_b128 v[164:167], v134 offset:3072
	v_add_u32_e32 v134, s63, v154
	ds_read_b128 v[168:171], v134
	ds_read_b128 v[178:181], v134 offset:1024
	ds_read_b128 v[182:185], v134 offset:2048
	ds_read_b128 v[186:189], v134 offset:3072
	s_add_u32 s40, s46, 0x40000
	s_addc_u32 s41, s47, 0
	s_mov_b32 m0, s51
	v_lshl_add_u64 v[226:227], s[40:41], 0, v[132:133]
	ds_read_b128 v[190:193], v158 offset:32768
	ds_read_b128 v[194:197], v158 offset:33792
	ds_read_b128 v[198:201], v158 offset:34816
	ds_read_b128 v[202:205], v158 offset:35840
	ds_read_b128 v[206:209], v158 offset:36864
	ds_read_b128 v[210:213], v158 offset:37888
	ds_read_b128 v[214:217], v158 offset:38912
	ds_read_b128 v[218:221], v158 offset:39936
	global_load_lds_dwordx4 v[226:227], off
	v_lshl_add_u64 v[226:227], s[40:41], 0, v[130:131]
	s_mov_b32 m0, s52
	s_nop 0
	global_load_lds_dwordx4 v[226:227], off
	s_waitcnt vmcnt(8)
	s_waitcnt lgkmcnt(0)
	s_barrier
	s_setprio 1
	s_waitcnt lgkmcnt(0)
	v_mfma_f32_16x16x32_bf16 v[126:129], v[140:143], v[190:193], v[126:129]
	v_mfma_f32_16x16x32_bf16 v[122:125], v[148:151], v[190:193], v[122:125]
	v_mfma_f32_16x16x32_bf16 v[110:113], v[140:143], v[198:201], v[110:113]
	v_mfma_f32_16x16x32_bf16 v[106:109], v[148:151], v[198:201], v[106:109]
	v_mfma_f32_16x16x32_bf16 v[94:97], v[140:143], v[206:209], v[94:97]
	v_mfma_f32_16x16x32_bf16 v[90:93], v[148:151], v[206:209], v[90:93]
	v_mfma_f32_16x16x32_bf16 v[78:81], v[140:143], v[214:217], v[78:81]
	v_mfma_f32_16x16x32_bf16 v[74:77], v[148:151], v[214:217], v[74:77]
	v_mfma_f32_16x16x32_bf16 v[126:129], v[144:147], v[194:197], v[126:129]
	v_mfma_f32_16x16x32_bf16 v[122:125], v[164:167], v[194:197], v[122:125]
	v_mfma_f32_16x16x32_bf16 v[110:113], v[144:147], v[202:205], v[110:113]
	v_mfma_f32_16x16x32_bf16 v[106:109], v[164:167], v[202:205], v[106:109]
	v_mfma_f32_16x16x32_bf16 v[94:97], v[144:147], v[210:213], v[94:97]
	v_mfma_f32_16x16x32_bf16 v[90:93], v[164:167], v[210:213], v[90:93]
	v_mfma_f32_16x16x32_bf16 v[78:81], v[144:147], v[218:221], v[78:81]
	v_mfma_f32_16x16x32_bf16 v[74:77], v[164:167], v[218:221], v[74:77]
	v_mfma_f32_16x16x32_bf16 v[118:121], v[168:171], v[190:193], v[118:121]
	v_mfma_f32_16x16x32_bf16 v[114:117], v[182:185], v[190:193], v[114:117]
	v_mfma_f32_16x16x32_bf16 v[102:105], v[168:171], v[198:201], v[102:105]
	v_mfma_f32_16x16x32_bf16 v[98:101], v[182:185], v[198:201], v[98:101]
	v_mfma_f32_16x16x32_bf16 v[86:89], v[168:171], v[206:209], v[86:89]
	v_mfma_f32_16x16x32_bf16 v[82:85], v[182:185], v[206:209], v[82:85]
	v_mfma_f32_16x16x32_bf16 v[70:73], v[168:171], v[214:217], v[70:73]
	v_mfma_f32_16x16x32_bf16 v[66:69], v[182:185], v[214:217], v[66:69]
	v_mfma_f32_16x16x32_bf16 v[118:121], v[178:181], v[194:197], v[118:121]
	v_mfma_f32_16x16x32_bf16 v[114:117], v[186:189], v[194:197], v[114:117]
	v_mfma_f32_16x16x32_bf16 v[102:105], v[178:181], v[202:205], v[102:105]
	v_mfma_f32_16x16x32_bf16 v[98:101], v[186:189], v[202:205], v[98:101]
	v_mfma_f32_16x16x32_bf16 v[86:89], v[178:181], v[210:213], v[86:89]
	v_mfma_f32_16x16x32_bf16 v[82:85], v[186:189], v[210:213], v[82:85]
	v_mfma_f32_16x16x32_bf16 v[70:73], v[178:181], v[218:221], v[70:73]
	v_mfma_f32_16x16x32_bf16 v[66:69], v[186:189], v[218:221], v[66:69]
	s_setprio 0
	s_barrier
	s_add_i32 s40, s62, s48
	v_lshl_add_u64 v[152:153], v[152:153], 0, s[20:21]
	s_mov_b32 m0, s40
	ds_read_b128 v[190:193], v158 offset:49152
	ds_read_b128 v[194:197], v158 offset:50176
	ds_read_b128 v[198:201], v158 offset:51200
	ds_read_b128 v[202:205], v158 offset:52224
	ds_read_b128 v[206:209], v158 offset:53248
	ds_read_b128 v[210:213], v158 offset:54272
	ds_read_b128 v[214:217], v158 offset:55296
	ds_read_b128 v[218:221], v158 offset:56320
	global_load_lds_dwordx4 v[152:153], off
	s_add_i32 m0, s40, 0x2000
	s_add_u32 s40, s44, 0x40080
	v_lshl_add_u64 v[152:153], v[172:173], 0, s[20:21]
	s_addc_u32 s41, s45, 0
	s_add_i32 s44, s63, s48
	global_load_lds_dwordx4 v[152:153], off
	v_lshl_add_u64 v[152:153], s[40:41], 0, v[132:133]
	s_mov_b32 m0, s44
	s_nop 0
	global_load_lds_dwordx4 v[152:153], off
	v_lshl_add_u64 v[152:153], s[40:41], 0, v[130:131]
	s_add_i32 m0, s44, 0x2000
	s_nop 0
	global_load_lds_dwordx4 v[152:153], off
	v_lshl_add_u64 v[152:153], v[222:223], 0, s[20:21]
	s_mov_b32 m0, s55
	s_nop 0
	global_load_lds_dwordx4 v[152:153], off
	v_lshl_add_u64 v[152:153], v[224:225], 0, s[20:21]
	s_mov_b32 m0, s56
	s_nop 0
	global_load_lds_dwordx4 v[152:153], off
	s_waitcnt vmcnt(8)
	s_waitcnt lgkmcnt(0)
	s_barrier
	s_setprio 1
	s_waitcnt lgkmcnt(0)
	v_mfma_f32_16x16x32_bf16 v[62:65], v[140:143], v[190:193], v[62:65]
	v_mfma_f32_16x16x32_bf16 v[58:61], v[148:151], v[190:193], v[58:61]
	v_mfma_f32_16x16x32_bf16 v[46:49], v[140:143], v[198:201], v[46:49]
	v_mfma_f32_16x16x32_bf16 v[42:45], v[148:151], v[198:201], v[42:45]
	v_mfma_f32_16x16x32_bf16 v[30:33], v[140:143], v[206:209], v[30:33]
	v_mfma_f32_16x16x32_bf16 v[26:29], v[148:151], v[206:209], v[26:29]
	v_mfma_f32_16x16x32_bf16 v[14:17], v[140:143], v[214:217], v[14:17]
	v_mfma_f32_16x16x32_bf16 v[10:13], v[148:151], v[214:217], v[10:13]
	v_mfma_f32_16x16x32_bf16 v[62:65], v[144:147], v[194:197], v[62:65]
	v_mfma_f32_16x16x32_bf16 v[58:61], v[164:167], v[194:197], v[58:61]
	v_mfma_f32_16x16x32_bf16 v[46:49], v[144:147], v[202:205], v[46:49]
	v_mfma_f32_16x16x32_bf16 v[42:45], v[164:167], v[202:205], v[42:45]
	v_mfma_f32_16x16x32_bf16 v[30:33], v[144:147], v[210:213], v[30:33]
	v_mfma_f32_16x16x32_bf16 v[26:29], v[164:167], v[210:213], v[26:29]
	v_mfma_f32_16x16x32_bf16 v[14:17], v[144:147], v[218:221], v[14:17]
	v_mfma_f32_16x16x32_bf16 v[10:13], v[164:167], v[218:221], v[10:13]
	v_mfma_f32_16x16x32_bf16 v[54:57], v[168:171], v[190:193], v[54:57]
	v_mfma_f32_16x16x32_bf16 v[50:53], v[182:185], v[190:193], v[50:53]
	v_mfma_f32_16x16x32_bf16 v[38:41], v[168:171], v[198:201], v[38:41]
	v_mfma_f32_16x16x32_bf16 v[34:37], v[182:185], v[198:201], v[34:37]
	v_mfma_f32_16x16x32_bf16 v[22:25], v[168:171], v[206:209], v[22:25]
	v_mfma_f32_16x16x32_bf16 v[18:21], v[182:185], v[206:209], v[18:21]
	v_mfma_f32_16x16x32_bf16 v[6:9], v[168:171], v[214:217], v[6:9]
	v_mfma_f32_16x16x32_bf16 v[2:5], v[182:185], v[214:217], v[2:5]
	v_mfma_f32_16x16x32_bf16 v[54:57], v[178:181], v[194:197], v[54:57]
	v_mfma_f32_16x16x32_bf16 v[50:53], v[186:189], v[194:197], v[50:53]
	v_mfma_f32_16x16x32_bf16 v[38:41], v[178:181], v[202:205], v[38:41]
	v_mfma_f32_16x16x32_bf16 v[34:37], v[186:189], v[202:205], v[34:37]
	v_mfma_f32_16x16x32_bf16 v[22:25], v[178:181], v[210:213], v[22:25]
	v_mfma_f32_16x16x32_bf16 v[18:21], v[186:189], v[210:213], v[18:21]
	v_mfma_f32_16x16x32_bf16 v[6:9], v[178:181], v[218:221], v[6:9]
	v_mfma_f32_16x16x32_bf16 v[2:5], v[186:189], v[218:221], v[2:5]
	s_setprio 0
	s_barrier
	s_add_i32 s61, s61, 2
	s_add_u32 s35, s35, 0x100
	s_addc_u32 s39, s39, 0
	s_cmp_gt_u32 s61, 13
	s_mov_b64 s[40:41], s[42:43]
	s_cbranch_scc0 .LBB0_405
	s_branch .Lpeel_exit_405
.LBB0_405:
	ds_read_b128 v[140:143], v156
	ds_read_b128 v[144:147], v156 offset:1024
	ds_read_b128 v[148:151], v156 offset:2048
	ds_read_b128 v[164:167], v156 offset:3072
	ds_read_b128 v[168:171], v157
	ds_read_b128 v[178:181], v157 offset:1024
	ds_read_b128 v[182:185], v157 offset:2048
	ds_read_b128 v[186:189], v157 offset:3072
	s_add_u32 s42, s40, 0x100
	s_addc_u32 s43, s41, 0
	s_cmp_eq_u32 s61, 12
	s_cselect_b32 s47, s5, s43
	s_cselect_b32 s46, s29, s42
	s_cselect_b32 s45, s27, s39
	s_cselect_b32 s44, s34, s35
	v_lshl_add_u64 v[152:153], s[40:41], 0, v[136:137]
	s_add_i32 m0, s49, 0xc000
	ds_read_b128 v[190:193], v158
	ds_read_b128 v[194:197], v158 offset:1024
	ds_read_b128 v[198:201], v158 offset:2048
	ds_read_b128 v[202:205], v158 offset:3072
	ds_read_b128 v[206:209], v158 offset:4096
	ds_read_b128 v[210:213], v158 offset:5120
	ds_read_b128 v[214:217], v158 offset:6144
	ds_read_b128 v[218:221], v158 offset:7168
	global_load_lds_dwordx4 v[152:153], off
	v_lshl_add_u64 v[152:153], s[40:41], 0, v[138:139]
	s_add_i32 m0, s49, 0xe000
	s_nop 0
	global_load_lds_dwordx4 v[152:153], off
	s_waitcnt vmcnt(8)
	s_waitcnt lgkmcnt(0)
	s_barrier
	s_setprio 1
	s_waitcnt lgkmcnt(0)
	v_mfma_f32_16x16x32_bf16 v[126:129], v[140:143], v[190:193], v[126:129]
	v_mfma_f32_16x16x32_bf16 v[122:125], v[148:151], v[190:193], v[122:125]
	v_mfma_f32_16x16x32_bf16 v[110:113], v[140:143], v[198:201], v[110:113]
	v_mfma_f32_16x16x32_bf16 v[106:109], v[148:151], v[198:201], v[106:109]
	v_mfma_f32_16x16x32_bf16 v[94:97], v[140:143], v[206:209], v[94:97]
	v_mfma_f32_16x16x32_bf16 v[90:93], v[148:151], v[206:209], v[90:93]
	v_mfma_f32_16x16x32_bf16 v[78:81], v[140:143], v[214:217], v[78:81]
	v_mfma_f32_16x16x32_bf16 v[74:77], v[148:151], v[214:217], v[74:77]
	v_mfma_f32_16x16x32_bf16 v[126:129], v[144:147], v[194:197], v[126:129]
	v_mfma_f32_16x16x32_bf16 v[122:125], v[164:167], v[194:197], v[122:125]
	v_mfma_f32_16x16x32_bf16 v[110:113], v[144:147], v[202:205], v[110:113]
	v_mfma_f32_16x16x32_bf16 v[106:109], v[164:167], v[202:205], v[106:109]
	v_mfma_f32_16x16x32_bf16 v[94:97], v[144:147], v[210:213], v[94:97]
	v_mfma_f32_16x16x32_bf16 v[90:93], v[164:167], v[210:213], v[90:93]
	v_mfma_f32_16x16x32_bf16 v[78:81], v[144:147], v[218:221], v[78:81]
	v_mfma_f32_16x16x32_bf16 v[74:77], v[164:167], v[218:221], v[74:77]
	v_mfma_f32_16x16x32_bf16 v[118:121], v[168:171], v[190:193], v[118:121]
	v_mfma_f32_16x16x32_bf16 v[114:117], v[182:185], v[190:193], v[114:117]
	v_mfma_f32_16x16x32_bf16 v[102:105], v[168:171], v[198:201], v[102:105]
	v_mfma_f32_16x16x32_bf16 v[98:101], v[182:185], v[198:201], v[98:101]
	v_mfma_f32_16x16x32_bf16 v[86:89], v[168:171], v[206:209], v[86:89]
	v_mfma_f32_16x16x32_bf16 v[82:85], v[182:185], v[206:209], v[82:85]
	v_mfma_f32_16x16x32_bf16 v[70:73], v[168:171], v[214:217], v[70:73]
	v_mfma_f32_16x16x32_bf16 v[66:69], v[182:185], v[214:217], v[66:69]
	v_mfma_f32_16x16x32_bf16 v[118:121], v[178:181], v[194:197], v[118:121]
	v_mfma_f32_16x16x32_bf16 v[114:117], v[186:189], v[194:197], v[114:117]
	v_mfma_f32_16x16x32_bf16 v[102:105], v[178:181], v[202:205], v[102:105]
	v_mfma_f32_16x16x32_bf16 v[98:101], v[186:189], v[202:205], v[98:101]
	v_mfma_f32_16x16x32_bf16 v[86:89], v[178:181], v[210:213], v[86:89]
	v_mfma_f32_16x16x32_bf16 v[82:85], v[186:189], v[210:213], v[82:85]
	v_mfma_f32_16x16x32_bf16 v[70:73], v[178:181], v[218:221], v[70:73]
	v_mfma_f32_16x16x32_bf16 v[66:69], v[186:189], v[218:221], v[66:69]
	s_setprio 0
	s_barrier
	s_add_i32 s40, s59, s48
	v_lshl_add_u64 v[152:153], s[44:45], 0, v[132:133]
	s_mov_b32 m0, s40
	ds_read_b128 v[190:193], v158 offset:16384
	ds_read_b128 v[194:197], v158 offset:17408
	ds_read_b128 v[198:201], v158 offset:18432
	ds_read_b128 v[202:205], v158 offset:19456
	ds_read_b128 v[206:209], v158 offset:20480
	ds_read_b128 v[210:213], v158 offset:21504
	ds_read_b128 v[214:217], v158 offset:22528
	ds_read_b128 v[218:221], v158 offset:23552
	global_load_lds_dwordx4 v[152:153], off
	s_add_i32 m0, s40, 0x2000
	s_add_u32 s40, s44, 0x40000
	v_lshl_add_u64 v[172:173], s[44:45], 0, v[130:131]
	s_addc_u32 s41, s45, 0
	s_add_i32 s62, s60, s48
	global_load_lds_dwordx4 v[172:173], off
	v_lshl_add_u64 v[222:223], s[40:41], 0, v[132:133]
	s_mov_b32 m0, s62
	v_lshl_add_u64 v[224:225], s[46:47], 0, v[130:131]
	global_load_lds_dwordx4 v[222:223], off
	v_lshl_add_u64 v[222:223], s[40:41], 0, v[130:131]
	s_add_i32 m0, s62, 0x2000
	s_nop 0
	global_load_lds_dwordx4 v[222:223], off
	v_lshl_add_u64 v[222:223], s[46:47], 0, v[132:133]
	s_mov_b32 m0, s49
	s_nop 0
	global_load_lds_dwordx4 v[222:223], off
	s_mov_b32 m0, s50
	s_nop 0
	global_load_lds_dwordx4 v[224:225], off
	s_waitcnt vmcnt(8)
	s_waitcnt lgkmcnt(0)
	s_barrier
	s_setprio 1
	s_waitcnt lgkmcnt(0)
	v_mfma_f32_16x16x32_bf16 v[62:65], v[140:143], v[190:193], v[62:65]
	v_mfma_f32_16x16x32_bf16 v[58:61], v[148:151], v[190:193], v[58:61]
	v_mfma_f32_16x16x32_bf16 v[46:49], v[140:143], v[198:201], v[46:49]
	v_mfma_f32_16x16x32_bf16 v[42:45], v[148:151], v[198:201], v[42:45]
	v_mfma_f32_16x16x32_bf16 v[30:33], v[140:143], v[206:209], v[30:33]
	v_mfma_f32_16x16x32_bf16 v[26:29], v[148:151], v[206:209], v[26:29]
	v_mfma_f32_16x16x32_bf16 v[14:17], v[140:143], v[214:217], v[14:17]
	v_mfma_f32_16x16x32_bf16 v[10:13], v[148:151], v[214:217], v[10:13]
	v_mfma_f32_16x16x32_bf16 v[62:65], v[144:147], v[194:197], v[62:65]
	v_mfma_f32_16x16x32_bf16 v[58:61], v[164:167], v[194:197], v[58:61]
	v_mfma_f32_16x16x32_bf16 v[46:49], v[144:147], v[202:205], v[46:49]
	v_mfma_f32_16x16x32_bf16 v[42:45], v[164:167], v[202:205], v[42:45]
	v_mfma_f32_16x16x32_bf16 v[30:33], v[144:147], v[210:213], v[30:33]
	v_mfma_f32_16x16x32_bf16 v[26:29], v[164:167], v[210:213], v[26:29]
	v_mfma_f32_16x16x32_bf16 v[14:17], v[144:147], v[218:221], v[14:17]
	v_mfma_f32_16x16x32_bf16 v[10:13], v[164:167], v[218:221], v[10:13]
	v_mfma_f32_16x16x32_bf16 v[54:57], v[168:171], v[190:193], v[54:57]
	v_mfma_f32_16x16x32_bf16 v[50:53], v[182:185], v[190:193], v[50:53]
	v_mfma_f32_16x16x32_bf16 v[38:41], v[168:171], v[198:201], v[38:41]
	v_mfma_f32_16x16x32_bf16 v[34:37], v[182:185], v[198:201], v[34:37]
	v_mfma_f32_16x16x32_bf16 v[22:25], v[168:171], v[206:209], v[22:25]
	v_mfma_f32_16x16x32_bf16 v[18:21], v[182:185], v[206:209], v[18:21]
	v_mfma_f32_16x16x32_bf16 v[6:9], v[168:171], v[214:217], v[6:9]
	v_mfma_f32_16x16x32_bf16 v[2:5], v[182:185], v[214:217], v[2:5]
	v_mfma_f32_16x16x32_bf16 v[54:57], v[178:181], v[194:197], v[54:57]
	v_mfma_f32_16x16x32_bf16 v[50:53], v[186:189], v[194:197], v[50:53]
	v_mfma_f32_16x16x32_bf16 v[38:41], v[178:181], v[202:205], v[38:41]
	v_mfma_f32_16x16x32_bf16 v[34:37], v[186:189], v[202:205], v[34:37]
	v_mfma_f32_16x16x32_bf16 v[22:25], v[178:181], v[210:213], v[22:25]
	v_mfma_f32_16x16x32_bf16 v[18:21], v[186:189], v[210:213], v[18:21]
	v_mfma_f32_16x16x32_bf16 v[6:9], v[178:181], v[218:221], v[6:9]
	v_mfma_f32_16x16x32_bf16 v[2:5], v[186:189], v[218:221], v[2:5]
	s_setprio 0
	s_barrier
	s_add_i32 s62, 0, 0x18000
	v_add_u32_e32 v134, s62, v154
	s_add_i32 s63, 0, 0x1c000
	ds_read_b128 v[140:143], v134
	ds_read_b128 v[144:147], v134 offset:1024
	ds_read_b128 v[148:151], v134 offset:2048
	ds_read_b128 v[164:167], v134 offset:3072
	v_add_u32_e32 v134, s63, v154
	ds_read_b128 v[168:171], v134
	ds_read_b128 v[178:181], v134 offset:1024
	ds_read_b128 v[182:185], v134 offset:2048
	ds_read_b128 v[186:189], v134 offset:3072
	s_add_u32 s40, s46, 0x40000
	s_addc_u32 s41, s47, 0
	s_mov_b32 m0, s51
	v_lshl_add_u64 v[226:227], s[40:41], 0, v[132:133]
	ds_read_b128 v[190:193], v158 offset:32768
	ds_read_b128 v[194:197], v158 offset:33792
	ds_read_b128 v[198:201], v158 offset:34816
	ds_read_b128 v[202:205], v158 offset:35840
	ds_read_b128 v[206:209], v158 offset:36864
	ds_read_b128 v[210:213], v158 offset:37888
	ds_read_b128 v[214:217], v158 offset:38912
	ds_read_b128 v[218:221], v158 offset:39936
	global_load_lds_dwordx4 v[226:227], off
	v_lshl_add_u64 v[226:227], s[40:41], 0, v[130:131]
	s_mov_b32 m0, s52
	s_nop 0
	global_load_lds_dwordx4 v[226:227], off
	s_waitcnt vmcnt(8)
	s_waitcnt lgkmcnt(0)
	s_barrier
	s_setprio 1
	s_waitcnt lgkmcnt(0)
	v_mfma_f32_16x16x32_bf16 v[126:129], v[140:143], v[190:193], v[126:129]
	v_mfma_f32_16x16x32_bf16 v[122:125], v[148:151], v[190:193], v[122:125]
	v_mfma_f32_16x16x32_bf16 v[110:113], v[140:143], v[198:201], v[110:113]
	v_mfma_f32_16x16x32_bf16 v[106:109], v[148:151], v[198:201], v[106:109]
	v_mfma_f32_16x16x32_bf16 v[94:97], v[140:143], v[206:209], v[94:97]
	v_mfma_f32_16x16x32_bf16 v[90:93], v[148:151], v[206:209], v[90:93]
	v_mfma_f32_16x16x32_bf16 v[78:81], v[140:143], v[214:217], v[78:81]
	v_mfma_f32_16x16x32_bf16 v[74:77], v[148:151], v[214:217], v[74:77]
	v_mfma_f32_16x16x32_bf16 v[126:129], v[144:147], v[194:197], v[126:129]
	v_mfma_f32_16x16x32_bf16 v[122:125], v[164:167], v[194:197], v[122:125]
	v_mfma_f32_16x16x32_bf16 v[110:113], v[144:147], v[202:205], v[110:113]
	v_mfma_f32_16x16x32_bf16 v[106:109], v[164:167], v[202:205], v[106:109]
	v_mfma_f32_16x16x32_bf16 v[94:97], v[144:147], v[210:213], v[94:97]
	v_mfma_f32_16x16x32_bf16 v[90:93], v[164:167], v[210:213], v[90:93]
	v_mfma_f32_16x16x32_bf16 v[78:81], v[144:147], v[218:221], v[78:81]
	v_mfma_f32_16x16x32_bf16 v[74:77], v[164:167], v[218:221], v[74:77]
	v_mfma_f32_16x16x32_bf16 v[118:121], v[168:171], v[190:193], v[118:121]
	v_mfma_f32_16x16x32_bf16 v[114:117], v[182:185], v[190:193], v[114:117]
	v_mfma_f32_16x16x32_bf16 v[102:105], v[168:171], v[198:201], v[102:105]
	v_mfma_f32_16x16x32_bf16 v[98:101], v[182:185], v[198:201], v[98:101]
	v_mfma_f32_16x16x32_bf16 v[86:89], v[168:171], v[206:209], v[86:89]
	v_mfma_f32_16x16x32_bf16 v[82:85], v[182:185], v[206:209], v[82:85]
	v_mfma_f32_16x16x32_bf16 v[70:73], v[168:171], v[214:217], v[70:73]
	v_mfma_f32_16x16x32_bf16 v[66:69], v[182:185], v[214:217], v[66:69]
	v_mfma_f32_16x16x32_bf16 v[118:121], v[178:181], v[194:197], v[118:121]
	v_mfma_f32_16x16x32_bf16 v[114:117], v[186:189], v[194:197], v[114:117]
	v_mfma_f32_16x16x32_bf16 v[102:105], v[178:181], v[202:205], v[102:105]
	v_mfma_f32_16x16x32_bf16 v[98:101], v[186:189], v[202:205], v[98:101]
	v_mfma_f32_16x16x32_bf16 v[86:89], v[178:181], v[210:213], v[86:89]
	v_mfma_f32_16x16x32_bf16 v[82:85], v[186:189], v[210:213], v[82:85]
	v_mfma_f32_16x16x32_bf16 v[70:73], v[178:181], v[218:221], v[70:73]
	v_mfma_f32_16x16x32_bf16 v[66:69], v[186:189], v[218:221], v[66:69]
	s_setprio 0
	s_barrier
	s_add_i32 s40, s62, s48
	v_lshl_add_u64 v[152:153], v[152:153], 0, s[20:21]
	s_mov_b32 m0, s40
	ds_read_b128 v[190:193], v158 offset:49152
	ds_read_b128 v[194:197], v158 offset:50176
	ds_read_b128 v[198:201], v158 offset:51200
	ds_read_b128 v[202:205], v158 offset:52224
	ds_read_b128 v[206:209], v158 offset:53248
	ds_read_b128 v[210:213], v158 offset:54272
	ds_read_b128 v[214:217], v158 offset:55296
	ds_read_b128 v[218:221], v158 offset:56320
	global_load_lds_dwordx4 v[152:153], off
	s_add_i32 m0, s40, 0x2000
	s_add_u32 s40, s44, 0x40080
	v_lshl_add_u64 v[152:153], v[172:173], 0, s[20:21]
	s_addc_u32 s41, s45, 0
	s_add_i32 s44, s63, s48
	global_load_lds_dwordx4 v[152:153], off
	v_lshl_add_u64 v[152:153], s[40:41], 0, v[132:133]
	s_mov_b32 m0, s44
	s_nop 0
	global_load_lds_dwordx4 v[152:153], off
	v_lshl_add_u64 v[152:153], s[40:41], 0, v[130:131]
	s_add_i32 m0, s44, 0x2000
	s_nop 0
	global_load_lds_dwordx4 v[152:153], off
	v_lshl_add_u64 v[152:153], v[222:223], 0, s[20:21]
	s_mov_b32 m0, s55
	s_nop 0
	global_load_lds_dwordx4 v[152:153], off
	v_lshl_add_u64 v[152:153], v[224:225], 0, s[20:21]
	s_mov_b32 m0, s56
	s_nop 0
	global_load_lds_dwordx4 v[152:153], off
	s_waitcnt vmcnt(8)
	s_waitcnt lgkmcnt(0)
	s_barrier
	s_setprio 1
	s_waitcnt lgkmcnt(0)
	v_mfma_f32_16x16x32_bf16 v[62:65], v[140:143], v[190:193], v[62:65]
	v_mfma_f32_16x16x32_bf16 v[58:61], v[148:151], v[190:193], v[58:61]
	v_mfma_f32_16x16x32_bf16 v[46:49], v[140:143], v[198:201], v[46:49]
	v_mfma_f32_16x16x32_bf16 v[42:45], v[148:151], v[198:201], v[42:45]
	v_mfma_f32_16x16x32_bf16 v[30:33], v[140:143], v[206:209], v[30:33]
	v_mfma_f32_16x16x32_bf16 v[26:29], v[148:151], v[206:209], v[26:29]
	v_mfma_f32_16x16x32_bf16 v[14:17], v[140:143], v[214:217], v[14:17]
	v_mfma_f32_16x16x32_bf16 v[10:13], v[148:151], v[214:217], v[10:13]
	v_mfma_f32_16x16x32_bf16 v[62:65], v[144:147], v[194:197], v[62:65]
	v_mfma_f32_16x16x32_bf16 v[58:61], v[164:167], v[194:197], v[58:61]
	v_mfma_f32_16x16x32_bf16 v[46:49], v[144:147], v[202:205], v[46:49]
	v_mfma_f32_16x16x32_bf16 v[42:45], v[164:167], v[202:205], v[42:45]
	v_mfma_f32_16x16x32_bf16 v[30:33], v[144:147], v[210:213], v[30:33]
	v_mfma_f32_16x16x32_bf16 v[26:29], v[164:167], v[210:213], v[26:29]
	v_mfma_f32_16x16x32_bf16 v[14:17], v[144:147], v[218:221], v[14:17]
	v_mfma_f32_16x16x32_bf16 v[10:13], v[164:167], v[218:221], v[10:13]
	v_mfma_f32_16x16x32_bf16 v[54:57], v[168:171], v[190:193], v[54:57]
	v_mfma_f32_16x16x32_bf16 v[50:53], v[182:185], v[190:193], v[50:53]
	v_mfma_f32_16x16x32_bf16 v[38:41], v[168:171], v[198:201], v[38:41]
	v_mfma_f32_16x16x32_bf16 v[34:37], v[182:185], v[198:201], v[34:37]
	v_mfma_f32_16x16x32_bf16 v[22:25], v[168:171], v[206:209], v[22:25]
	v_mfma_f32_16x16x32_bf16 v[18:21], v[182:185], v[206:209], v[18:21]
	v_mfma_f32_16x16x32_bf16 v[6:9], v[168:171], v[214:217], v[6:9]
	v_mfma_f32_16x16x32_bf16 v[2:5], v[182:185], v[214:217], v[2:5]
	v_mfma_f32_16x16x32_bf16 v[54:57], v[178:181], v[194:197], v[54:57]
	v_mfma_f32_16x16x32_bf16 v[50:53], v[186:189], v[194:197], v[50:53]
	v_mfma_f32_16x16x32_bf16 v[38:41], v[178:181], v[202:205], v[38:41]
	v_mfma_f32_16x16x32_bf16 v[34:37], v[186:189], v[202:205], v[34:37]
	v_mfma_f32_16x16x32_bf16 v[22:25], v[178:181], v[210:213], v[22:25]
	v_mfma_f32_16x16x32_bf16 v[18:21], v[186:189], v[210:213], v[18:21]
	v_mfma_f32_16x16x32_bf16 v[6:9], v[178:181], v[218:221], v[6:9]
	v_mfma_f32_16x16x32_bf16 v[2:5], v[186:189], v[218:221], v[2:5]
	s_setprio 0
	s_barrier
	s_add_i32 s61, s61, 2
	s_add_u32 s35, s35, 0x100
	s_addc_u32 s39, s39, 0
	s_cmp_gt_u32 s61, 13
	s_mov_b64 s[40:41], s[42:43]
	s_cbranch_scc0 .LBB0_405

.LBB0_1029:
	v_add_u32_e32 v179, s28, v1
	ds_read_b128 v[180:183], v179
	ds_read_b128 v[184:187], v179 offset:1024
	ds_read_b128 v[188:191], v179 offset:2048
	ds_read_b128 v[192:195], v179 offset:3072
	v_add_u32_e32 v179, s29, v1
	ds_read_b128 v[196:199], v179
	ds_read_b128 v[200:203], v179 offset:1024
	ds_read_b128 v[204:207], v179 offset:2048
	ds_read_b128 v[208:211], v179 offset:3072
	s_add_u32 s22, s20, 0xfff80080
	s_addc_u32 s23, s21, -1
	s_cmp_eq_u32 s46, 4
	s_cselect_b32 s25, s7, s23
	s_cselect_b32 s24, s6, s22
	s_cselect_b32 s23, s1, s45
	s_cselect_b32 s22, s0, s44
	s_mov_b32 m0, s30
	v_lshl_add_u64 v[244:245], s[20:21], 0, v[170:171]
	ds_read_b128 v[212:215], v178
	ds_read_b128 v[216:219], v178 offset:1024
	ds_read_b128 v[220:223], v178 offset:2048
	ds_read_b128 v[224:227], v178 offset:3072
	ds_read_b128 v[228:231], v178 offset:4096
	ds_read_b128 v[232:235], v178 offset:5120
	ds_read_b128 v[236:239], v178 offset:6144
	ds_read_b128 v[240:243], v178 offset:7168
	global_load_lds_dwordx4 v[244:245], off
	v_lshl_add_u64 v[244:245], s[20:21], 0, v[172:173]
	s_mov_b32 m0, s31
	s_nop 0
	global_load_lds_dwordx4 v[244:245], off
	s_waitcnt vmcnt(8)
	s_waitcnt lgkmcnt(0)
	s_barrier
	s_setprio 1
	s_waitcnt lgkmcnt(0)
	v_mfma_f32_16x16x32_bf16 v[126:129], v[180:183], v[212:215], v[126:129]
	v_mfma_f32_16x16x32_bf16 v[122:125], v[188:191], v[212:215], v[122:125]
	v_mfma_f32_16x16x32_bf16 v[118:121], v[180:183], v[220:223], v[118:121]
	v_mfma_f32_16x16x32_bf16 v[114:117], v[188:191], v[220:223], v[114:117]
	v_mfma_f32_16x16x32_bf16 v[110:113], v[180:183], v[228:231], v[110:113]
	v_mfma_f32_16x16x32_bf16 v[106:109], v[188:191], v[228:231], v[106:109]
	v_mfma_f32_16x16x32_bf16 v[102:105], v[180:183], v[236:239], v[102:105]
	v_mfma_f32_16x16x32_bf16 v[98:101], v[188:191], v[236:239], v[98:101]
	v_mfma_f32_16x16x32_bf16 v[126:129], v[184:187], v[216:219], v[126:129]
	v_mfma_f32_16x16x32_bf16 v[122:125], v[192:195], v[216:219], v[122:125]
	v_mfma_f32_16x16x32_bf16 v[118:121], v[184:187], v[224:227], v[118:121]
	v_mfma_f32_16x16x32_bf16 v[114:117], v[192:195], v[224:227], v[114:117]
	v_mfma_f32_16x16x32_bf16 v[110:113], v[184:187], v[232:235], v[110:113]
	v_mfma_f32_16x16x32_bf16 v[106:109], v[192:195], v[232:235], v[106:109]
	v_mfma_f32_16x16x32_bf16 v[102:105], v[184:187], v[240:243], v[102:105]
	v_mfma_f32_16x16x32_bf16 v[98:101], v[192:195], v[240:243], v[98:101]
	v_mfma_f32_16x16x32_bf16 v[94:97], v[196:199], v[212:215], v[94:97]
	v_mfma_f32_16x16x32_bf16 v[90:93], v[204:207], v[212:215], v[90:93]
	v_mfma_f32_16x16x32_bf16 v[86:89], v[196:199], v[220:223], v[86:89]
	v_mfma_f32_16x16x32_bf16 v[82:85], v[204:207], v[220:223], v[82:85]
	v_mfma_f32_16x16x32_bf16 v[78:81], v[196:199], v[228:231], v[78:81]
	v_mfma_f32_16x16x32_bf16 v[74:77], v[204:207], v[228:231], v[74:77]
	v_mfma_f32_16x16x32_bf16 v[70:73], v[196:199], v[236:239], v[70:73]
	v_mfma_f32_16x16x32_bf16 v[66:69], v[204:207], v[236:239], v[66:69]
	v_mfma_f32_16x16x32_bf16 v[94:97], v[200:203], v[216:219], v[94:97]
	v_mfma_f32_16x16x32_bf16 v[90:93], v[208:211], v[216:219], v[90:93]
	v_mfma_f32_16x16x32_bf16 v[86:89], v[200:203], v[224:227], v[86:89]
	v_mfma_f32_16x16x32_bf16 v[82:85], v[208:211], v[224:227], v[82:85]
	v_mfma_f32_16x16x32_bf16 v[78:81], v[200:203], v[232:235], v[78:81]
	v_mfma_f32_16x16x32_bf16 v[74:77], v[208:211], v[232:235], v[74:77]
	v_mfma_f32_16x16x32_bf16 v[70:73], v[200:203], v[240:243], v[70:73]
	v_mfma_f32_16x16x32_bf16 v[66:69], v[208:211], v[240:243], v[66:69]
	s_setprio 0
	s_barrier
	s_mov_b32 m0, s34
	v_lshl_add_u64 v[244:245], s[22:23], 0, v[132:133]
	s_add_u32 s48, s22, 0x80000
	ds_read_b128 v[212:215], v178 offset:16384
	ds_read_b128 v[216:219], v178 offset:17408
	ds_read_b128 v[220:223], v178 offset:18432
	ds_read_b128 v[224:227], v178 offset:19456
	ds_read_b128 v[228:231], v178 offset:20480
	ds_read_b128 v[232:235], v178 offset:21504
	ds_read_b128 v[236:239], v178 offset:22528
	ds_read_b128 v[240:243], v178 offset:23552
	global_load_lds_dwordx4 v[244:245], off
	v_lshl_add_u64 v[246:247], s[22:23], 0, v[136:137]
	s_mov_b32 m0, s35
	s_addc_u32 s49, s23, 0
	global_load_lds_dwordx4 v[246:247], off
	v_lshl_add_u64 v[248:249], s[48:49], 0, v[132:133]
	s_mov_b32 m0, s36
	v_lshl_add_u64 v[250:251], s[24:25], 0, v[134:135]
	global_load_lds_dwordx4 v[248:249], off
	v_lshl_add_u64 v[248:249], s[48:49], 0, v[136:137]
	s_mov_b32 m0, s37
	s_nop 0
	global_load_lds_dwordx4 v[248:249], off
	v_lshl_add_u64 v[248:249], s[24:25], 0, v[130:131]
	s_mov_b32 m0, s3
	s_nop 0
	global_load_lds_dwordx4 v[248:249], off
	s_mov_b32 m0, s14
	s_nop 0
	global_load_lds_dwordx4 v[250:251], off
	s_waitcnt vmcnt(8)
	s_waitcnt lgkmcnt(0)
	s_barrier
	s_setprio 1
	s_waitcnt lgkmcnt(0)
	v_mfma_f32_16x16x32_bf16 v[62:65], v[180:183], v[212:215], v[62:65]
	v_mfma_f32_16x16x32_bf16 v[58:61], v[188:191], v[212:215], v[58:61]
	v_mfma_f32_16x16x32_bf16 v[54:57], v[180:183], v[220:223], v[54:57]
	v_mfma_f32_16x16x32_bf16 v[50:53], v[188:191], v[220:223], v[50:53]
	v_mfma_f32_16x16x32_bf16 v[46:49], v[180:183], v[228:231], v[46:49]
	v_mfma_f32_16x16x32_bf16 v[42:45], v[188:191], v[228:231], v[42:45]
	v_mfma_f32_16x16x32_bf16 v[38:41], v[180:183], v[236:239], v[38:41]
	v_mfma_f32_16x16x32_bf16 v[34:37], v[188:191], v[236:239], v[34:37]
	v_mfma_f32_16x16x32_bf16 v[62:65], v[184:187], v[216:219], v[62:65]
	v_mfma_f32_16x16x32_bf16 v[58:61], v[192:195], v[216:219], v[58:61]
	v_mfma_f32_16x16x32_bf16 v[54:57], v[184:187], v[224:227], v[54:57]
	v_mfma_f32_16x16x32_bf16 v[50:53], v[192:195], v[224:227], v[50:53]
	v_mfma_f32_16x16x32_bf16 v[46:49], v[184:187], v[232:235], v[46:49]
	v_mfma_f32_16x16x32_bf16 v[42:45], v[192:195], v[232:235], v[42:45]
	v_mfma_f32_16x16x32_bf16 v[38:41], v[184:187], v[240:243], v[38:41]
	v_mfma_f32_16x16x32_bf16 v[34:37], v[192:195], v[240:243], v[34:37]
	v_mfma_f32_16x16x32_bf16 v[30:33], v[196:199], v[212:215], v[30:33]
	v_mfma_f32_16x16x32_bf16 v[26:29], v[204:207], v[212:215], v[26:29]
	v_mfma_f32_16x16x32_bf16 v[22:25], v[196:199], v[220:223], v[22:25]
	v_mfma_f32_16x16x32_bf16 v[18:21], v[204:207], v[220:223], v[18:21]
	v_mfma_f32_16x16x32_bf16 v[14:17], v[196:199], v[228:231], v[14:17]
	v_mfma_f32_16x16x32_bf16 v[10:13], v[204:207], v[228:231], v[10:13]
	v_mfma_f32_16x16x32_bf16 v[6:9], v[196:199], v[236:239], v[6:9]
	v_mfma_f32_16x16x32_bf16 v[2:5], v[204:207], v[236:239], v[2:5]
	v_mfma_f32_16x16x32_bf16 v[30:33], v[200:203], v[216:219], v[30:33]
	v_mfma_f32_16x16x32_bf16 v[26:29], v[208:211], v[216:219], v[26:29]
	v_mfma_f32_16x16x32_bf16 v[22:25], v[200:203], v[224:227], v[22:25]
	v_mfma_f32_16x16x32_bf16 v[18:21], v[208:211], v[224:227], v[18:21]
	v_mfma_f32_16x16x32_bf16 v[14:17], v[200:203], v[232:235], v[14:17]
	v_mfma_f32_16x16x32_bf16 v[10:13], v[208:211], v[232:235], v[10:13]
	v_mfma_f32_16x16x32_bf16 v[6:9], v[200:203], v[240:243], v[6:9]
	v_mfma_f32_16x16x32_bf16 v[2:5], v[208:211], v[240:243], v[2:5]
	s_setprio 0
	s_barrier
	v_add_u32_e32 v179, s38, v1
	ds_read_b128 v[180:183], v179
	ds_read_b128 v[184:187], v179 offset:1024
	ds_read_b128 v[188:191], v179 offset:2048
	ds_read_b128 v[192:195], v179 offset:3072
	v_add_u32_e32 v179, s39, v1
	ds_read_b128 v[196:199], v179
	ds_read_b128 v[200:203], v179 offset:1024
	ds_read_b128 v[204:207], v179 offset:2048
	ds_read_b128 v[208:211], v179 offset:3072
	s_add_u32 s24, s24, 0x80000
	s_addc_u32 s25, s25, 0
	s_mov_b32 m0, s15
	v_lshl_add_u64 v[252:253], s[24:25], 0, v[130:131]
	ds_read_b128 v[212:215], v178 offset:32768
	ds_read_b128 v[216:219], v178 offset:33792
	ds_read_b128 v[220:223], v178 offset:34816
	ds_read_b128 v[224:227], v178 offset:35840
	ds_read_b128 v[228:231], v178 offset:36864
	ds_read_b128 v[232:235], v178 offset:37888
	ds_read_b128 v[236:239], v178 offset:38912
	ds_read_b128 v[240:243], v178 offset:39936
	global_load_lds_dwordx4 v[252:253], off
	v_lshl_add_u64 v[252:253], s[24:25], 0, v[134:135]
	s_mov_b32 m0, s16
	s_nop 0
	global_load_lds_dwordx4 v[252:253], off
	s_waitcnt vmcnt(8)
	s_waitcnt lgkmcnt(0)
	s_barrier
	s_setprio 1
	s_waitcnt lgkmcnt(0)
	v_mfma_f32_16x16x32_bf16 v[126:129], v[180:183], v[212:215], v[126:129]
	v_mfma_f32_16x16x32_bf16 v[122:125], v[188:191], v[212:215], v[122:125]
	v_mfma_f32_16x16x32_bf16 v[118:121], v[180:183], v[220:223], v[118:121]
	v_mfma_f32_16x16x32_bf16 v[114:117], v[188:191], v[220:223], v[114:117]
	v_mfma_f32_16x16x32_bf16 v[110:113], v[180:183], v[228:231], v[110:113]
	v_mfma_f32_16x16x32_bf16 v[106:109], v[188:191], v[228:231], v[106:109]
	v_mfma_f32_16x16x32_bf16 v[102:105], v[180:183], v[236:239], v[102:105]
	v_mfma_f32_16x16x32_bf16 v[98:101], v[188:191], v[236:239], v[98:101]
	v_mfma_f32_16x16x32_bf16 v[126:129], v[184:187], v[216:219], v[126:129]
	v_mfma_f32_16x16x32_bf16 v[122:125], v[192:195], v[216:219], v[122:125]
	v_mfma_f32_16x16x32_bf16 v[118:121], v[184:187], v[224:227], v[118:121]
	v_mfma_f32_16x16x32_bf16 v[114:117], v[192:195], v[224:227], v[114:117]
	v_mfma_f32_16x16x32_bf16 v[110:113], v[184:187], v[232:235], v[110:113]
	v_mfma_f32_16x16x32_bf16 v[106:109], v[192:195], v[232:235], v[106:109]
	v_mfma_f32_16x16x32_bf16 v[102:105], v[184:187], v[240:243], v[102:105]
	v_mfma_f32_16x16x32_bf16 v[98:101], v[192:195], v[240:243], v[98:101]
	v_mfma_f32_16x16x32_bf16 v[94:97], v[196:199], v[212:215], v[94:97]
	v_mfma_f32_16x16x32_bf16 v[90:93], v[204:207], v[212:215], v[90:93]
	v_mfma_f32_16x16x32_bf16 v[86:89], v[196:199], v[220:223], v[86:89]
	v_mfma_f32_16x16x32_bf16 v[82:85], v[204:207], v[220:223], v[82:85]
	v_mfma_f32_16x16x32_bf16 v[78:81], v[196:199], v[228:231], v[78:81]
	v_mfma_f32_16x16x32_bf16 v[74:77], v[204:207], v[228:231], v[74:77]
	v_mfma_f32_16x16x32_bf16 v[70:73], v[196:199], v[236:239], v[70:73]
	v_mfma_f32_16x16x32_bf16 v[66:69], v[204:207], v[236:239], v[66:69]
	v_mfma_f32_16x16x32_bf16 v[94:97], v[200:203], v[216:219], v[94:97]
	v_mfma_f32_16x16x32_bf16 v[90:93], v[208:211], v[216:219], v[90:93]
	v_mfma_f32_16x16x32_bf16 v[86:89], v[200:203], v[224:227], v[86:89]
	v_mfma_f32_16x16x32_bf16 v[82:85], v[208:211], v[224:227], v[82:85]
	v_mfma_f32_16x16x32_bf16 v[78:81], v[200:203], v[232:235], v[78:81]
	v_mfma_f32_16x16x32_bf16 v[74:77], v[208:211], v[232:235], v[74:77]
	v_mfma_f32_16x16x32_bf16 v[70:73], v[200:203], v[240:243], v[70:73]
	v_mfma_f32_16x16x32_bf16 v[66:69], v[208:211], v[240:243], v[66:69]
	s_setprio 0
	s_barrier
	s_mov_b32 m0, s40
	v_lshl_add_u64 v[244:245], v[244:245], 0, s[8:9]
	s_add_u32 s22, s22, 0x80080
	ds_read_b128 v[212:215], v178 offset:49152
	ds_read_b128 v[216:219], v178 offset:50176
	ds_read_b128 v[220:223], v178 offset:51200
	ds_read_b128 v[224:227], v178 offset:52224
	ds_read_b128 v[228:231], v178 offset:53248
	ds_read_b128 v[232:235], v178 offset:54272
	ds_read_b128 v[236:239], v178 offset:55296
	ds_read_b128 v[240:243], v178 offset:56320
	global_load_lds_dwordx4 v[244:245], off
	v_lshl_add_u64 v[244:245], v[246:247], 0, s[8:9]
	s_mov_b32 m0, s41
	s_addc_u32 s23, s23, 0
	global_load_lds_dwordx4 v[244:245], off
	v_lshl_add_u64 v[244:245], s[22:23], 0, v[132:133]
	s_mov_b32 m0, s42
	s_nop 0
	global_load_lds_dwordx4 v[244:245], off
	v_lshl_add_u64 v[244:245], s[22:23], 0, v[136:137]
	s_mov_b32 m0, s43
	s_nop 0
	global_load_lds_dwordx4 v[244:245], off
	v_lshl_add_u64 v[244:245], v[248:249], 0, s[8:9]
	s_mov_b32 m0, s17
	s_nop 0
	global_load_lds_dwordx4 v[244:245], off
	v_lshl_add_u64 v[244:245], v[250:251], 0, s[8:9]
	s_mov_b32 m0, s26
	s_nop 0
	global_load_lds_dwordx4 v[244:245], off
	s_waitcnt vmcnt(8)
	s_waitcnt lgkmcnt(0)
	s_barrier
	s_setprio 1
	s_waitcnt lgkmcnt(0)
	v_mfma_f32_16x16x32_bf16 v[62:65], v[180:183], v[212:215], v[62:65]
	v_mfma_f32_16x16x32_bf16 v[58:61], v[188:191], v[212:215], v[58:61]
	v_mfma_f32_16x16x32_bf16 v[54:57], v[180:183], v[220:223], v[54:57]
	v_mfma_f32_16x16x32_bf16 v[50:53], v[188:191], v[220:223], v[50:53]
	v_mfma_f32_16x16x32_bf16 v[46:49], v[180:183], v[228:231], v[46:49]
	v_mfma_f32_16x16x32_bf16 v[42:45], v[188:191], v[228:231], v[42:45]
	v_mfma_f32_16x16x32_bf16 v[38:41], v[180:183], v[236:239], v[38:41]
	v_mfma_f32_16x16x32_bf16 v[34:37], v[188:191], v[236:239], v[34:37]
	v_mfma_f32_16x16x32_bf16 v[62:65], v[184:187], v[216:219], v[62:65]
	v_mfma_f32_16x16x32_bf16 v[58:61], v[192:195], v[216:219], v[58:61]
	v_mfma_f32_16x16x32_bf16 v[54:57], v[184:187], v[224:227], v[54:57]
	v_mfma_f32_16x16x32_bf16 v[50:53], v[192:195], v[224:227], v[50:53]
	v_mfma_f32_16x16x32_bf16 v[46:49], v[184:187], v[232:235], v[46:49]
	v_mfma_f32_16x16x32_bf16 v[42:45], v[192:195], v[232:235], v[42:45]
	v_mfma_f32_16x16x32_bf16 v[38:41], v[184:187], v[240:243], v[38:41]
	v_mfma_f32_16x16x32_bf16 v[34:37], v[192:195], v[240:243], v[34:37]
	v_mfma_f32_16x16x32_bf16 v[30:33], v[196:199], v[212:215], v[30:33]
	v_mfma_f32_16x16x32_bf16 v[26:29], v[204:207], v[212:215], v[26:29]
	v_mfma_f32_16x16x32_bf16 v[22:25], v[196:199], v[220:223], v[22:25]
	v_mfma_f32_16x16x32_bf16 v[18:21], v[204:207], v[220:223], v[18:21]
	v_mfma_f32_16x16x32_bf16 v[14:17], v[196:199], v[228:231], v[14:17]
	v_mfma_f32_16x16x32_bf16 v[10:13], v[204:207], v[228:231], v[10:13]
	v_mfma_f32_16x16x32_bf16 v[6:9], v[196:199], v[236:239], v[6:9]
	v_mfma_f32_16x16x32_bf16 v[2:5], v[204:207], v[236:239], v[2:5]
	v_mfma_f32_16x16x32_bf16 v[30:33], v[200:203], v[216:219], v[30:33]
	v_mfma_f32_16x16x32_bf16 v[26:29], v[208:211], v[216:219], v[26:29]
	v_mfma_f32_16x16x32_bf16 v[22:25], v[200:203], v[224:227], v[22:25]
	v_mfma_f32_16x16x32_bf16 v[18:21], v[208:211], v[224:227], v[18:21]
	v_mfma_f32_16x16x32_bf16 v[14:17], v[200:203], v[232:235], v[14:17]
	v_mfma_f32_16x16x32_bf16 v[10:13], v[208:211], v[232:235], v[10:13]
	v_mfma_f32_16x16x32_bf16 v[6:9], v[200:203], v[240:243], v[6:9]
	v_mfma_f32_16x16x32_bf16 v[2:5], v[208:211], v[240:243], v[2:5]
	s_setprio 0
	s_barrier
	s_add_i32 s46, s46, 2
	s_add_u32 s20, s20, 0x100
	s_addc_u32 s21, s21, 0
	s_add_u32 s44, s44, 0x100
	s_addc_u32 s45, s45, 0
	s_cmp_gt_u32 s46, 5
	s_cbranch_scc0 .LBB0_1029
	s_and_b64 vcc, exec, s[10:11]
	s_cbranch_vccnz .LBB0_1034
	s_mov_b64 s[20:21], -1
	s_and_b64 vcc, exec, s[18:19]
	s_cbranch_vccnz .LBB0_1035

.LBB0_1134:
	s_ashr_i32 s29, s28, 31
	s_lshl_b64 s[30:31], s[28:29], 19
	s_add_u32 s30, s3, s30
	s_addc_u32 s31, s14, s31
	s_and_b64 s[34:35], s[0:1], exec
	s_cselect_b32 s29, s31, s39
	s_cselect_b32 s57, s30, s38
	s_ashr_i32 s27, s26, 31
	s_lshl_b64 s[34:35], s[26:27], 19
	s_add_u32 s34, s15, s34
	s_addc_u32 s35, s16, s35
	s_and_b64 s[42:43], s[0:1], exec
	s_cselect_b32 s27, s35, s41
	s_cselect_b32 s58, s34, s40
	s_add_u32 s59, s40, 0x100
	s_addc_u32 s60, s41, 0
	s_mov_b32 s61, -2
	ds_read_b128 v[146:149], v156
	ds_read_b128 v[150:153], v156 offset:1024
	ds_read_b128 v[160:163], v156 offset:2048
	ds_read_b128 v[164:167], v156 offset:3072
	ds_read_b128 v[168:171], v157
	ds_read_b128 v[178:181], v157 offset:1024
	ds_read_b128 v[182:185], v157 offset:2048
	ds_read_b128 v[186:189], v157 offset:3072
	s_add_u32 s40, s38, 0x100
	s_addc_u32 s41, s39, 0
	s_cmp_eq_u32 s61, 12
	s_cselect_b32 s45, s29, s41
	s_cselect_b32 s44, s57, s40
	s_cselect_b32 s43, s27, s60
	s_cselect_b32 s42, s58, s59
	v_lshl_add_u64 v[172:173], s[38:39], 0, v[138:139]
	s_add_i32 m0, s37, 0xc000
	ds_read_b128 v[190:193], v158
	ds_read_b128 v[194:197], v158 offset:1024
	ds_read_b128 v[198:201], v158 offset:2048
	ds_read_b128 v[202:205], v158 offset:3072
	ds_read_b128 v[206:209], v158 offset:4096
	ds_read_b128 v[210:213], v158 offset:5120
	ds_read_b128 v[214:217], v158 offset:6144
	ds_read_b128 v[218:221], v158 offset:7168
	global_load_lds_dwordx4 v[172:173], off
	v_lshl_add_u64 v[172:173], s[38:39], 0, v[140:141]
	s_add_i32 m0, s37, 0xe000
	s_nop 0
	global_load_lds_dwordx4 v[172:173], off
	s_waitcnt vmcnt(8)
	s_waitcnt lgkmcnt(0)
	s_barrier
	s_setprio 1
	s_waitcnt lgkmcnt(0)
	v_mfma_f32_16x16x32_bf16 v[126:129], v[146:149], v[190:193], 0
	v_mfma_f32_16x16x32_bf16 v[122:125], v[160:163], v[190:193], 0
	v_mfma_f32_16x16x32_bf16 v[110:113], v[146:149], v[198:201], 0
	v_mfma_f32_16x16x32_bf16 v[106:109], v[160:163], v[198:201], 0
	v_mfma_f32_16x16x32_bf16 v[94:97], v[146:149], v[206:209], 0
	v_mfma_f32_16x16x32_bf16 v[90:93], v[160:163], v[206:209], 0
	v_mfma_f32_16x16x32_bf16 v[78:81], v[146:149], v[214:217], 0
	v_mfma_f32_16x16x32_bf16 v[74:77], v[160:163], v[214:217], 0
	v_mfma_f32_16x16x32_bf16 v[126:129], v[150:153], v[194:197], v[126:129]
	v_mfma_f32_16x16x32_bf16 v[122:125], v[164:167], v[194:197], v[122:125]
	v_mfma_f32_16x16x32_bf16 v[110:113], v[150:153], v[202:205], v[110:113]
	v_mfma_f32_16x16x32_bf16 v[106:109], v[164:167], v[202:205], v[106:109]
	v_mfma_f32_16x16x32_bf16 v[94:97], v[150:153], v[210:213], v[94:97]
	v_mfma_f32_16x16x32_bf16 v[90:93], v[164:167], v[210:213], v[90:93]
	v_mfma_f32_16x16x32_bf16 v[78:81], v[150:153], v[218:221], v[78:81]
	v_mfma_f32_16x16x32_bf16 v[74:77], v[164:167], v[218:221], v[74:77]
	v_mfma_f32_16x16x32_bf16 v[118:121], v[168:171], v[190:193], 0
	v_mfma_f32_16x16x32_bf16 v[114:117], v[182:185], v[190:193], 0
	v_mfma_f32_16x16x32_bf16 v[102:105], v[168:171], v[198:201], 0
	v_mfma_f32_16x16x32_bf16 v[98:101], v[182:185], v[198:201], 0
	v_mfma_f32_16x16x32_bf16 v[86:89], v[168:171], v[206:209], 0
	v_mfma_f32_16x16x32_bf16 v[82:85], v[182:185], v[206:209], 0
	v_mfma_f32_16x16x32_bf16 v[70:73], v[168:171], v[214:217], 0
	v_mfma_f32_16x16x32_bf16 v[66:69], v[182:185], v[214:217], 0
	v_mfma_f32_16x16x32_bf16 v[118:121], v[178:181], v[194:197], v[118:121]
	v_mfma_f32_16x16x32_bf16 v[114:117], v[186:189], v[194:197], v[114:117]
	v_mfma_f32_16x16x32_bf16 v[102:105], v[178:181], v[202:205], v[102:105]
	v_mfma_f32_16x16x32_bf16 v[98:101], v[186:189], v[202:205], v[98:101]
	v_mfma_f32_16x16x32_bf16 v[86:89], v[178:181], v[210:213], v[86:89]
	v_mfma_f32_16x16x32_bf16 v[82:85], v[186:189], v[210:213], v[82:85]
	v_mfma_f32_16x16x32_bf16 v[70:73], v[178:181], v[218:221], v[70:73]
	v_mfma_f32_16x16x32_bf16 v[66:69], v[186:189], v[218:221], v[66:69]
	s_setprio 0
	s_barrier
	s_add_i32 s38, s54, s46
	v_lshl_add_u64 v[172:173], s[42:43], 0, v[132:133]
	s_mov_b32 m0, s38
	ds_read_b128 v[190:193], v158 offset:16384
	ds_read_b128 v[194:197], v158 offset:17408
	ds_read_b128 v[198:201], v158 offset:18432
	ds_read_b128 v[202:205], v158 offset:19456
	ds_read_b128 v[206:209], v158 offset:20480
	ds_read_b128 v[210:213], v158 offset:21504
	ds_read_b128 v[214:217], v158 offset:22528
	ds_read_b128 v[218:221], v158 offset:23552
	global_load_lds_dwordx4 v[172:173], off
	s_add_i32 m0, s38, 0x2000
	s_add_u32 s38, s42, 0x40000
	v_lshl_add_u64 v[222:223], s[42:43], 0, v[136:137]
	s_addc_u32 s39, s43, 0
	s_add_i32 s62, s55, s46
	global_load_lds_dwordx4 v[222:223], off
	v_lshl_add_u64 v[224:225], s[38:39], 0, v[132:133]
	s_mov_b32 m0, s62
	v_lshl_add_u64 v[226:227], s[44:45], 0, v[134:135]
	global_load_lds_dwordx4 v[224:225], off
	v_lshl_add_u64 v[224:225], s[38:39], 0, v[136:137]
	s_add_i32 m0, s62, 0x2000
	s_nop 0
	global_load_lds_dwordx4 v[224:225], off
	v_lshl_add_u64 v[224:225], s[44:45], 0, v[130:131]
	s_mov_b32 m0, s37
	s_nop 0
	global_load_lds_dwordx4 v[224:225], off
	s_mov_b32 m0, s47
	s_nop 0
	global_load_lds_dwordx4 v[226:227], off
	s_waitcnt vmcnt(8)
	s_waitcnt lgkmcnt(0)
	s_barrier
	s_setprio 1
	s_waitcnt lgkmcnt(0)
	v_mfma_f32_16x16x32_bf16 v[62:65], v[146:149], v[190:193], 0
	v_mfma_f32_16x16x32_bf16 v[58:61], v[160:163], v[190:193], 0
	v_mfma_f32_16x16x32_bf16 v[46:49], v[146:149], v[198:201], 0
	v_mfma_f32_16x16x32_bf16 v[42:45], v[160:163], v[198:201], 0
	v_mfma_f32_16x16x32_bf16 v[30:33], v[146:149], v[206:209], 0
	v_mfma_f32_16x16x32_bf16 v[26:29], v[160:163], v[206:209], 0
	v_mfma_f32_16x16x32_bf16 v[14:17], v[146:149], v[214:217], 0
	v_mfma_f32_16x16x32_bf16 v[10:13], v[160:163], v[214:217], 0
	v_mfma_f32_16x16x32_bf16 v[62:65], v[150:153], v[194:197], v[62:65]
	v_mfma_f32_16x16x32_bf16 v[58:61], v[164:167], v[194:197], v[58:61]
	v_mfma_f32_16x16x32_bf16 v[46:49], v[150:153], v[202:205], v[46:49]
	v_mfma_f32_16x16x32_bf16 v[42:45], v[164:167], v[202:205], v[42:45]
	v_mfma_f32_16x16x32_bf16 v[30:33], v[150:153], v[210:213], v[30:33]
	v_mfma_f32_16x16x32_bf16 v[26:29], v[164:167], v[210:213], v[26:29]
	v_mfma_f32_16x16x32_bf16 v[14:17], v[150:153], v[218:221], v[14:17]
	v_mfma_f32_16x16x32_bf16 v[10:13], v[164:167], v[218:221], v[10:13]
	v_mfma_f32_16x16x32_bf16 v[54:57], v[168:171], v[190:193], 0
	v_mfma_f32_16x16x32_bf16 v[50:53], v[182:185], v[190:193], 0
	v_mfma_f32_16x16x32_bf16 v[38:41], v[168:171], v[198:201], 0
	v_mfma_f32_16x16x32_bf16 v[34:37], v[182:185], v[198:201], 0
	v_mfma_f32_16x16x32_bf16 v[22:25], v[168:171], v[206:209], 0
	v_mfma_f32_16x16x32_bf16 v[18:21], v[182:185], v[206:209], 0
	v_mfma_f32_16x16x32_bf16 v[6:9], v[168:171], v[214:217], 0
	v_mfma_f32_16x16x32_bf16 v[2:5], v[182:185], v[214:217], 0
	v_mfma_f32_16x16x32_bf16 v[54:57], v[178:181], v[194:197], v[54:57]
	v_mfma_f32_16x16x32_bf16 v[50:53], v[186:189], v[194:197], v[50:53]
	v_mfma_f32_16x16x32_bf16 v[38:41], v[178:181], v[202:205], v[38:41]
	v_mfma_f32_16x16x32_bf16 v[34:37], v[186:189], v[202:205], v[34:37]
	v_mfma_f32_16x16x32_bf16 v[22:25], v[178:181], v[210:213], v[22:25]
	v_mfma_f32_16x16x32_bf16 v[18:21], v[186:189], v[210:213], v[18:21]
	v_mfma_f32_16x16x32_bf16 v[6:9], v[178:181], v[218:221], v[6:9]
	v_mfma_f32_16x16x32_bf16 v[2:5], v[186:189], v[218:221], v[2:5]
	s_setprio 0
	s_barrier
	s_add_i32 s62, 0, 0x18000
	v_add_u32_e32 v159, s62, v154
	s_add_i32 s63, 0, 0x1c000
	ds_read_b128 v[146:149], v159
	ds_read_b128 v[150:153], v159 offset:1024
	ds_read_b128 v[160:163], v159 offset:2048
	ds_read_b128 v[164:167], v159 offset:3072
	v_add_u32_e32 v159, s63, v154
	ds_read_b128 v[168:171], v159
	ds_read_b128 v[178:181], v159 offset:1024
	ds_read_b128 v[182:185], v159 offset:2048
	ds_read_b128 v[186:189], v159 offset:3072
	s_add_u32 s38, s44, 0x40000
	s_addc_u32 s39, s45, 0
	s_mov_b32 m0, s48
	v_lshl_add_u64 v[228:229], s[38:39], 0, v[130:131]
	ds_read_b128 v[190:193], v158 offset:32768
	ds_read_b128 v[194:197], v158 offset:33792
	ds_read_b128 v[198:201], v158 offset:34816
	ds_read_b128 v[202:205], v158 offset:35840
	ds_read_b128 v[206:209], v158 offset:36864
	ds_read_b128 v[210:213], v158 offset:37888
	ds_read_b128 v[214:217], v158 offset:38912
	ds_read_b128 v[218:221], v158 offset:39936
	global_load_lds_dwordx4 v[228:229], off
	v_lshl_add_u64 v[228:229], s[38:39], 0, v[134:135]
	s_mov_b32 m0, s49
	s_nop 0
	global_load_lds_dwordx4 v[228:229], off
	s_waitcnt vmcnt(8)
	s_waitcnt lgkmcnt(0)
	s_barrier
	s_setprio 1
	s_waitcnt lgkmcnt(0)
	v_mfma_f32_16x16x32_bf16 v[126:129], v[146:149], v[190:193], v[126:129]
	v_mfma_f32_16x16x32_bf16 v[122:125], v[160:163], v[190:193], v[122:125]
	v_mfma_f32_16x16x32_bf16 v[110:113], v[146:149], v[198:201], v[110:113]
	v_mfma_f32_16x16x32_bf16 v[106:109], v[160:163], v[198:201], v[106:109]
	v_mfma_f32_16x16x32_bf16 v[94:97], v[146:149], v[206:209], v[94:97]
	v_mfma_f32_16x16x32_bf16 v[90:93], v[160:163], v[206:209], v[90:93]
	v_mfma_f32_16x16x32_bf16 v[78:81], v[146:149], v[214:217], v[78:81]
	v_mfma_f32_16x16x32_bf16 v[74:77], v[160:163], v[214:217], v[74:77]
	v_mfma_f32_16x16x32_bf16 v[126:129], v[150:153], v[194:197], v[126:129]
	v_mfma_f32_16x16x32_bf16 v[122:125], v[164:167], v[194:197], v[122:125]
	v_mfma_f32_16x16x32_bf16 v[110:113], v[150:153], v[202:205], v[110:113]
	v_mfma_f32_16x16x32_bf16 v[106:109], v[164:167], v[202:205], v[106:109]
	v_mfma_f32_16x16x32_bf16 v[94:97], v[150:153], v[210:213], v[94:97]
	v_mfma_f32_16x16x32_bf16 v[90:93], v[164:167], v[210:213], v[90:93]
	v_mfma_f32_16x16x32_bf16 v[78:81], v[150:153], v[218:221], v[78:81]
	v_mfma_f32_16x16x32_bf16 v[74:77], v[164:167], v[218:221], v[74:77]
	v_mfma_f32_16x16x32_bf16 v[118:121], v[168:171], v[190:193], v[118:121]
	v_mfma_f32_16x16x32_bf16 v[114:117], v[182:185], v[190:193], v[114:117]
	v_mfma_f32_16x16x32_bf16 v[102:105], v[168:171], v[198:201], v[102:105]
	v_mfma_f32_16x16x32_bf16 v[98:101], v[182:185], v[198:201], v[98:101]
	v_mfma_f32_16x16x32_bf16 v[86:89], v[168:171], v[206:209], v[86:89]
	v_mfma_f32_16x16x32_bf16 v[82:85], v[182:185], v[206:209], v[82:85]
	v_mfma_f32_16x16x32_bf16 v[70:73], v[168:171], v[214:217], v[70:73]
	v_mfma_f32_16x16x32_bf16 v[66:69], v[182:185], v[214:217], v[66:69]
	v_mfma_f32_16x16x32_bf16 v[118:121], v[178:181], v[194:197], v[118:121]
	v_mfma_f32_16x16x32_bf16 v[114:117], v[186:189], v[194:197], v[114:117]
	v_mfma_f32_16x16x32_bf16 v[102:105], v[178:181], v[202:205], v[102:105]
	v_mfma_f32_16x16x32_bf16 v[98:101], v[186:189], v[202:205], v[98:101]
	v_mfma_f32_16x16x32_bf16 v[86:89], v[178:181], v[210:213], v[86:89]
	v_mfma_f32_16x16x32_bf16 v[82:85], v[186:189], v[210:213], v[82:85]
	v_mfma_f32_16x16x32_bf16 v[70:73], v[178:181], v[218:221], v[70:73]
	v_mfma_f32_16x16x32_bf16 v[66:69], v[186:189], v[218:221], v[66:69]
	s_setprio 0
	s_barrier
	s_add_i32 s38, s62, s46
	v_lshl_add_u64 v[172:173], v[172:173], 0, s[12:13]
	s_mov_b32 m0, s38
	ds_read_b128 v[190:193], v158 offset:49152
	ds_read_b128 v[194:197], v158 offset:50176
	ds_read_b128 v[198:201], v158 offset:51200
	ds_read_b128 v[202:205], v158 offset:52224
	ds_read_b128 v[206:209], v158 offset:53248
	ds_read_b128 v[210:213], v158 offset:54272
	ds_read_b128 v[214:217], v158 offset:55296
	ds_read_b128 v[218:221], v158 offset:56320
	global_load_lds_dwordx4 v[172:173], off
	s_add_i32 m0, s38, 0x2000
	s_add_u32 s38, s42, 0x40080
	v_lshl_add_u64 v[172:173], v[222:223], 0, s[12:13]
	s_addc_u32 s39, s43, 0
	s_add_i32 s42, s63, s46
	global_load_lds_dwordx4 v[172:173], off
	v_lshl_add_u64 v[172:173], s[38:39], 0, v[132:133]
	s_mov_b32 m0, s42
	s_nop 0
	global_load_lds_dwordx4 v[172:173], off
	v_lshl_add_u64 v[172:173], s[38:39], 0, v[136:137]
	s_add_i32 m0, s42, 0x2000
	s_nop 0
	global_load_lds_dwordx4 v[172:173], off
	v_lshl_add_u64 v[172:173], v[224:225], 0, s[12:13]
	s_mov_b32 m0, s51
	s_nop 0
	global_load_lds_dwordx4 v[172:173], off
	v_lshl_add_u64 v[172:173], v[226:227], 0, s[12:13]
	s_mov_b32 m0, s52
	s_nop 0
	global_load_lds_dwordx4 v[172:173], off
	s_waitcnt vmcnt(8)
	s_waitcnt lgkmcnt(0)
	s_barrier
	s_setprio 1
	s_waitcnt lgkmcnt(0)
	v_mfma_f32_16x16x32_bf16 v[62:65], v[146:149], v[190:193], v[62:65]
	v_mfma_f32_16x16x32_bf16 v[58:61], v[160:163], v[190:193], v[58:61]
	v_mfma_f32_16x16x32_bf16 v[46:49], v[146:149], v[198:201], v[46:49]
	v_mfma_f32_16x16x32_bf16 v[42:45], v[160:163], v[198:201], v[42:45]
	v_mfma_f32_16x16x32_bf16 v[30:33], v[146:149], v[206:209], v[30:33]
	v_mfma_f32_16x16x32_bf16 v[26:29], v[160:163], v[206:209], v[26:29]
	v_mfma_f32_16x16x32_bf16 v[14:17], v[146:149], v[214:217], v[14:17]
	v_mfma_f32_16x16x32_bf16 v[10:13], v[160:163], v[214:217], v[10:13]
	v_mfma_f32_16x16x32_bf16 v[62:65], v[150:153], v[194:197], v[62:65]
	v_mfma_f32_16x16x32_bf16 v[58:61], v[164:167], v[194:197], v[58:61]
	v_mfma_f32_16x16x32_bf16 v[46:49], v[150:153], v[202:205], v[46:49]
	v_mfma_f32_16x16x32_bf16 v[42:45], v[164:167], v[202:205], v[42:45]
	v_mfma_f32_16x16x32_bf16 v[30:33], v[150:153], v[210:213], v[30:33]
	v_mfma_f32_16x16x32_bf16 v[26:29], v[164:167], v[210:213], v[26:29]
	v_mfma_f32_16x16x32_bf16 v[14:17], v[150:153], v[218:221], v[14:17]
	v_mfma_f32_16x16x32_bf16 v[10:13], v[164:167], v[218:221], v[10:13]
	v_mfma_f32_16x16x32_bf16 v[54:57], v[168:171], v[190:193], v[54:57]
	v_mfma_f32_16x16x32_bf16 v[50:53], v[182:185], v[190:193], v[50:53]
	v_mfma_f32_16x16x32_bf16 v[38:41], v[168:171], v[198:201], v[38:41]
	v_mfma_f32_16x16x32_bf16 v[34:37], v[182:185], v[198:201], v[34:37]
	v_mfma_f32_16x16x32_bf16 v[22:25], v[168:171], v[206:209], v[22:25]
	v_mfma_f32_16x16x32_bf16 v[18:21], v[182:185], v[206:209], v[18:21]
	v_mfma_f32_16x16x32_bf16 v[6:9], v[168:171], v[214:217], v[6:9]
	v_mfma_f32_16x16x32_bf16 v[2:5], v[182:185], v[214:217], v[2:5]
	v_mfma_f32_16x16x32_bf16 v[54:57], v[178:181], v[194:197], v[54:57]
	v_mfma_f32_16x16x32_bf16 v[50:53], v[186:189], v[194:197], v[50:53]
	v_mfma_f32_16x16x32_bf16 v[38:41], v[178:181], v[202:205], v[38:41]
	v_mfma_f32_16x16x32_bf16 v[34:37], v[186:189], v[202:205], v[34:37]
	v_mfma_f32_16x16x32_bf16 v[22:25], v[178:181], v[210:213], v[22:25]
	v_mfma_f32_16x16x32_bf16 v[18:21], v[186:189], v[210:213], v[18:21]
	v_mfma_f32_16x16x32_bf16 v[6:9], v[178:181], v[218:221], v[6:9]
	v_mfma_f32_16x16x32_bf16 v[2:5], v[186:189], v[218:221], v[2:5]
	s_setprio 0
	s_barrier
	s_add_i32 s61, s61, 2
	s_add_u32 s59, s59, 0x100
	s_addc_u32 s60, s60, 0
	s_cmp_gt_u32 s61, 13
	s_mov_b64 s[38:39], s[40:41]
	s_cbranch_scc0 .LBB0_1135
	s_branch .Lpeel_exit_1135
.LBB0_1135:
	ds_read_b128 v[146:149], v156
	ds_read_b128 v[150:153], v156 offset:1024
	ds_read_b128 v[160:163], v156 offset:2048
	ds_read_b128 v[164:167], v156 offset:3072
	ds_read_b128 v[168:171], v157
	ds_read_b128 v[178:181], v157 offset:1024
	ds_read_b128 v[182:185], v157 offset:2048
	ds_read_b128 v[186:189], v157 offset:3072
	s_add_u32 s40, s38, 0x100
	s_addc_u32 s41, s39, 0
	s_cmp_eq_u32 s61, 12
	s_cselect_b32 s45, s29, s41
	s_cselect_b32 s44, s57, s40
	s_cselect_b32 s43, s27, s60
	s_cselect_b32 s42, s58, s59
	v_lshl_add_u64 v[172:173], s[38:39], 0, v[138:139]
	s_add_i32 m0, s37, 0xc000
	ds_read_b128 v[190:193], v158
	ds_read_b128 v[194:197], v158 offset:1024
	ds_read_b128 v[198:201], v158 offset:2048
	ds_read_b128 v[202:205], v158 offset:3072
	ds_read_b128 v[206:209], v158 offset:4096
	ds_read_b128 v[210:213], v158 offset:5120
	ds_read_b128 v[214:217], v158 offset:6144
	ds_read_b128 v[218:221], v158 offset:7168
	global_load_lds_dwordx4 v[172:173], off
	v_lshl_add_u64 v[172:173], s[38:39], 0, v[140:141]
	s_add_i32 m0, s37, 0xe000
	s_nop 0
	global_load_lds_dwordx4 v[172:173], off
	s_waitcnt vmcnt(8)
	s_waitcnt lgkmcnt(0)
	s_barrier
	s_setprio 1
	s_waitcnt lgkmcnt(0)
	v_mfma_f32_16x16x32_bf16 v[126:129], v[146:149], v[190:193], v[126:129]
	v_mfma_f32_16x16x32_bf16 v[122:125], v[160:163], v[190:193], v[122:125]
	v_mfma_f32_16x16x32_bf16 v[110:113], v[146:149], v[198:201], v[110:113]
	v_mfma_f32_16x16x32_bf16 v[106:109], v[160:163], v[198:201], v[106:109]
	v_mfma_f32_16x16x32_bf16 v[94:97], v[146:149], v[206:209], v[94:97]
	v_mfma_f32_16x16x32_bf16 v[90:93], v[160:163], v[206:209], v[90:93]
	v_mfma_f32_16x16x32_bf16 v[78:81], v[146:149], v[214:217], v[78:81]
	v_mfma_f32_16x16x32_bf16 v[74:77], v[160:163], v[214:217], v[74:77]
	v_mfma_f32_16x16x32_bf16 v[126:129], v[150:153], v[194:197], v[126:129]
	v_mfma_f32_16x16x32_bf16 v[122:125], v[164:167], v[194:197], v[122:125]
	v_mfma_f32_16x16x32_bf16 v[110:113], v[150:153], v[202:205], v[110:113]
	v_mfma_f32_16x16x32_bf16 v[106:109], v[164:167], v[202:205], v[106:109]
	v_mfma_f32_16x16x32_bf16 v[94:97], v[150:153], v[210:213], v[94:97]
	v_mfma_f32_16x16x32_bf16 v[90:93], v[164:167], v[210:213], v[90:93]
	v_mfma_f32_16x16x32_bf16 v[78:81], v[150:153], v[218:221], v[78:81]
	v_mfma_f32_16x16x32_bf16 v[74:77], v[164:167], v[218:221], v[74:77]
	v_mfma_f32_16x16x32_bf16 v[118:121], v[168:171], v[190:193], v[118:121]
	v_mfma_f32_16x16x32_bf16 v[114:117], v[182:185], v[190:193], v[114:117]
	v_mfma_f32_16x16x32_bf16 v[102:105], v[168:171], v[198:201], v[102:105]
	v_mfma_f32_16x16x32_bf16 v[98:101], v[182:185], v[198:201], v[98:101]
	v_mfma_f32_16x16x32_bf16 v[86:89], v[168:171], v[206:209], v[86:89]
	v_mfma_f32_16x16x32_bf16 v[82:85], v[182:185], v[206:209], v[82:85]
	v_mfma_f32_16x16x32_bf16 v[70:73], v[168:171], v[214:217], v[70:73]
	v_mfma_f32_16x16x32_bf16 v[66:69], v[182:185], v[214:217], v[66:69]
	v_mfma_f32_16x16x32_bf16 v[118:121], v[178:181], v[194:197], v[118:121]
	v_mfma_f32_16x16x32_bf16 v[114:117], v[186:189], v[194:197], v[114:117]
	v_mfma_f32_16x16x32_bf16 v[102:105], v[178:181], v[202:205], v[102:105]
	v_mfma_f32_16x16x32_bf16 v[98:101], v[186:189], v[202:205], v[98:101]
	v_mfma_f32_16x16x32_bf16 v[86:89], v[178:181], v[210:213], v[86:89]
	v_mfma_f32_16x16x32_bf16 v[82:85], v[186:189], v[210:213], v[82:85]
	v_mfma_f32_16x16x32_bf16 v[70:73], v[178:181], v[218:221], v[70:73]
	v_mfma_f32_16x16x32_bf16 v[66:69], v[186:189], v[218:221], v[66:69]
	s_setprio 0
	s_barrier
	s_add_i32 s38, s54, s46
	v_lshl_add_u64 v[172:173], s[42:43], 0, v[132:133]
	s_mov_b32 m0, s38
	ds_read_b128 v[190:193], v158 offset:16384
	ds_read_b128 v[194:197], v158 offset:17408
	ds_read_b128 v[198:201], v158 offset:18432
	ds_read_b128 v[202:205], v158 offset:19456
	ds_read_b128 v[206:209], v158 offset:20480
	ds_read_b128 v[210:213], v158 offset:21504
	ds_read_b128 v[214:217], v158 offset:22528
	ds_read_b128 v[218:221], v158 offset:23552
	global_load_lds_dwordx4 v[172:173], off
	s_add_i32 m0, s38, 0x2000
	s_add_u32 s38, s42, 0x40000
	v_lshl_add_u64 v[222:223], s[42:43], 0, v[136:137]
	s_addc_u32 s39, s43, 0
	s_add_i32 s62, s55, s46
	global_load_lds_dwordx4 v[222:223], off
	v_lshl_add_u64 v[224:225], s[38:39], 0, v[132:133]
	s_mov_b32 m0, s62
	v_lshl_add_u64 v[226:227], s[44:45], 0, v[134:135]
	global_load_lds_dwordx4 v[224:225], off
	v_lshl_add_u64 v[224:225], s[38:39], 0, v[136:137]
	s_add_i32 m0, s62, 0x2000
	s_nop 0
	global_load_lds_dwordx4 v[224:225], off
	v_lshl_add_u64 v[224:225], s[44:45], 0, v[130:131]
	s_mov_b32 m0, s37
	s_nop 0
	global_load_lds_dwordx4 v[224:225], off
	s_mov_b32 m0, s47
	s_nop 0
	global_load_lds_dwordx4 v[226:227], off
	s_waitcnt vmcnt(8)
	s_waitcnt lgkmcnt(0)
	s_barrier
	s_setprio 1
	s_waitcnt lgkmcnt(0)
	v_mfma_f32_16x16x32_bf16 v[62:65], v[146:149], v[190:193], v[62:65]
	v_mfma_f32_16x16x32_bf16 v[58:61], v[160:163], v[190:193], v[58:61]
	v_mfma_f32_16x16x32_bf16 v[46:49], v[146:149], v[198:201], v[46:49]
	v_mfma_f32_16x16x32_bf16 v[42:45], v[160:163], v[198:201], v[42:45]
	v_mfma_f32_16x16x32_bf16 v[30:33], v[146:149], v[206:209], v[30:33]
	v_mfma_f32_16x16x32_bf16 v[26:29], v[160:163], v[206:209], v[26:29]
	v_mfma_f32_16x16x32_bf16 v[14:17], v[146:149], v[214:217], v[14:17]
	v_mfma_f32_16x16x32_bf16 v[10:13], v[160:163], v[214:217], v[10:13]
	v_mfma_f32_16x16x32_bf16 v[62:65], v[150:153], v[194:197], v[62:65]
	v_mfma_f32_16x16x32_bf16 v[58:61], v[164:167], v[194:197], v[58:61]
	v_mfma_f32_16x16x32_bf16 v[46:49], v[150:153], v[202:205], v[46:49]
	v_mfma_f32_16x16x32_bf16 v[42:45], v[164:167], v[202:205], v[42:45]
	v_mfma_f32_16x16x32_bf16 v[30:33], v[150:153], v[210:213], v[30:33]
	v_mfma_f32_16x16x32_bf16 v[26:29], v[164:167], v[210:213], v[26:29]
	v_mfma_f32_16x16x32_bf16 v[14:17], v[150:153], v[218:221], v[14:17]
	v_mfma_f32_16x16x32_bf16 v[10:13], v[164:167], v[218:221], v[10:13]
	v_mfma_f32_16x16x32_bf16 v[54:57], v[168:171], v[190:193], v[54:57]
	v_mfma_f32_16x16x32_bf16 v[50:53], v[182:185], v[190:193], v[50:53]
	v_mfma_f32_16x16x32_bf16 v[38:41], v[168:171], v[198:201], v[38:41]
	v_mfma_f32_16x16x32_bf16 v[34:37], v[182:185], v[198:201], v[34:37]
	v_mfma_f32_16x16x32_bf16 v[22:25], v[168:171], v[206:209], v[22:25]
	v_mfma_f32_16x16x32_bf16 v[18:21], v[182:185], v[206:209], v[18:21]
	v_mfma_f32_16x16x32_bf16 v[6:9], v[168:171], v[214:217], v[6:9]
	v_mfma_f32_16x16x32_bf16 v[2:5], v[182:185], v[214:217], v[2:5]
	v_mfma_f32_16x16x32_bf16 v[54:57], v[178:181], v[194:197], v[54:57]
	v_mfma_f32_16x16x32_bf16 v[50:53], v[186:189], v[194:197], v[50:53]
	v_mfma_f32_16x16x32_bf16 v[38:41], v[178:181], v[202:205], v[38:41]
	v_mfma_f32_16x16x32_bf16 v[34:37], v[186:189], v[202:205], v[34:37]
	v_mfma_f32_16x16x32_bf16 v[22:25], v[178:181], v[210:213], v[22:25]
	v_mfma_f32_16x16x32_bf16 v[18:21], v[186:189], v[210:213], v[18:21]
	v_mfma_f32_16x16x32_bf16 v[6:9], v[178:181], v[218:221], v[6:9]
	v_mfma_f32_16x16x32_bf16 v[2:5], v[186:189], v[218:221], v[2:5]
	s_setprio 0
	s_barrier
	s_add_i32 s62, 0, 0x18000
	v_add_u32_e32 v159, s62, v154
	s_add_i32 s63, 0, 0x1c000
	ds_read_b128 v[146:149], v159
	ds_read_b128 v[150:153], v159 offset:1024
	ds_read_b128 v[160:163], v159 offset:2048
	ds_read_b128 v[164:167], v159 offset:3072
	v_add_u32_e32 v159, s63, v154
	ds_read_b128 v[168:171], v159
	ds_read_b128 v[178:181], v159 offset:1024
	ds_read_b128 v[182:185], v159 offset:2048
	ds_read_b128 v[186:189], v159 offset:3072
	s_add_u32 s38, s44, 0x40000
	s_addc_u32 s39, s45, 0
	s_mov_b32 m0, s48
	v_lshl_add_u64 v[228:229], s[38:39], 0, v[130:131]
	ds_read_b128 v[190:193], v158 offset:32768
	ds_read_b128 v[194:197], v158 offset:33792
	ds_read_b128 v[198:201], v158 offset:34816
	ds_read_b128 v[202:205], v158 offset:35840
	ds_read_b128 v[206:209], v158 offset:36864
	ds_read_b128 v[210:213], v158 offset:37888
	ds_read_b128 v[214:217], v158 offset:38912
	ds_read_b128 v[218:221], v158 offset:39936
	global_load_lds_dwordx4 v[228:229], off
	v_lshl_add_u64 v[228:229], s[38:39], 0, v[134:135]
	s_mov_b32 m0, s49
	s_nop 0
	global_load_lds_dwordx4 v[228:229], off
	s_waitcnt vmcnt(8)
	s_waitcnt lgkmcnt(0)
	s_barrier
	s_setprio 1
	s_waitcnt lgkmcnt(0)
	v_mfma_f32_16x16x32_bf16 v[126:129], v[146:149], v[190:193], v[126:129]
	v_mfma_f32_16x16x32_bf16 v[122:125], v[160:163], v[190:193], v[122:125]
	v_mfma_f32_16x16x32_bf16 v[110:113], v[146:149], v[198:201], v[110:113]
	v_mfma_f32_16x16x32_bf16 v[106:109], v[160:163], v[198:201], v[106:109]
	v_mfma_f32_16x16x32_bf16 v[94:97], v[146:149], v[206:209], v[94:97]
	v_mfma_f32_16x16x32_bf16 v[90:93], v[160:163], v[206:209], v[90:93]
	v_mfma_f32_16x16x32_bf16 v[78:81], v[146:149], v[214:217], v[78:81]
	v_mfma_f32_16x16x32_bf16 v[74:77], v[160:163], v[214:217], v[74:77]
	v_mfma_f32_16x16x32_bf16 v[126:129], v[150:153], v[194:197], v[126:129]
	v_mfma_f32_16x16x32_bf16 v[122:125], v[164:167], v[194:197], v[122:125]
	v_mfma_f32_16x16x32_bf16 v[110:113], v[150:153], v[202:205], v[110:113]
	v_mfma_f32_16x16x32_bf16 v[106:109], v[164:167], v[202:205], v[106:109]
	v_mfma_f32_16x16x32_bf16 v[94:97], v[150:153], v[210:213], v[94:97]
	v_mfma_f32_16x16x32_bf16 v[90:93], v[164:167], v[210:213], v[90:93]
	v_mfma_f32_16x16x32_bf16 v[78:81], v[150:153], v[218:221], v[78:81]
	v_mfma_f32_16x16x32_bf16 v[74:77], v[164:167], v[218:221], v[74:77]
	v_mfma_f32_16x16x32_bf16 v[118:121], v[168:171], v[190:193], v[118:121]
	v_mfma_f32_16x16x32_bf16 v[114:117], v[182:185], v[190:193], v[114:117]
	v_mfma_f32_16x16x32_bf16 v[102:105], v[168:171], v[198:201], v[102:105]
	v_mfma_f32_16x16x32_bf16 v[98:101], v[182:185], v[198:201], v[98:101]
	v_mfma_f32_16x16x32_bf16 v[86:89], v[168:171], v[206:209], v[86:89]
	v_mfma_f32_16x16x32_bf16 v[82:85], v[182:185], v[206:209], v[82:85]
	v_mfma_f32_16x16x32_bf16 v[70:73], v[168:171], v[214:217], v[70:73]
	v_mfma_f32_16x16x32_bf16 v[66:69], v[182:185], v[214:217], v[66:69]
	v_mfma_f32_16x16x32_bf16 v[118:121], v[178:181], v[194:197], v[118:121]
	v_mfma_f32_16x16x32_bf16 v[114:117], v[186:189], v[194:197], v[114:117]
	v_mfma_f32_16x16x32_bf16 v[102:105], v[178:181], v[202:205], v[102:105]
	v_mfma_f32_16x16x32_bf16 v[98:101], v[186:189], v[202:205], v[98:101]
	v_mfma_f32_16x16x32_bf16 v[86:89], v[178:181], v[210:213], v[86:89]
	v_mfma_f32_16x16x32_bf16 v[82:85], v[186:189], v[210:213], v[82:85]
	v_mfma_f32_16x16x32_bf16 v[70:73], v[178:181], v[218:221], v[70:73]
	v_mfma_f32_16x16x32_bf16 v[66:69], v[186:189], v[218:221], v[66:69]
	s_setprio 0
	s_barrier
	s_add_i32 s38, s62, s46
	v_lshl_add_u64 v[172:173], v[172:173], 0, s[12:13]
	s_mov_b32 m0, s38
	ds_read_b128 v[190:193], v158 offset:49152
	ds_read_b128 v[194:197], v158 offset:50176
	ds_read_b128 v[198:201], v158 offset:51200
	ds_read_b128 v[202:205], v158 offset:52224
	ds_read_b128 v[206:209], v158 offset:53248
	ds_read_b128 v[210:213], v158 offset:54272
	ds_read_b128 v[214:217], v158 offset:55296
	ds_read_b128 v[218:221], v158 offset:56320
	global_load_lds_dwordx4 v[172:173], off
	s_add_i32 m0, s38, 0x2000
	s_add_u32 s38, s42, 0x40080
	v_lshl_add_u64 v[172:173], v[222:223], 0, s[12:13]
	s_addc_u32 s39, s43, 0
	s_add_i32 s42, s63, s46
	global_load_lds_dwordx4 v[172:173], off
	v_lshl_add_u64 v[172:173], s[38:39], 0, v[132:133]
	s_mov_b32 m0, s42
	s_nop 0
	global_load_lds_dwordx4 v[172:173], off
	v_lshl_add_u64 v[172:173], s[38:39], 0, v[136:137]
	s_add_i32 m0, s42, 0x2000
	s_nop 0
	global_load_lds_dwordx4 v[172:173], off
	v_lshl_add_u64 v[172:173], v[224:225], 0, s[12:13]
	s_mov_b32 m0, s51
	s_nop 0
	global_load_lds_dwordx4 v[172:173], off
	v_lshl_add_u64 v[172:173], v[226:227], 0, s[12:13]
	s_mov_b32 m0, s52
	s_nop 0
	global_load_lds_dwordx4 v[172:173], off
	s_waitcnt vmcnt(8)
	s_waitcnt lgkmcnt(0)
	s_barrier
	s_setprio 1
	s_waitcnt lgkmcnt(0)
	v_mfma_f32_16x16x32_bf16 v[62:65], v[146:149], v[190:193], v[62:65]
	v_mfma_f32_16x16x32_bf16 v[58:61], v[160:163], v[190:193], v[58:61]
	v_mfma_f32_16x16x32_bf16 v[46:49], v[146:149], v[198:201], v[46:49]
	v_mfma_f32_16x16x32_bf16 v[42:45], v[160:163], v[198:201], v[42:45]
	v_mfma_f32_16x16x32_bf16 v[30:33], v[146:149], v[206:209], v[30:33]
	v_mfma_f32_16x16x32_bf16 v[26:29], v[160:163], v[206:209], v[26:29]
	v_mfma_f32_16x16x32_bf16 v[14:17], v[146:149], v[214:217], v[14:17]
	v_mfma_f32_16x16x32_bf16 v[10:13], v[160:163], v[214:217], v[10:13]
	v_mfma_f32_16x16x32_bf16 v[62:65], v[150:153], v[194:197], v[62:65]
	v_mfma_f32_16x16x32_bf16 v[58:61], v[164:167], v[194:197], v[58:61]
	v_mfma_f32_16x16x32_bf16 v[46:49], v[150:153], v[202:205], v[46:49]
	v_mfma_f32_16x16x32_bf16 v[42:45], v[164:167], v[202:205], v[42:45]
	v_mfma_f32_16x16x32_bf16 v[30:33], v[150:153], v[210:213], v[30:33]
	v_mfma_f32_16x16x32_bf16 v[26:29], v[164:167], v[210:213], v[26:29]
	v_mfma_f32_16x16x32_bf16 v[14:17], v[150:153], v[218:221], v[14:17]
	v_mfma_f32_16x16x32_bf16 v[10:13], v[164:167], v[218:221], v[10:13]
	v_mfma_f32_16x16x32_bf16 v[54:57], v[168:171], v[190:193], v[54:57]
	v_mfma_f32_16x16x32_bf16 v[50:53], v[182:185], v[190:193], v[50:53]
	v_mfma_f32_16x16x32_bf16 v[38:41], v[168:171], v[198:201], v[38:41]
	v_mfma_f32_16x16x32_bf16 v[34:37], v[182:185], v[198:201], v[34:37]
	v_mfma_f32_16x16x32_bf16 v[22:25], v[168:171], v[206:209], v[22:25]
	v_mfma_f32_16x16x32_bf16 v[18:21], v[182:185], v[206:209], v[18:21]
	v_mfma_f32_16x16x32_bf16 v[6:9], v[168:171], v[214:217], v[6:9]
	v_mfma_f32_16x16x32_bf16 v[2:5], v[182:185], v[214:217], v[2:5]
	v_mfma_f32_16x16x32_bf16 v[54:57], v[178:181], v[194:197], v[54:57]
	v_mfma_f32_16x16x32_bf16 v[50:53], v[186:189], v[194:197], v[50:53]
	v_mfma_f32_16x16x32_bf16 v[38:41], v[178:181], v[202:205], v[38:41]
	v_mfma_f32_16x16x32_bf16 v[34:37], v[186:189], v[202:205], v[34:37]
	v_mfma_f32_16x16x32_bf16 v[22:25], v[178:181], v[210:213], v[22:25]
	v_mfma_f32_16x16x32_bf16 v[18:21], v[186:189], v[210:213], v[18:21]
	v_mfma_f32_16x16x32_bf16 v[6:9], v[178:181], v[218:221], v[6:9]
	v_mfma_f32_16x16x32_bf16 v[2:5], v[186:189], v[218:221], v[2:5]
	s_setprio 0
	s_barrier
	s_add_i32 s61, s61, 2
	s_add_u32 s59, s59, 0x100
	s_addc_u32 s60, s60, 0
	s_cmp_gt_u32 s61, 13
	s_mov_b64 s[38:39], s[40:41]
	s_cbranch_scc0 .LBB0_1135

.LBB0_1223:
	s_ashr_i32 s27, s26, 31
	s_lshl_b64 s[28:29], s[26:27], 19
	s_add_u32 s28, s3, s28
	s_addc_u32 s29, s14, s29
	s_and_b64 s[30:31], s[4:5], exec
	s_cselect_b32 s27, s29, s37
	s_cselect_b32 s35, s28, s36
	s_ashr_i32 s25, s24, 31
	s_lshl_b64 s[30:31], s[24:25], 19
	s_add_u32 s30, s15, s30
	s_addc_u32 s31, s16, s31
	s_and_b64 s[40:41], s[4:5], exec
	s_cselect_b32 s25, s31, s39
	s_cselect_b32 s56, s30, s38
	s_add_u32 s57, s38, 0x100
	s_addc_u32 s58, s39, 0
	s_mov_b32 s59, -2
	s_waitcnt lgkmcnt(0)
	ds_read_b128 v[146:149], v154
	ds_read_b128 v[158:161], v154 offset:1024
	ds_read_b128 v[162:165], v154 offset:2048
	ds_read_b128 v[166:169], v154 offset:3072
	ds_read_b128 v[170:173], v155
	ds_read_b128 v[178:181], v155 offset:1024
	ds_read_b128 v[182:185], v155 offset:2048
	ds_read_b128 v[186:189], v155 offset:3072
	s_add_u32 s38, s36, 0x100
	s_addc_u32 s39, s37, 0
	s_cmp_eq_u32 s59, 12
	s_cselect_b32 s43, s27, s39
	s_cselect_b32 s42, s35, s38
	s_cselect_b32 s41, s25, s58
	s_cselect_b32 s40, s56, s57
	v_lshl_add_u64 v[150:151], s[36:37], 0, v[138:139]
	s_add_i32 m0, s44, 0xc000
	ds_read_b128 v[190:193], v156
	ds_read_b128 v[194:197], v156 offset:1024
	ds_read_b128 v[198:201], v156 offset:2048
	ds_read_b128 v[202:205], v156 offset:3072
	ds_read_b128 v[206:209], v156 offset:4096
	ds_read_b128 v[210:213], v156 offset:5120
	ds_read_b128 v[214:217], v156 offset:6144
	ds_read_b128 v[218:221], v156 offset:7168
	global_load_lds_dwordx4 v[150:151], off
	v_lshl_add_u64 v[150:151], s[36:37], 0, v[140:141]
	s_add_i32 m0, s44, 0xe000
	s_nop 0
	global_load_lds_dwordx4 v[150:151], off
	s_waitcnt vmcnt(8)
	s_waitcnt lgkmcnt(0)
	s_barrier
	s_setprio 1
	s_waitcnt lgkmcnt(0)
	v_mfma_f32_16x16x32_bf16 v[126:129], v[146:149], v[190:193], 0
	v_mfma_f32_16x16x32_bf16 v[122:125], v[162:165], v[190:193], 0
	v_mfma_f32_16x16x32_bf16 v[110:113], v[146:149], v[198:201], 0
	v_mfma_f32_16x16x32_bf16 v[106:109], v[162:165], v[198:201], 0
	v_mfma_f32_16x16x32_bf16 v[94:97], v[146:149], v[206:209], 0
	v_mfma_f32_16x16x32_bf16 v[90:93], v[162:165], v[206:209], 0
	v_mfma_f32_16x16x32_bf16 v[78:81], v[146:149], v[214:217], 0
	v_mfma_f32_16x16x32_bf16 v[74:77], v[162:165], v[214:217], 0
	v_mfma_f32_16x16x32_bf16 v[126:129], v[158:161], v[194:197], v[126:129]
	v_mfma_f32_16x16x32_bf16 v[122:125], v[166:169], v[194:197], v[122:125]
	v_mfma_f32_16x16x32_bf16 v[110:113], v[158:161], v[202:205], v[110:113]
	v_mfma_f32_16x16x32_bf16 v[106:109], v[166:169], v[202:205], v[106:109]
	v_mfma_f32_16x16x32_bf16 v[94:97], v[158:161], v[210:213], v[94:97]
	v_mfma_f32_16x16x32_bf16 v[90:93], v[166:169], v[210:213], v[90:93]
	v_mfma_f32_16x16x32_bf16 v[78:81], v[158:161], v[218:221], v[78:81]
	v_mfma_f32_16x16x32_bf16 v[74:77], v[166:169], v[218:221], v[74:77]
	v_mfma_f32_16x16x32_bf16 v[118:121], v[170:173], v[190:193], 0
	v_mfma_f32_16x16x32_bf16 v[114:117], v[182:185], v[190:193], 0
	v_mfma_f32_16x16x32_bf16 v[102:105], v[170:173], v[198:201], 0
	v_mfma_f32_16x16x32_bf16 v[98:101], v[182:185], v[198:201], 0
	v_mfma_f32_16x16x32_bf16 v[86:89], v[170:173], v[206:209], 0
	v_mfma_f32_16x16x32_bf16 v[82:85], v[182:185], v[206:209], 0
	v_mfma_f32_16x16x32_bf16 v[70:73], v[170:173], v[214:217], 0
	v_mfma_f32_16x16x32_bf16 v[66:69], v[182:185], v[214:217], 0
	v_mfma_f32_16x16x32_bf16 v[118:121], v[178:181], v[194:197], v[118:121]
	v_mfma_f32_16x16x32_bf16 v[114:117], v[186:189], v[194:197], v[114:117]
	v_mfma_f32_16x16x32_bf16 v[102:105], v[178:181], v[202:205], v[102:105]
	v_mfma_f32_16x16x32_bf16 v[98:101], v[186:189], v[202:205], v[98:101]
	v_mfma_f32_16x16x32_bf16 v[86:89], v[178:181], v[210:213], v[86:89]
	v_mfma_f32_16x16x32_bf16 v[82:85], v[186:189], v[210:213], v[82:85]
	v_mfma_f32_16x16x32_bf16 v[70:73], v[178:181], v[218:221], v[70:73]
	v_mfma_f32_16x16x32_bf16 v[66:69], v[186:189], v[218:221], v[66:69]
	s_setprio 0
	s_barrier
	s_add_i32 s36, s53, s17
	v_lshl_add_u64 v[150:151], s[40:41], 0, v[132:133]
	s_mov_b32 m0, s36
	ds_read_b128 v[190:193], v156 offset:16384
	ds_read_b128 v[194:197], v156 offset:17408
	ds_read_b128 v[198:201], v156 offset:18432
	ds_read_b128 v[202:205], v156 offset:19456
	ds_read_b128 v[206:209], v156 offset:20480
	ds_read_b128 v[210:213], v156 offset:21504
	ds_read_b128 v[214:217], v156 offset:22528
	ds_read_b128 v[218:221], v156 offset:23552
	global_load_lds_dwordx4 v[150:151], off
	s_add_i32 m0, s36, 0x2000
	s_add_u32 s36, s40, 0x40000
	v_lshl_add_u64 v[222:223], s[40:41], 0, v[136:137]
	s_addc_u32 s37, s41, 0
	s_add_i32 s60, s54, s17
	global_load_lds_dwordx4 v[222:223], off
	v_lshl_add_u64 v[224:225], s[36:37], 0, v[132:133]
	s_mov_b32 m0, s60
	v_lshl_add_u64 v[226:227], s[42:43], 0, v[134:135]
	global_load_lds_dwordx4 v[224:225], off
	v_lshl_add_u64 v[224:225], s[36:37], 0, v[136:137]
	s_add_i32 m0, s60, 0x2000
	s_nop 0
	global_load_lds_dwordx4 v[224:225], off
	v_lshl_add_u64 v[224:225], s[42:43], 0, v[130:131]
	s_mov_b32 m0, s44
	s_nop 0
	global_load_lds_dwordx4 v[224:225], off
	s_mov_b32 m0, s45
	s_nop 0
	global_load_lds_dwordx4 v[226:227], off
	s_waitcnt vmcnt(8)
	s_waitcnt lgkmcnt(0)
	s_barrier
	s_setprio 1
	s_waitcnt lgkmcnt(0)
	v_mfma_f32_16x16x32_bf16 v[62:65], v[146:149], v[190:193], 0
	v_mfma_f32_16x16x32_bf16 v[58:61], v[162:165], v[190:193], 0
	v_mfma_f32_16x16x32_bf16 v[46:49], v[146:149], v[198:201], 0
	v_mfma_f32_16x16x32_bf16 v[42:45], v[162:165], v[198:201], 0
	v_mfma_f32_16x16x32_bf16 v[30:33], v[146:149], v[206:209], 0
	v_mfma_f32_16x16x32_bf16 v[26:29], v[162:165], v[206:209], 0
	v_mfma_f32_16x16x32_bf16 v[14:17], v[146:149], v[214:217], 0
	v_mfma_f32_16x16x32_bf16 v[10:13], v[162:165], v[214:217], 0
	v_mfma_f32_16x16x32_bf16 v[62:65], v[158:161], v[194:197], v[62:65]
	v_mfma_f32_16x16x32_bf16 v[58:61], v[166:169], v[194:197], v[58:61]
	v_mfma_f32_16x16x32_bf16 v[46:49], v[158:161], v[202:205], v[46:49]
	v_mfma_f32_16x16x32_bf16 v[42:45], v[166:169], v[202:205], v[42:45]
	v_mfma_f32_16x16x32_bf16 v[30:33], v[158:161], v[210:213], v[30:33]
	v_mfma_f32_16x16x32_bf16 v[26:29], v[166:169], v[210:213], v[26:29]
	v_mfma_f32_16x16x32_bf16 v[14:17], v[158:161], v[218:221], v[14:17]
	v_mfma_f32_16x16x32_bf16 v[10:13], v[166:169], v[218:221], v[10:13]
	v_mfma_f32_16x16x32_bf16 v[54:57], v[170:173], v[190:193], 0
	v_mfma_f32_16x16x32_bf16 v[50:53], v[182:185], v[190:193], 0
	v_mfma_f32_16x16x32_bf16 v[38:41], v[170:173], v[198:201], 0
	v_mfma_f32_16x16x32_bf16 v[34:37], v[182:185], v[198:201], 0
	v_mfma_f32_16x16x32_bf16 v[22:25], v[170:173], v[206:209], 0
	v_mfma_f32_16x16x32_bf16 v[18:21], v[182:185], v[206:209], 0
	v_mfma_f32_16x16x32_bf16 v[6:9], v[170:173], v[214:217], 0
	v_mfma_f32_16x16x32_bf16 v[2:5], v[182:185], v[214:217], 0
	v_mfma_f32_16x16x32_bf16 v[54:57], v[178:181], v[194:197], v[54:57]
	v_mfma_f32_16x16x32_bf16 v[50:53], v[186:189], v[194:197], v[50:53]
	v_mfma_f32_16x16x32_bf16 v[38:41], v[178:181], v[202:205], v[38:41]
	v_mfma_f32_16x16x32_bf16 v[34:37], v[186:189], v[202:205], v[34:37]
	v_mfma_f32_16x16x32_bf16 v[22:25], v[178:181], v[210:213], v[22:25]
	v_mfma_f32_16x16x32_bf16 v[18:21], v[186:189], v[210:213], v[18:21]
	v_mfma_f32_16x16x32_bf16 v[6:9], v[178:181], v[218:221], v[6:9]
	v_mfma_f32_16x16x32_bf16 v[2:5], v[186:189], v[218:221], v[2:5]
	s_setprio 0
	s_barrier
	s_add_i32 s60, 0, 0x18000
	s_add_i32 s61, 0, 0x1c000
	v_add_u32_e32 v166, s60, v152
	v_add_u32_e32 v177, s61, v152
	ds_read_b128 v[146:149], v166
	ds_read_b128 v[158:161], v166 offset:1024
	ds_read_b128 v[162:165], v166 offset:2048
	ds_read_b128 v[166:169], v166 offset:3072
	ds_read_b128 v[170:173], v177
	ds_read_b128 v[178:181], v177 offset:1024
	ds_read_b128 v[182:185], v177 offset:2048
	ds_read_b128 v[186:189], v177 offset:3072
	s_add_u32 s36, s42, 0x40000
	s_addc_u32 s37, s43, 0
	s_mov_b32 m0, s46
	v_lshl_add_u64 v[228:229], s[36:37], 0, v[130:131]
	ds_read_b128 v[190:193], v156 offset:32768
	ds_read_b128 v[194:197], v156 offset:33792
	ds_read_b128 v[198:201], v156 offset:34816
	ds_read_b128 v[202:205], v156 offset:35840
	ds_read_b128 v[206:209], v156 offset:36864
	ds_read_b128 v[210:213], v156 offset:37888
	ds_read_b128 v[214:217], v156 offset:38912
	ds_read_b128 v[218:221], v156 offset:39936
	global_load_lds_dwordx4 v[228:229], off
	v_lshl_add_u64 v[228:229], s[36:37], 0, v[134:135]
	s_mov_b32 m0, s47
	s_nop 0
	global_load_lds_dwordx4 v[228:229], off
	s_waitcnt vmcnt(8)
	s_waitcnt lgkmcnt(0)
	s_barrier
	s_setprio 1
	s_waitcnt lgkmcnt(0)
	v_mfma_f32_16x16x32_bf16 v[126:129], v[146:149], v[190:193], v[126:129]
	v_mfma_f32_16x16x32_bf16 v[122:125], v[162:165], v[190:193], v[122:125]
	v_mfma_f32_16x16x32_bf16 v[110:113], v[146:149], v[198:201], v[110:113]
	v_mfma_f32_16x16x32_bf16 v[106:109], v[162:165], v[198:201], v[106:109]
	v_mfma_f32_16x16x32_bf16 v[94:97], v[146:149], v[206:209], v[94:97]
	v_mfma_f32_16x16x32_bf16 v[90:93], v[162:165], v[206:209], v[90:93]
	v_mfma_f32_16x16x32_bf16 v[78:81], v[146:149], v[214:217], v[78:81]
	v_mfma_f32_16x16x32_bf16 v[74:77], v[162:165], v[214:217], v[74:77]
	v_mfma_f32_16x16x32_bf16 v[126:129], v[158:161], v[194:197], v[126:129]
	v_mfma_f32_16x16x32_bf16 v[122:125], v[166:169], v[194:197], v[122:125]
	v_mfma_f32_16x16x32_bf16 v[110:113], v[158:161], v[202:205], v[110:113]
	v_mfma_f32_16x16x32_bf16 v[106:109], v[166:169], v[202:205], v[106:109]
	v_mfma_f32_16x16x32_bf16 v[94:97], v[158:161], v[210:213], v[94:97]
	v_mfma_f32_16x16x32_bf16 v[90:93], v[166:169], v[210:213], v[90:93]
	v_mfma_f32_16x16x32_bf16 v[78:81], v[158:161], v[218:221], v[78:81]
	v_mfma_f32_16x16x32_bf16 v[74:77], v[166:169], v[218:221], v[74:77]
	v_mfma_f32_16x16x32_bf16 v[118:121], v[170:173], v[190:193], v[118:121]
	v_mfma_f32_16x16x32_bf16 v[114:117], v[182:185], v[190:193], v[114:117]
	v_mfma_f32_16x16x32_bf16 v[102:105], v[170:173], v[198:201], v[102:105]
	v_mfma_f32_16x16x32_bf16 v[98:101], v[182:185], v[198:201], v[98:101]
	v_mfma_f32_16x16x32_bf16 v[86:89], v[170:173], v[206:209], v[86:89]
	v_mfma_f32_16x16x32_bf16 v[82:85], v[182:185], v[206:209], v[82:85]
	v_mfma_f32_16x16x32_bf16 v[70:73], v[170:173], v[214:217], v[70:73]
	v_mfma_f32_16x16x32_bf16 v[66:69], v[182:185], v[214:217], v[66:69]
	v_mfma_f32_16x16x32_bf16 v[118:121], v[178:181], v[194:197], v[118:121]
	v_mfma_f32_16x16x32_bf16 v[114:117], v[186:189], v[194:197], v[114:117]
	v_mfma_f32_16x16x32_bf16 v[102:105], v[178:181], v[202:205], v[102:105]
	v_mfma_f32_16x16x32_bf16 v[98:101], v[186:189], v[202:205], v[98:101]
	v_mfma_f32_16x16x32_bf16 v[86:89], v[178:181], v[210:213], v[86:89]
	v_mfma_f32_16x16x32_bf16 v[82:85], v[186:189], v[210:213], v[82:85]
	v_mfma_f32_16x16x32_bf16 v[70:73], v[178:181], v[218:221], v[70:73]
	v_mfma_f32_16x16x32_bf16 v[66:69], v[186:189], v[218:221], v[66:69]
	s_setprio 0
	s_barrier
	s_add_i32 s36, s60, s17
	v_lshl_add_u64 v[150:151], v[150:151], 0, s[20:21]
	s_mov_b32 m0, s36
	ds_read_b128 v[190:193], v156 offset:49152
	ds_read_b128 v[194:197], v156 offset:50176
	ds_read_b128 v[198:201], v156 offset:51200
	ds_read_b128 v[202:205], v156 offset:52224
	ds_read_b128 v[206:209], v156 offset:53248
	ds_read_b128 v[210:213], v156 offset:54272
	ds_read_b128 v[214:217], v156 offset:55296
	ds_read_b128 v[218:221], v156 offset:56320
	global_load_lds_dwordx4 v[150:151], off
	s_add_i32 m0, s36, 0x2000
	s_add_u32 s36, s40, 0x40080
	v_lshl_add_u64 v[150:151], v[222:223], 0, s[20:21]
	s_addc_u32 s37, s41, 0
	s_add_i32 s40, s61, s17
	global_load_lds_dwordx4 v[150:151], off
	v_lshl_add_u64 v[150:151], s[36:37], 0, v[132:133]
	s_mov_b32 m0, s40
	s_nop 0
	global_load_lds_dwordx4 v[150:151], off
	v_lshl_add_u64 v[150:151], s[36:37], 0, v[136:137]
	s_add_i32 m0, s40, 0x2000
	s_nop 0
	global_load_lds_dwordx4 v[150:151], off
	v_lshl_add_u64 v[150:151], v[224:225], 0, s[20:21]
	s_mov_b32 m0, s49
	s_nop 0
	global_load_lds_dwordx4 v[150:151], off
	v_lshl_add_u64 v[150:151], v[226:227], 0, s[20:21]
	s_mov_b32 m0, s50
	s_nop 0
	global_load_lds_dwordx4 v[150:151], off
	s_waitcnt vmcnt(8)
	s_waitcnt lgkmcnt(0)
	s_barrier
	s_setprio 1
	s_waitcnt lgkmcnt(0)
	v_mfma_f32_16x16x32_bf16 v[62:65], v[146:149], v[190:193], v[62:65]
	v_mfma_f32_16x16x32_bf16 v[58:61], v[162:165], v[190:193], v[58:61]
	v_mfma_f32_16x16x32_bf16 v[46:49], v[146:149], v[198:201], v[46:49]
	v_mfma_f32_16x16x32_bf16 v[42:45], v[162:165], v[198:201], v[42:45]
	v_mfma_f32_16x16x32_bf16 v[30:33], v[146:149], v[206:209], v[30:33]
	v_mfma_f32_16x16x32_bf16 v[26:29], v[162:165], v[206:209], v[26:29]
	v_mfma_f32_16x16x32_bf16 v[14:17], v[146:149], v[214:217], v[14:17]
	v_mfma_f32_16x16x32_bf16 v[10:13], v[162:165], v[214:217], v[10:13]
	v_mfma_f32_16x16x32_bf16 v[62:65], v[158:161], v[194:197], v[62:65]
	v_mfma_f32_16x16x32_bf16 v[58:61], v[166:169], v[194:197], v[58:61]
	v_mfma_f32_16x16x32_bf16 v[46:49], v[158:161], v[202:205], v[46:49]
	v_mfma_f32_16x16x32_bf16 v[42:45], v[166:169], v[202:205], v[42:45]
	v_mfma_f32_16x16x32_bf16 v[30:33], v[158:161], v[210:213], v[30:33]
	v_mfma_f32_16x16x32_bf16 v[26:29], v[166:169], v[210:213], v[26:29]
	v_mfma_f32_16x16x32_bf16 v[14:17], v[158:161], v[218:221], v[14:17]
	v_mfma_f32_16x16x32_bf16 v[10:13], v[166:169], v[218:221], v[10:13]
	v_mfma_f32_16x16x32_bf16 v[54:57], v[170:173], v[190:193], v[54:57]
	v_mfma_f32_16x16x32_bf16 v[50:53], v[182:185], v[190:193], v[50:53]
	v_mfma_f32_16x16x32_bf16 v[38:41], v[170:173], v[198:201], v[38:41]
	v_mfma_f32_16x16x32_bf16 v[34:37], v[182:185], v[198:201], v[34:37]
	v_mfma_f32_16x16x32_bf16 v[22:25], v[170:173], v[206:209], v[22:25]
	v_mfma_f32_16x16x32_bf16 v[18:21], v[182:185], v[206:209], v[18:21]
	v_mfma_f32_16x16x32_bf16 v[6:9], v[170:173], v[214:217], v[6:9]
	v_mfma_f32_16x16x32_bf16 v[2:5], v[182:185], v[214:217], v[2:5]
	v_mfma_f32_16x16x32_bf16 v[54:57], v[178:181], v[194:197], v[54:57]
	v_mfma_f32_16x16x32_bf16 v[50:53], v[186:189], v[194:197], v[50:53]
	v_mfma_f32_16x16x32_bf16 v[38:41], v[178:181], v[202:205], v[38:41]
	v_mfma_f32_16x16x32_bf16 v[34:37], v[186:189], v[202:205], v[34:37]
	v_mfma_f32_16x16x32_bf16 v[22:25], v[178:181], v[210:213], v[22:25]
	v_mfma_f32_16x16x32_bf16 v[18:21], v[186:189], v[210:213], v[18:21]
	v_mfma_f32_16x16x32_bf16 v[6:9], v[178:181], v[218:221], v[6:9]
	v_mfma_f32_16x16x32_bf16 v[2:5], v[186:189], v[218:221], v[2:5]
	s_setprio 0
	s_barrier
	s_add_i32 s59, s59, 2
	s_add_u32 s57, s57, 0x100
	s_addc_u32 s58, s58, 0
	s_cmp_gt_u32 s59, 13
	s_mov_b64 s[36:37], s[38:39]
	s_cbranch_scc0 .LBB0_1224
	s_branch .Lpeel_exit_1224
.LBB0_1224:
	ds_read_b128 v[146:149], v154
	ds_read_b128 v[158:161], v154 offset:1024
	ds_read_b128 v[162:165], v154 offset:2048
	ds_read_b128 v[166:169], v154 offset:3072
	ds_read_b128 v[170:173], v155
	ds_read_b128 v[178:181], v155 offset:1024
	ds_read_b128 v[182:185], v155 offset:2048
	ds_read_b128 v[186:189], v155 offset:3072
	s_add_u32 s38, s36, 0x100
	s_addc_u32 s39, s37, 0
	s_cmp_eq_u32 s59, 12
	s_cselect_b32 s43, s27, s39
	s_cselect_b32 s42, s35, s38
	s_cselect_b32 s41, s25, s58
	s_cselect_b32 s40, s56, s57
	v_lshl_add_u64 v[150:151], s[36:37], 0, v[138:139]
	s_add_i32 m0, s44, 0xc000
	ds_read_b128 v[190:193], v156
	ds_read_b128 v[194:197], v156 offset:1024
	ds_read_b128 v[198:201], v156 offset:2048
	ds_read_b128 v[202:205], v156 offset:3072
	ds_read_b128 v[206:209], v156 offset:4096
	ds_read_b128 v[210:213], v156 offset:5120
	ds_read_b128 v[214:217], v156 offset:6144
	ds_read_b128 v[218:221], v156 offset:7168
	global_load_lds_dwordx4 v[150:151], off
	v_lshl_add_u64 v[150:151], s[36:37], 0, v[140:141]
	s_add_i32 m0, s44, 0xe000
	s_nop 0
	global_load_lds_dwordx4 v[150:151], off
	s_waitcnt vmcnt(8)
	s_waitcnt lgkmcnt(0)
	s_barrier
	s_setprio 1
	s_waitcnt lgkmcnt(0)
	v_mfma_f32_16x16x32_bf16 v[126:129], v[146:149], v[190:193], v[126:129]
	v_mfma_f32_16x16x32_bf16 v[122:125], v[162:165], v[190:193], v[122:125]
	v_mfma_f32_16x16x32_bf16 v[110:113], v[146:149], v[198:201], v[110:113]
	v_mfma_f32_16x16x32_bf16 v[106:109], v[162:165], v[198:201], v[106:109]
	v_mfma_f32_16x16x32_bf16 v[94:97], v[146:149], v[206:209], v[94:97]
	v_mfma_f32_16x16x32_bf16 v[90:93], v[162:165], v[206:209], v[90:93]
	v_mfma_f32_16x16x32_bf16 v[78:81], v[146:149], v[214:217], v[78:81]
	v_mfma_f32_16x16x32_bf16 v[74:77], v[162:165], v[214:217], v[74:77]
	v_mfma_f32_16x16x32_bf16 v[126:129], v[158:161], v[194:197], v[126:129]
	v_mfma_f32_16x16x32_bf16 v[122:125], v[166:169], v[194:197], v[122:125]
	v_mfma_f32_16x16x32_bf16 v[110:113], v[158:161], v[202:205], v[110:113]
	v_mfma_f32_16x16x32_bf16 v[106:109], v[166:169], v[202:205], v[106:109]
	v_mfma_f32_16x16x32_bf16 v[94:97], v[158:161], v[210:213], v[94:97]
	v_mfma_f32_16x16x32_bf16 v[90:93], v[166:169], v[210:213], v[90:93]
	v_mfma_f32_16x16x32_bf16 v[78:81], v[158:161], v[218:221], v[78:81]
	v_mfma_f32_16x16x32_bf16 v[74:77], v[166:169], v[218:221], v[74:77]
	v_mfma_f32_16x16x32_bf16 v[118:121], v[170:173], v[190:193], v[118:121]
	v_mfma_f32_16x16x32_bf16 v[114:117], v[182:185], v[190:193], v[114:117]
	v_mfma_f32_16x16x32_bf16 v[102:105], v[170:173], v[198:201], v[102:105]
	v_mfma_f32_16x16x32_bf16 v[98:101], v[182:185], v[198:201], v[98:101]
	v_mfma_f32_16x16x32_bf16 v[86:89], v[170:173], v[206:209], v[86:89]
	v_mfma_f32_16x16x32_bf16 v[82:85], v[182:185], v[206:209], v[82:85]
	v_mfma_f32_16x16x32_bf16 v[70:73], v[170:173], v[214:217], v[70:73]
	v_mfma_f32_16x16x32_bf16 v[66:69], v[182:185], v[214:217], v[66:69]
	v_mfma_f32_16x16x32_bf16 v[118:121], v[178:181], v[194:197], v[118:121]
	v_mfma_f32_16x16x32_bf16 v[114:117], v[186:189], v[194:197], v[114:117]
	v_mfma_f32_16x16x32_bf16 v[102:105], v[178:181], v[202:205], v[102:105]
	v_mfma_f32_16x16x32_bf16 v[98:101], v[186:189], v[202:205], v[98:101]
	v_mfma_f32_16x16x32_bf16 v[86:89], v[178:181], v[210:213], v[86:89]
	v_mfma_f32_16x16x32_bf16 v[82:85], v[186:189], v[210:213], v[82:85]
	v_mfma_f32_16x16x32_bf16 v[70:73], v[178:181], v[218:221], v[70:73]
	v_mfma_f32_16x16x32_bf16 v[66:69], v[186:189], v[218:221], v[66:69]
	s_setprio 0
	s_barrier
	s_add_i32 s36, s53, s17
	v_lshl_add_u64 v[150:151], s[40:41], 0, v[132:133]
	s_mov_b32 m0, s36
	ds_read_b128 v[190:193], v156 offset:16384
	ds_read_b128 v[194:197], v156 offset:17408
	ds_read_b128 v[198:201], v156 offset:18432
	ds_read_b128 v[202:205], v156 offset:19456
	ds_read_b128 v[206:209], v156 offset:20480
	ds_read_b128 v[210:213], v156 offset:21504
	ds_read_b128 v[214:217], v156 offset:22528
	ds_read_b128 v[218:221], v156 offset:23552
	global_load_lds_dwordx4 v[150:151], off
	s_add_i32 m0, s36, 0x2000
	s_add_u32 s36, s40, 0x40000
	v_lshl_add_u64 v[222:223], s[40:41], 0, v[136:137]
	s_addc_u32 s37, s41, 0
	s_add_i32 s60, s54, s17
	global_load_lds_dwordx4 v[222:223], off
	v_lshl_add_u64 v[224:225], s[36:37], 0, v[132:133]
	s_mov_b32 m0, s60
	v_lshl_add_u64 v[226:227], s[42:43], 0, v[134:135]
	global_load_lds_dwordx4 v[224:225], off
	v_lshl_add_u64 v[224:225], s[36:37], 0, v[136:137]
	s_add_i32 m0, s60, 0x2000
	s_nop 0
	global_load_lds_dwordx4 v[224:225], off
	v_lshl_add_u64 v[224:225], s[42:43], 0, v[130:131]
	s_mov_b32 m0, s44
	s_nop 0
	global_load_lds_dwordx4 v[224:225], off
	s_mov_b32 m0, s45
	s_nop 0
	global_load_lds_dwordx4 v[226:227], off
	s_waitcnt vmcnt(8)
	s_waitcnt lgkmcnt(0)
	s_barrier
	s_setprio 1
	s_waitcnt lgkmcnt(0)
	v_mfma_f32_16x16x32_bf16 v[62:65], v[146:149], v[190:193], v[62:65]
	v_mfma_f32_16x16x32_bf16 v[58:61], v[162:165], v[190:193], v[58:61]
	v_mfma_f32_16x16x32_bf16 v[46:49], v[146:149], v[198:201], v[46:49]
	v_mfma_f32_16x16x32_bf16 v[42:45], v[162:165], v[198:201], v[42:45]
	v_mfma_f32_16x16x32_bf16 v[30:33], v[146:149], v[206:209], v[30:33]
	v_mfma_f32_16x16x32_bf16 v[26:29], v[162:165], v[206:209], v[26:29]
	v_mfma_f32_16x16x32_bf16 v[14:17], v[146:149], v[214:217], v[14:17]
	v_mfma_f32_16x16x32_bf16 v[10:13], v[162:165], v[214:217], v[10:13]
	v_mfma_f32_16x16x32_bf16 v[62:65], v[158:161], v[194:197], v[62:65]
	v_mfma_f32_16x16x32_bf16 v[58:61], v[166:169], v[194:197], v[58:61]
	v_mfma_f32_16x16x32_bf16 v[46:49], v[158:161], v[202:205], v[46:49]
	v_mfma_f32_16x16x32_bf16 v[42:45], v[166:169], v[202:205], v[42:45]
	v_mfma_f32_16x16x32_bf16 v[30:33], v[158:161], v[210:213], v[30:33]
	v_mfma_f32_16x16x32_bf16 v[26:29], v[166:169], v[210:213], v[26:29]
	v_mfma_f32_16x16x32_bf16 v[14:17], v[158:161], v[218:221], v[14:17]
	v_mfma_f32_16x16x32_bf16 v[10:13], v[166:169], v[218:221], v[10:13]
	v_mfma_f32_16x16x32_bf16 v[54:57], v[170:173], v[190:193], v[54:57]
	v_mfma_f32_16x16x32_bf16 v[50:53], v[182:185], v[190:193], v[50:53]
	v_mfma_f32_16x16x32_bf16 v[38:41], v[170:173], v[198:201], v[38:41]
	v_mfma_f32_16x16x32_bf16 v[34:37], v[182:185], v[198:201], v[34:37]
	v_mfma_f32_16x16x32_bf16 v[22:25], v[170:173], v[206:209], v[22:25]
	v_mfma_f32_16x16x32_bf16 v[18:21], v[182:185], v[206:209], v[18:21]
	v_mfma_f32_16x16x32_bf16 v[6:9], v[170:173], v[214:217], v[6:9]
	v_mfma_f32_16x16x32_bf16 v[2:5], v[182:185], v[214:217], v[2:5]
	v_mfma_f32_16x16x32_bf16 v[54:57], v[178:181], v[194:197], v[54:57]
	v_mfma_f32_16x16x32_bf16 v[50:53], v[186:189], v[194:197], v[50:53]
	v_mfma_f32_16x16x32_bf16 v[38:41], v[178:181], v[202:205], v[38:41]
	v_mfma_f32_16x16x32_bf16 v[34:37], v[186:189], v[202:205], v[34:37]
	v_mfma_f32_16x16x32_bf16 v[22:25], v[178:181], v[210:213], v[22:25]
	v_mfma_f32_16x16x32_bf16 v[18:21], v[186:189], v[210:213], v[18:21]
	v_mfma_f32_16x16x32_bf16 v[6:9], v[178:181], v[218:221], v[6:9]
	v_mfma_f32_16x16x32_bf16 v[2:5], v[186:189], v[218:221], v[2:5]
	s_setprio 0
	s_barrier
	s_add_i32 s60, 0, 0x18000
	s_add_i32 s61, 0, 0x1c000
	v_add_u32_e32 v166, s60, v152
	v_add_u32_e32 v177, s61, v152
	ds_read_b128 v[146:149], v166
	ds_read_b128 v[158:161], v166 offset:1024
	ds_read_b128 v[162:165], v166 offset:2048
	ds_read_b128 v[166:169], v166 offset:3072
	ds_read_b128 v[170:173], v177
	ds_read_b128 v[178:181], v177 offset:1024
	ds_read_b128 v[182:185], v177 offset:2048
	ds_read_b128 v[186:189], v177 offset:3072
	s_add_u32 s36, s42, 0x40000
	s_addc_u32 s37, s43, 0
	s_mov_b32 m0, s46
	v_lshl_add_u64 v[228:229], s[36:37], 0, v[130:131]
	ds_read_b128 v[190:193], v156 offset:32768
	ds_read_b128 v[194:197], v156 offset:33792
	ds_read_b128 v[198:201], v156 offset:34816
	ds_read_b128 v[202:205], v156 offset:35840
	ds_read_b128 v[206:209], v156 offset:36864
	ds_read_b128 v[210:213], v156 offset:37888
	ds_read_b128 v[214:217], v156 offset:38912
	ds_read_b128 v[218:221], v156 offset:39936
	global_load_lds_dwordx4 v[228:229], off
	v_lshl_add_u64 v[228:229], s[36:37], 0, v[134:135]
	s_mov_b32 m0, s47
	s_nop 0
	global_load_lds_dwordx4 v[228:229], off
	s_waitcnt vmcnt(8)
	s_waitcnt lgkmcnt(0)
	s_barrier
	s_setprio 1
	s_waitcnt lgkmcnt(0)
	v_mfma_f32_16x16x32_bf16 v[126:129], v[146:149], v[190:193], v[126:129]
	v_mfma_f32_16x16x32_bf16 v[122:125], v[162:165], v[190:193], v[122:125]
	v_mfma_f32_16x16x32_bf16 v[110:113], v[146:149], v[198:201], v[110:113]
	v_mfma_f32_16x16x32_bf16 v[106:109], v[162:165], v[198:201], v[106:109]
	v_mfma_f32_16x16x32_bf16 v[94:97], v[146:149], v[206:209], v[94:97]
	v_mfma_f32_16x16x32_bf16 v[90:93], v[162:165], v[206:209], v[90:93]
	v_mfma_f32_16x16x32_bf16 v[78:81], v[146:149], v[214:217], v[78:81]
	v_mfma_f32_16x16x32_bf16 v[74:77], v[162:165], v[214:217], v[74:77]
	v_mfma_f32_16x16x32_bf16 v[126:129], v[158:161], v[194:197], v[126:129]
	v_mfma_f32_16x16x32_bf16 v[122:125], v[166:169], v[194:197], v[122:125]
	v_mfma_f32_16x16x32_bf16 v[110:113], v[158:161], v[202:205], v[110:113]
	v_mfma_f32_16x16x32_bf16 v[106:109], v[166:169], v[202:205], v[106:109]
	v_mfma_f32_16x16x32_bf16 v[94:97], v[158:161], v[210:213], v[94:97]
	v_mfma_f32_16x16x32_bf16 v[90:93], v[166:169], v[210:213], v[90:93]
	v_mfma_f32_16x16x32_bf16 v[78:81], v[158:161], v[218:221], v[78:81]
	v_mfma_f32_16x16x32_bf16 v[74:77], v[166:169], v[218:221], v[74:77]
	v_mfma_f32_16x16x32_bf16 v[118:121], v[170:173], v[190:193], v[118:121]
	v_mfma_f32_16x16x32_bf16 v[114:117], v[182:185], v[190:193], v[114:117]
	v_mfma_f32_16x16x32_bf16 v[102:105], v[170:173], v[198:201], v[102:105]
	v_mfma_f32_16x16x32_bf16 v[98:101], v[182:185], v[198:201], v[98:101]
	v_mfma_f32_16x16x32_bf16 v[86:89], v[170:173], v[206:209], v[86:89]
	v_mfma_f32_16x16x32_bf16 v[82:85], v[182:185], v[206:209], v[82:85]
	v_mfma_f32_16x16x32_bf16 v[70:73], v[170:173], v[214:217], v[70:73]
	v_mfma_f32_16x16x32_bf16 v[66:69], v[182:185], v[214:217], v[66:69]
	v_mfma_f32_16x16x32_bf16 v[118:121], v[178:181], v[194:197], v[118:121]
	v_mfma_f32_16x16x32_bf16 v[114:117], v[186:189], v[194:197], v[114:117]
	v_mfma_f32_16x16x32_bf16 v[102:105], v[178:181], v[202:205], v[102:105]
	v_mfma_f32_16x16x32_bf16 v[98:101], v[186:189], v[202:205], v[98:101]
	v_mfma_f32_16x16x32_bf16 v[86:89], v[178:181], v[210:213], v[86:89]
	v_mfma_f32_16x16x32_bf16 v[82:85], v[186:189], v[210:213], v[82:85]
	v_mfma_f32_16x16x32_bf16 v[70:73], v[178:181], v[218:221], v[70:73]
	v_mfma_f32_16x16x32_bf16 v[66:69], v[186:189], v[218:221], v[66:69]
	s_setprio 0
	s_barrier
	s_add_i32 s36, s60, s17
	v_lshl_add_u64 v[150:151], v[150:151], 0, s[20:21]
	s_mov_b32 m0, s36
	ds_read_b128 v[190:193], v156 offset:49152
	ds_read_b128 v[194:197], v156 offset:50176
	ds_read_b128 v[198:201], v156 offset:51200
	ds_read_b128 v[202:205], v156 offset:52224
	ds_read_b128 v[206:209], v156 offset:53248
	ds_read_b128 v[210:213], v156 offset:54272
	ds_read_b128 v[214:217], v156 offset:55296
	ds_read_b128 v[218:221], v156 offset:56320
	global_load_lds_dwordx4 v[150:151], off
	s_add_i32 m0, s36, 0x2000
	s_add_u32 s36, s40, 0x40080
	v_lshl_add_u64 v[150:151], v[222:223], 0, s[20:21]
	s_addc_u32 s37, s41, 0
	s_add_i32 s40, s61, s17
	global_load_lds_dwordx4 v[150:151], off
	v_lshl_add_u64 v[150:151], s[36:37], 0, v[132:133]
	s_mov_b32 m0, s40
	s_nop 0
	global_load_lds_dwordx4 v[150:151], off
	v_lshl_add_u64 v[150:151], s[36:37], 0, v[136:137]
	s_add_i32 m0, s40, 0x2000
	s_nop 0
	global_load_lds_dwordx4 v[150:151], off
	v_lshl_add_u64 v[150:151], v[224:225], 0, s[20:21]
	s_mov_b32 m0, s49
	s_nop 0
	global_load_lds_dwordx4 v[150:151], off
	v_lshl_add_u64 v[150:151], v[226:227], 0, s[20:21]
	s_mov_b32 m0, s50
	s_nop 0
	global_load_lds_dwordx4 v[150:151], off
	s_waitcnt vmcnt(8)
	s_waitcnt lgkmcnt(0)
	s_barrier
	s_setprio 1
	s_waitcnt lgkmcnt(0)
	v_mfma_f32_16x16x32_bf16 v[62:65], v[146:149], v[190:193], v[62:65]
	v_mfma_f32_16x16x32_bf16 v[58:61], v[162:165], v[190:193], v[58:61]
	v_mfma_f32_16x16x32_bf16 v[46:49], v[146:149], v[198:201], v[46:49]
	v_mfma_f32_16x16x32_bf16 v[42:45], v[162:165], v[198:201], v[42:45]
	v_mfma_f32_16x16x32_bf16 v[30:33], v[146:149], v[206:209], v[30:33]
	v_mfma_f32_16x16x32_bf16 v[26:29], v[162:165], v[206:209], v[26:29]
	v_mfma_f32_16x16x32_bf16 v[14:17], v[146:149], v[214:217], v[14:17]
	v_mfma_f32_16x16x32_bf16 v[10:13], v[162:165], v[214:217], v[10:13]
	v_mfma_f32_16x16x32_bf16 v[62:65], v[158:161], v[194:197], v[62:65]
	v_mfma_f32_16x16x32_bf16 v[58:61], v[166:169], v[194:197], v[58:61]
	v_mfma_f32_16x16x32_bf16 v[46:49], v[158:161], v[202:205], v[46:49]
	v_mfma_f32_16x16x32_bf16 v[42:45], v[166:169], v[202:205], v[42:45]
	v_mfma_f32_16x16x32_bf16 v[30:33], v[158:161], v[210:213], v[30:33]
	v_mfma_f32_16x16x32_bf16 v[26:29], v[166:169], v[210:213], v[26:29]
	v_mfma_f32_16x16x32_bf16 v[14:17], v[158:161], v[218:221], v[14:17]
	v_mfma_f32_16x16x32_bf16 v[10:13], v[166:169], v[218:221], v[10:13]
	v_mfma_f32_16x16x32_bf16 v[54:57], v[170:173], v[190:193], v[54:57]
	v_mfma_f32_16x16x32_bf16 v[50:53], v[182:185], v[190:193], v[50:53]
	v_mfma_f32_16x16x32_bf16 v[38:41], v[170:173], v[198:201], v[38:41]
	v_mfma_f32_16x16x32_bf16 v[34:37], v[182:185], v[198:201], v[34:37]
	v_mfma_f32_16x16x32_bf16 v[22:25], v[170:173], v[206:209], v[22:25]
	v_mfma_f32_16x16x32_bf16 v[18:21], v[182:185], v[206:209], v[18:21]
	v_mfma_f32_16x16x32_bf16 v[6:9], v[170:173], v[214:217], v[6:9]
	v_mfma_f32_16x16x32_bf16 v[2:5], v[182:185], v[214:217], v[2:5]
	v_mfma_f32_16x16x32_bf16 v[54:57], v[178:181], v[194:197], v[54:57]
	v_mfma_f32_16x16x32_bf16 v[50:53], v[186:189], v[194:197], v[50:53]
	v_mfma_f32_16x16x32_bf16 v[38:41], v[178:181], v[202:205], v[38:41]
	v_mfma_f32_16x16x32_bf16 v[34:37], v[186:189], v[202:205], v[34:37]
	v_mfma_f32_16x16x32_bf16 v[22:25], v[178:181], v[210:213], v[22:25]
	v_mfma_f32_16x16x32_bf16 v[18:21], v[186:189], v[210:213], v[18:21]
	v_mfma_f32_16x16x32_bf16 v[6:9], v[178:181], v[218:221], v[6:9]
	v_mfma_f32_16x16x32_bf16 v[2:5], v[186:189], v[218:221], v[2:5]
	s_setprio 0
	s_barrier
	s_add_i32 s59, s59, 2
	s_add_u32 s57, s57, 0x100
	s_addc_u32 s58, s58, 0
	s_cmp_gt_u32 s59, 13
	s_mov_b64 s[36:37], s[38:39]
	s_cbranch_scc0 .LBB0_1224

.LBB0_1322:
	s_ashr_i32 s23, s22, 31
	s_lshl_b64 s[24:25], s[22:23], 19
	s_add_u32 s24, s3, s24
	s_addc_u32 s25, s14, s25
	s_and_b64 s[26:27], s[0:1], exec
	s_cselect_b32 s23, s25, s29
	s_cselect_b32 s50, s24, s28
	s_ashr_i32 s21, s20, 31
	s_lshl_b64 s[26:27], s[20:21], 19
	s_add_u32 s26, s15, s26
	s_addc_u32 s27, s16, s27
	s_and_b64 s[34:35], s[0:1], exec
	s_cselect_b32 s21, s27, s31
	s_cselect_b32 s51, s26, s30
	s_add_u32 s52, s30, 0x100
	s_addc_u32 s53, s31, 0
	s_mov_b32 s54, -2
	ds_read_b128 v[148:151], v154
	ds_read_b128 v[160:163], v154 offset:1024
	ds_read_b128 v[164:167], v154 offset:2048
	ds_read_b128 v[168:171], v154 offset:3072
	ds_read_b128 v[178:181], v155
	ds_read_b128 v[182:185], v155 offset:1024
	ds_read_b128 v[186:189], v155 offset:2048
	ds_read_b128 v[190:193], v155 offset:3072
	s_add_u32 s30, s28, 0x100
	s_addc_u32 s31, s29, 0
	s_cmp_eq_u32 s54, 12
	s_cselect_b32 s37, s23, s31
	s_cselect_b32 s36, s50, s30
	s_cselect_b32 s35, s21, s53
	s_cselect_b32 s34, s51, s52
	v_lshl_add_u64 v[172:173], s[28:29], 0, v[140:141]
	s_add_i32 m0, s39, 0xc000
	ds_read_b128 v[194:197], v156
	ds_read_b128 v[198:201], v156 offset:1024
	ds_read_b128 v[202:205], v156 offset:2048
	ds_read_b128 v[206:209], v156 offset:3072
	ds_read_b128 v[210:213], v156 offset:4096
	ds_read_b128 v[214:217], v156 offset:5120
	ds_read_b128 v[218:221], v156 offset:6144
	ds_read_b128 v[222:225], v156 offset:7168
	global_load_lds_dwordx4 v[172:173], off
	v_lshl_add_u64 v[172:173], s[28:29], 0, v[142:143]
	s_add_i32 m0, s39, 0xe000
	s_nop 0
	global_load_lds_dwordx4 v[172:173], off
	s_waitcnt vmcnt(8)
	s_waitcnt lgkmcnt(0)
	s_barrier
	s_setprio 1
	s_waitcnt lgkmcnt(0)
	v_mfma_f32_16x16x32_bf16 v[126:129], v[148:151], v[194:197], 0
	v_mfma_f32_16x16x32_bf16 v[122:125], v[164:167], v[194:197], 0
	v_mfma_f32_16x16x32_bf16 v[110:113], v[148:151], v[202:205], 0
	v_mfma_f32_16x16x32_bf16 v[106:109], v[164:167], v[202:205], 0
	v_mfma_f32_16x16x32_bf16 v[94:97], v[148:151], v[210:213], 0
	v_mfma_f32_16x16x32_bf16 v[90:93], v[164:167], v[210:213], 0
	v_mfma_f32_16x16x32_bf16 v[78:81], v[148:151], v[218:221], 0
	v_mfma_f32_16x16x32_bf16 v[74:77], v[164:167], v[218:221], 0
	v_mfma_f32_16x16x32_bf16 v[126:129], v[160:163], v[198:201], v[126:129]
	v_mfma_f32_16x16x32_bf16 v[122:125], v[168:171], v[198:201], v[122:125]
	v_mfma_f32_16x16x32_bf16 v[110:113], v[160:163], v[206:209], v[110:113]
	v_mfma_f32_16x16x32_bf16 v[106:109], v[168:171], v[206:209], v[106:109]
	v_mfma_f32_16x16x32_bf16 v[94:97], v[160:163], v[214:217], v[94:97]
	v_mfma_f32_16x16x32_bf16 v[90:93], v[168:171], v[214:217], v[90:93]
	v_mfma_f32_16x16x32_bf16 v[78:81], v[160:163], v[222:225], v[78:81]
	v_mfma_f32_16x16x32_bf16 v[74:77], v[168:171], v[222:225], v[74:77]
	v_mfma_f32_16x16x32_bf16 v[118:121], v[178:181], v[194:197], 0
	v_mfma_f32_16x16x32_bf16 v[114:117], v[186:189], v[194:197], 0
	v_mfma_f32_16x16x32_bf16 v[102:105], v[178:181], v[202:205], 0
	v_mfma_f32_16x16x32_bf16 v[98:101], v[186:189], v[202:205], 0
	v_mfma_f32_16x16x32_bf16 v[86:89], v[178:181], v[210:213], 0
	v_mfma_f32_16x16x32_bf16 v[82:85], v[186:189], v[210:213], 0
	v_mfma_f32_16x16x32_bf16 v[70:73], v[178:181], v[218:221], 0
	v_mfma_f32_16x16x32_bf16 v[66:69], v[186:189], v[218:221], 0
	v_mfma_f32_16x16x32_bf16 v[118:121], v[182:185], v[198:201], v[118:121]
	v_mfma_f32_16x16x32_bf16 v[114:117], v[190:193], v[198:201], v[114:117]
	v_mfma_f32_16x16x32_bf16 v[102:105], v[182:185], v[206:209], v[102:105]
	v_mfma_f32_16x16x32_bf16 v[98:101], v[190:193], v[206:209], v[98:101]
	v_mfma_f32_16x16x32_bf16 v[86:89], v[182:185], v[214:217], v[86:89]
	v_mfma_f32_16x16x32_bf16 v[82:85], v[190:193], v[214:217], v[82:85]
	v_mfma_f32_16x16x32_bf16 v[70:73], v[182:185], v[222:225], v[70:73]
	v_mfma_f32_16x16x32_bf16 v[66:69], v[190:193], v[222:225], v[66:69]
	s_setprio 0
	s_barrier
	s_add_i32 s28, s47, s38
	v_lshl_add_u64 v[172:173], s[34:35], 0, v[132:133]
	s_mov_b32 m0, s28
	ds_read_b128 v[194:197], v156 offset:16384
	ds_read_b128 v[198:201], v156 offset:17408
	ds_read_b128 v[202:205], v156 offset:18432
	ds_read_b128 v[206:209], v156 offset:19456
	ds_read_b128 v[210:213], v156 offset:20480
	ds_read_b128 v[214:217], v156 offset:21504
	ds_read_b128 v[218:221], v156 offset:22528
	ds_read_b128 v[222:225], v156 offset:23552
	global_load_lds_dwordx4 v[172:173], off
	s_add_i32 m0, s28, 0x2000
	s_add_u32 s28, s34, 0x40000
	v_lshl_add_u64 v[226:227], s[34:35], 0, v[136:137]
	s_addc_u32 s29, s35, 0
	s_add_i32 s55, s48, s38
	global_load_lds_dwordx4 v[226:227], off
	v_lshl_add_u64 v[228:229], s[28:29], 0, v[132:133]
	s_mov_b32 m0, s55
	v_lshl_add_u64 v[230:231], s[36:37], 0, v[134:135]
	global_load_lds_dwordx4 v[228:229], off
	v_lshl_add_u64 v[228:229], s[28:29], 0, v[136:137]
	s_add_i32 m0, s55, 0x2000
	s_nop 0
	global_load_lds_dwordx4 v[228:229], off
	v_lshl_add_u64 v[228:229], s[36:37], 0, v[130:131]
	s_mov_b32 m0, s39
	s_nop 0
	global_load_lds_dwordx4 v[228:229], off
	s_mov_b32 m0, s40
	s_nop 0
	global_load_lds_dwordx4 v[230:231], off
	s_waitcnt vmcnt(8)
	s_waitcnt lgkmcnt(0)
	s_barrier
	s_setprio 1
	s_waitcnt lgkmcnt(0)
	v_mfma_f32_16x16x32_bf16 v[62:65], v[148:151], v[194:197], 0
	v_mfma_f32_16x16x32_bf16 v[58:61], v[164:167], v[194:197], 0
	v_mfma_f32_16x16x32_bf16 v[46:49], v[148:151], v[202:205], 0
	v_mfma_f32_16x16x32_bf16 v[42:45], v[164:167], v[202:205], 0
	v_mfma_f32_16x16x32_bf16 v[30:33], v[148:151], v[210:213], 0
	v_mfma_f32_16x16x32_bf16 v[26:29], v[164:167], v[210:213], 0
	v_mfma_f32_16x16x32_bf16 v[14:17], v[148:151], v[218:221], 0
	v_mfma_f32_16x16x32_bf16 v[10:13], v[164:167], v[218:221], 0
	v_mfma_f32_16x16x32_bf16 v[62:65], v[160:163], v[198:201], v[62:65]
	v_mfma_f32_16x16x32_bf16 v[58:61], v[168:171], v[198:201], v[58:61]
	v_mfma_f32_16x16x32_bf16 v[46:49], v[160:163], v[206:209], v[46:49]
	v_mfma_f32_16x16x32_bf16 v[42:45], v[168:171], v[206:209], v[42:45]
	v_mfma_f32_16x16x32_bf16 v[30:33], v[160:163], v[214:217], v[30:33]
	v_mfma_f32_16x16x32_bf16 v[26:29], v[168:171], v[214:217], v[26:29]
	v_mfma_f32_16x16x32_bf16 v[14:17], v[160:163], v[222:225], v[14:17]
	v_mfma_f32_16x16x32_bf16 v[10:13], v[168:171], v[222:225], v[10:13]
	v_mfma_f32_16x16x32_bf16 v[54:57], v[178:181], v[194:197], 0
	v_mfma_f32_16x16x32_bf16 v[50:53], v[186:189], v[194:197], 0
	v_mfma_f32_16x16x32_bf16 v[38:41], v[178:181], v[202:205], 0
	v_mfma_f32_16x16x32_bf16 v[34:37], v[186:189], v[202:205], 0
	v_mfma_f32_16x16x32_bf16 v[22:25], v[178:181], v[210:213], 0
	v_mfma_f32_16x16x32_bf16 v[18:21], v[186:189], v[210:213], 0
	v_mfma_f32_16x16x32_bf16 v[6:9], v[178:181], v[218:221], 0
	v_mfma_f32_16x16x32_bf16 v[2:5], v[186:189], v[218:221], 0
	v_mfma_f32_16x16x32_bf16 v[54:57], v[182:185], v[198:201], v[54:57]
	v_mfma_f32_16x16x32_bf16 v[50:53], v[190:193], v[198:201], v[50:53]
	v_mfma_f32_16x16x32_bf16 v[38:41], v[182:185], v[206:209], v[38:41]
	v_mfma_f32_16x16x32_bf16 v[34:37], v[190:193], v[206:209], v[34:37]
	v_mfma_f32_16x16x32_bf16 v[22:25], v[182:185], v[214:217], v[22:25]
	v_mfma_f32_16x16x32_bf16 v[18:21], v[190:193], v[214:217], v[18:21]
	v_mfma_f32_16x16x32_bf16 v[6:9], v[182:185], v[222:225], v[6:9]
	v_mfma_f32_16x16x32_bf16 v[2:5], v[190:193], v[222:225], v[2:5]
	s_setprio 0
	s_barrier
	s_add_i32 s55, 0, 0x18000
	v_add_u32_e32 v138, s55, v152
	s_add_i32 s56, 0, 0x1c000
	ds_read_b128 v[148:151], v138
	ds_read_b128 v[160:163], v138 offset:1024
	ds_read_b128 v[164:167], v138 offset:2048
	ds_read_b128 v[168:171], v138 offset:3072
	v_add_u32_e32 v138, s56, v152
	ds_read_b128 v[178:181], v138
	ds_read_b128 v[182:185], v138 offset:1024
	ds_read_b128 v[186:189], v138 offset:2048
	ds_read_b128 v[190:193], v138 offset:3072
	s_add_u32 s28, s36, 0x40000
	s_addc_u32 s29, s37, 0
	s_mov_b32 m0, s41
	v_lshl_add_u64 v[232:233], s[28:29], 0, v[130:131]
	ds_read_b128 v[194:197], v156 offset:32768
	ds_read_b128 v[198:201], v156 offset:33792
	ds_read_b128 v[202:205], v156 offset:34816
	ds_read_b128 v[206:209], v156 offset:35840
	ds_read_b128 v[210:213], v156 offset:36864
	ds_read_b128 v[214:217], v156 offset:37888
	ds_read_b128 v[218:221], v156 offset:38912
	ds_read_b128 v[222:225], v156 offset:39936
	global_load_lds_dwordx4 v[232:233], off
	v_lshl_add_u64 v[232:233], s[28:29], 0, v[134:135]
	s_mov_b32 m0, s42
	s_nop 0
	global_load_lds_dwordx4 v[232:233], off
	s_waitcnt vmcnt(8)
	s_waitcnt lgkmcnt(0)
	s_barrier
	s_setprio 1
	s_waitcnt lgkmcnt(0)
	v_mfma_f32_16x16x32_bf16 v[126:129], v[148:151], v[194:197], v[126:129]
	v_mfma_f32_16x16x32_bf16 v[122:125], v[164:167], v[194:197], v[122:125]
	v_mfma_f32_16x16x32_bf16 v[110:113], v[148:151], v[202:205], v[110:113]
	v_mfma_f32_16x16x32_bf16 v[106:109], v[164:167], v[202:205], v[106:109]
	v_mfma_f32_16x16x32_bf16 v[94:97], v[148:151], v[210:213], v[94:97]
	v_mfma_f32_16x16x32_bf16 v[90:93], v[164:167], v[210:213], v[90:93]
	v_mfma_f32_16x16x32_bf16 v[78:81], v[148:151], v[218:221], v[78:81]
	v_mfma_f32_16x16x32_bf16 v[74:77], v[164:167], v[218:221], v[74:77]
	v_mfma_f32_16x16x32_bf16 v[126:129], v[160:163], v[198:201], v[126:129]
	v_mfma_f32_16x16x32_bf16 v[122:125], v[168:171], v[198:201], v[122:125]
	v_mfma_f32_16x16x32_bf16 v[110:113], v[160:163], v[206:209], v[110:113]
	v_mfma_f32_16x16x32_bf16 v[106:109], v[168:171], v[206:209], v[106:109]
	v_mfma_f32_16x16x32_bf16 v[94:97], v[160:163], v[214:217], v[94:97]
	v_mfma_f32_16x16x32_bf16 v[90:93], v[168:171], v[214:217], v[90:93]
	v_mfma_f32_16x16x32_bf16 v[78:81], v[160:163], v[222:225], v[78:81]
	v_mfma_f32_16x16x32_bf16 v[74:77], v[168:171], v[222:225], v[74:77]
	v_mfma_f32_16x16x32_bf16 v[118:121], v[178:181], v[194:197], v[118:121]
	v_mfma_f32_16x16x32_bf16 v[114:117], v[186:189], v[194:197], v[114:117]
	v_mfma_f32_16x16x32_bf16 v[102:105], v[178:181], v[202:205], v[102:105]
	v_mfma_f32_16x16x32_bf16 v[98:101], v[186:189], v[202:205], v[98:101]
	v_mfma_f32_16x16x32_bf16 v[86:89], v[178:181], v[210:213], v[86:89]
	v_mfma_f32_16x16x32_bf16 v[82:85], v[186:189], v[210:213], v[82:85]
	v_mfma_f32_16x16x32_bf16 v[70:73], v[178:181], v[218:221], v[70:73]
	v_mfma_f32_16x16x32_bf16 v[66:69], v[186:189], v[218:221], v[66:69]
	v_mfma_f32_16x16x32_bf16 v[118:121], v[182:185], v[198:201], v[118:121]
	v_mfma_f32_16x16x32_bf16 v[114:117], v[190:193], v[198:201], v[114:117]
	v_mfma_f32_16x16x32_bf16 v[102:105], v[182:185], v[206:209], v[102:105]
	v_mfma_f32_16x16x32_bf16 v[98:101], v[190:193], v[206:209], v[98:101]
	v_mfma_f32_16x16x32_bf16 v[86:89], v[182:185], v[214:217], v[86:89]
	v_mfma_f32_16x16x32_bf16 v[82:85], v[190:193], v[214:217], v[82:85]
	v_mfma_f32_16x16x32_bf16 v[70:73], v[182:185], v[222:225], v[70:73]
	v_mfma_f32_16x16x32_bf16 v[66:69], v[190:193], v[222:225], v[66:69]
	s_setprio 0
	s_barrier
	s_add_i32 s28, s55, s38
	v_lshl_add_u64 v[172:173], v[172:173], 0, s[12:13]
	s_mov_b32 m0, s28
	ds_read_b128 v[194:197], v156 offset:49152
	ds_read_b128 v[198:201], v156 offset:50176
	ds_read_b128 v[202:205], v156 offset:51200
	ds_read_b128 v[206:209], v156 offset:52224
	ds_read_b128 v[210:213], v156 offset:53248
	ds_read_b128 v[214:217], v156 offset:54272
	ds_read_b128 v[218:221], v156 offset:55296
	ds_read_b128 v[222:225], v156 offset:56320
	global_load_lds_dwordx4 v[172:173], off
	s_add_i32 m0, s28, 0x2000
	s_add_u32 s28, s34, 0x40080
	v_lshl_add_u64 v[172:173], v[226:227], 0, s[12:13]
	s_addc_u32 s29, s35, 0
	s_add_i32 s34, s56, s38
	global_load_lds_dwordx4 v[172:173], off
	v_lshl_add_u64 v[172:173], s[28:29], 0, v[132:133]
	s_mov_b32 m0, s34
	s_nop 0
	global_load_lds_dwordx4 v[172:173], off
	v_lshl_add_u64 v[172:173], s[28:29], 0, v[136:137]
	s_add_i32 m0, s34, 0x2000
	s_nop 0
	global_load_lds_dwordx4 v[172:173], off
	v_lshl_add_u64 v[172:173], v[228:229], 0, s[12:13]
	s_mov_b32 m0, s44
	s_nop 0
	global_load_lds_dwordx4 v[172:173], off
	v_lshl_add_u64 v[172:173], v[230:231], 0, s[12:13]
	s_mov_b32 m0, s45
	s_nop 0
	global_load_lds_dwordx4 v[172:173], off
	s_waitcnt vmcnt(8)
	s_waitcnt lgkmcnt(0)
	s_barrier
	s_setprio 1
	s_waitcnt lgkmcnt(0)
	v_mfma_f32_16x16x32_bf16 v[62:65], v[148:151], v[194:197], v[62:65]
	v_mfma_f32_16x16x32_bf16 v[58:61], v[164:167], v[194:197], v[58:61]
	v_mfma_f32_16x16x32_bf16 v[46:49], v[148:151], v[202:205], v[46:49]
	v_mfma_f32_16x16x32_bf16 v[42:45], v[164:167], v[202:205], v[42:45]
	v_mfma_f32_16x16x32_bf16 v[30:33], v[148:151], v[210:213], v[30:33]
	v_mfma_f32_16x16x32_bf16 v[26:29], v[164:167], v[210:213], v[26:29]
	v_mfma_f32_16x16x32_bf16 v[14:17], v[148:151], v[218:221], v[14:17]
	v_mfma_f32_16x16x32_bf16 v[10:13], v[164:167], v[218:221], v[10:13]
	v_mfma_f32_16x16x32_bf16 v[62:65], v[160:163], v[198:201], v[62:65]
	v_mfma_f32_16x16x32_bf16 v[58:61], v[168:171], v[198:201], v[58:61]
	v_mfma_f32_16x16x32_bf16 v[46:49], v[160:163], v[206:209], v[46:49]
	v_mfma_f32_16x16x32_bf16 v[42:45], v[168:171], v[206:209], v[42:45]
	v_mfma_f32_16x16x32_bf16 v[30:33], v[160:163], v[214:217], v[30:33]
	v_mfma_f32_16x16x32_bf16 v[26:29], v[168:171], v[214:217], v[26:29]
	v_mfma_f32_16x16x32_bf16 v[14:17], v[160:163], v[222:225], v[14:17]
	v_mfma_f32_16x16x32_bf16 v[10:13], v[168:171], v[222:225], v[10:13]
	v_mfma_f32_16x16x32_bf16 v[54:57], v[178:181], v[194:197], v[54:57]
	v_mfma_f32_16x16x32_bf16 v[50:53], v[186:189], v[194:197], v[50:53]
	v_mfma_f32_16x16x32_bf16 v[38:41], v[178:181], v[202:205], v[38:41]
	v_mfma_f32_16x16x32_bf16 v[34:37], v[186:189], v[202:205], v[34:37]
	v_mfma_f32_16x16x32_bf16 v[22:25], v[178:181], v[210:213], v[22:25]
	v_mfma_f32_16x16x32_bf16 v[18:21], v[186:189], v[210:213], v[18:21]
	v_mfma_f32_16x16x32_bf16 v[6:9], v[178:181], v[218:221], v[6:9]
	v_mfma_f32_16x16x32_bf16 v[2:5], v[186:189], v[218:221], v[2:5]
	v_mfma_f32_16x16x32_bf16 v[54:57], v[182:185], v[198:201], v[54:57]
	v_mfma_f32_16x16x32_bf16 v[50:53], v[190:193], v[198:201], v[50:53]
	v_mfma_f32_16x16x32_bf16 v[38:41], v[182:185], v[206:209], v[38:41]
	v_mfma_f32_16x16x32_bf16 v[34:37], v[190:193], v[206:209], v[34:37]
	v_mfma_f32_16x16x32_bf16 v[22:25], v[182:185], v[214:217], v[22:25]
	v_mfma_f32_16x16x32_bf16 v[18:21], v[190:193], v[214:217], v[18:21]
	v_mfma_f32_16x16x32_bf16 v[6:9], v[182:185], v[222:225], v[6:9]
	v_mfma_f32_16x16x32_bf16 v[2:5], v[190:193], v[222:225], v[2:5]
	s_setprio 0
	s_barrier
	s_add_i32 s54, s54, 2
	s_add_u32 s52, s52, 0x100
	s_addc_u32 s53, s53, 0
	s_cmp_gt_u32 s54, 13
	s_mov_b64 s[28:29], s[30:31]
	s_cbranch_scc0 .LBB0_1323
	s_branch .Lpeel_exit_1323
.LBB0_1323:
	ds_read_b128 v[148:151], v154
	ds_read_b128 v[160:163], v154 offset:1024
	ds_read_b128 v[164:167], v154 offset:2048
	ds_read_b128 v[168:171], v154 offset:3072
	ds_read_b128 v[178:181], v155
	ds_read_b128 v[182:185], v155 offset:1024
	ds_read_b128 v[186:189], v155 offset:2048
	ds_read_b128 v[190:193], v155 offset:3072
	s_add_u32 s30, s28, 0x100
	s_addc_u32 s31, s29, 0
	s_cmp_eq_u32 s54, 12
	s_cselect_b32 s37, s23, s31
	s_cselect_b32 s36, s50, s30
	s_cselect_b32 s35, s21, s53
	s_cselect_b32 s34, s51, s52
	v_lshl_add_u64 v[172:173], s[28:29], 0, v[140:141]
	s_add_i32 m0, s39, 0xc000
	ds_read_b128 v[194:197], v156
	ds_read_b128 v[198:201], v156 offset:1024
	ds_read_b128 v[202:205], v156 offset:2048
	ds_read_b128 v[206:209], v156 offset:3072
	ds_read_b128 v[210:213], v156 offset:4096
	ds_read_b128 v[214:217], v156 offset:5120
	ds_read_b128 v[218:221], v156 offset:6144
	ds_read_b128 v[222:225], v156 offset:7168
	global_load_lds_dwordx4 v[172:173], off
	v_lshl_add_u64 v[172:173], s[28:29], 0, v[142:143]
	s_add_i32 m0, s39, 0xe000
	s_nop 0
	global_load_lds_dwordx4 v[172:173], off
	s_waitcnt vmcnt(8)
	s_waitcnt lgkmcnt(0)
	s_barrier
	s_setprio 1
	s_waitcnt lgkmcnt(0)
	v_mfma_f32_16x16x32_bf16 v[126:129], v[148:151], v[194:197], v[126:129]
	v_mfma_f32_16x16x32_bf16 v[122:125], v[164:167], v[194:197], v[122:125]
	v_mfma_f32_16x16x32_bf16 v[110:113], v[148:151], v[202:205], v[110:113]
	v_mfma_f32_16x16x32_bf16 v[106:109], v[164:167], v[202:205], v[106:109]
	v_mfma_f32_16x16x32_bf16 v[94:97], v[148:151], v[210:213], v[94:97]
	v_mfma_f32_16x16x32_bf16 v[90:93], v[164:167], v[210:213], v[90:93]
	v_mfma_f32_16x16x32_bf16 v[78:81], v[148:151], v[218:221], v[78:81]
	v_mfma_f32_16x16x32_bf16 v[74:77], v[164:167], v[218:221], v[74:77]
	v_mfma_f32_16x16x32_bf16 v[126:129], v[160:163], v[198:201], v[126:129]
	v_mfma_f32_16x16x32_bf16 v[122:125], v[168:171], v[198:201], v[122:125]
	v_mfma_f32_16x16x32_bf16 v[110:113], v[160:163], v[206:209], v[110:113]
	v_mfma_f32_16x16x32_bf16 v[106:109], v[168:171], v[206:209], v[106:109]
	v_mfma_f32_16x16x32_bf16 v[94:97], v[160:163], v[214:217], v[94:97]
	v_mfma_f32_16x16x32_bf16 v[90:93], v[168:171], v[214:217], v[90:93]
	v_mfma_f32_16x16x32_bf16 v[78:81], v[160:163], v[222:225], v[78:81]
	v_mfma_f32_16x16x32_bf16 v[74:77], v[168:171], v[222:225], v[74:77]
	v_mfma_f32_16x16x32_bf16 v[118:121], v[178:181], v[194:197], v[118:121]
	v_mfma_f32_16x16x32_bf16 v[114:117], v[186:189], v[194:197], v[114:117]
	v_mfma_f32_16x16x32_bf16 v[102:105], v[178:181], v[202:205], v[102:105]
	v_mfma_f32_16x16x32_bf16 v[98:101], v[186:189], v[202:205], v[98:101]
	v_mfma_f32_16x16x32_bf16 v[86:89], v[178:181], v[210:213], v[86:89]
	v_mfma_f32_16x16x32_bf16 v[82:85], v[186:189], v[210:213], v[82:85]
	v_mfma_f32_16x16x32_bf16 v[70:73], v[178:181], v[218:221], v[70:73]
	v_mfma_f32_16x16x32_bf16 v[66:69], v[186:189], v[218:221], v[66:69]
	v_mfma_f32_16x16x32_bf16 v[118:121], v[182:185], v[198:201], v[118:121]
	v_mfma_f32_16x16x32_bf16 v[114:117], v[190:193], v[198:201], v[114:117]
	v_mfma_f32_16x16x32_bf16 v[102:105], v[182:185], v[206:209], v[102:105]
	v_mfma_f32_16x16x32_bf16 v[98:101], v[190:193], v[206:209], v[98:101]
	v_mfma_f32_16x16x32_bf16 v[86:89], v[182:185], v[214:217], v[86:89]
	v_mfma_f32_16x16x32_bf16 v[82:85], v[190:193], v[214:217], v[82:85]
	v_mfma_f32_16x16x32_bf16 v[70:73], v[182:185], v[222:225], v[70:73]
	v_mfma_f32_16x16x32_bf16 v[66:69], v[190:193], v[222:225], v[66:69]
	s_setprio 0
	s_barrier
	s_add_i32 s28, s47, s38
	v_lshl_add_u64 v[172:173], s[34:35], 0, v[132:133]
	s_mov_b32 m0, s28
	ds_read_b128 v[194:197], v156 offset:16384
	ds_read_b128 v[198:201], v156 offset:17408
	ds_read_b128 v[202:205], v156 offset:18432
	ds_read_b128 v[206:209], v156 offset:19456
	ds_read_b128 v[210:213], v156 offset:20480
	ds_read_b128 v[214:217], v156 offset:21504
	ds_read_b128 v[218:221], v156 offset:22528
	ds_read_b128 v[222:225], v156 offset:23552
	global_load_lds_dwordx4 v[172:173], off
	s_add_i32 m0, s28, 0x2000
	s_add_u32 s28, s34, 0x40000
	v_lshl_add_u64 v[226:227], s[34:35], 0, v[136:137]
	s_addc_u32 s29, s35, 0
	s_add_i32 s55, s48, s38
	global_load_lds_dwordx4 v[226:227], off
	v_lshl_add_u64 v[228:229], s[28:29], 0, v[132:133]
	s_mov_b32 m0, s55
	v_lshl_add_u64 v[230:231], s[36:37], 0, v[134:135]
	global_load_lds_dwordx4 v[228:229], off
	v_lshl_add_u64 v[228:229], s[28:29], 0, v[136:137]
	s_add_i32 m0, s55, 0x2000
	s_nop 0
	global_load_lds_dwordx4 v[228:229], off
	v_lshl_add_u64 v[228:229], s[36:37], 0, v[130:131]
	s_mov_b32 m0, s39
	s_nop 0
	global_load_lds_dwordx4 v[228:229], off
	s_mov_b32 m0, s40
	s_nop 0
	global_load_lds_dwordx4 v[230:231], off
	s_waitcnt vmcnt(8)
	s_waitcnt lgkmcnt(0)
	s_barrier
	s_setprio 1
	s_waitcnt lgkmcnt(0)
	v_mfma_f32_16x16x32_bf16 v[62:65], v[148:151], v[194:197], v[62:65]
	v_mfma_f32_16x16x32_bf16 v[58:61], v[164:167], v[194:197], v[58:61]
	v_mfma_f32_16x16x32_bf16 v[46:49], v[148:151], v[202:205], v[46:49]
	v_mfma_f32_16x16x32_bf16 v[42:45], v[164:167], v[202:205], v[42:45]
	v_mfma_f32_16x16x32_bf16 v[30:33], v[148:151], v[210:213], v[30:33]
	v_mfma_f32_16x16x32_bf16 v[26:29], v[164:167], v[210:213], v[26:29]
	v_mfma_f32_16x16x32_bf16 v[14:17], v[148:151], v[218:221], v[14:17]
	v_mfma_f32_16x16x32_bf16 v[10:13], v[164:167], v[218:221], v[10:13]
	v_mfma_f32_16x16x32_bf16 v[62:65], v[160:163], v[198:201], v[62:65]
	v_mfma_f32_16x16x32_bf16 v[58:61], v[168:171], v[198:201], v[58:61]
	v_mfma_f32_16x16x32_bf16 v[46:49], v[160:163], v[206:209], v[46:49]
	v_mfma_f32_16x16x32_bf16 v[42:45], v[168:171], v[206:209], v[42:45]
	v_mfma_f32_16x16x32_bf16 v[30:33], v[160:163], v[214:217], v[30:33]
	v_mfma_f32_16x16x32_bf16 v[26:29], v[168:171], v[214:217], v[26:29]
	v_mfma_f32_16x16x32_bf16 v[14:17], v[160:163], v[222:225], v[14:17]
	v_mfma_f32_16x16x32_bf16 v[10:13], v[168:171], v[222:225], v[10:13]
	v_mfma_f32_16x16x32_bf16 v[54:57], v[178:181], v[194:197], v[54:57]
	v_mfma_f32_16x16x32_bf16 v[50:53], v[186:189], v[194:197], v[50:53]
	v_mfma_f32_16x16x32_bf16 v[38:41], v[178:181], v[202:205], v[38:41]
	v_mfma_f32_16x16x32_bf16 v[34:37], v[186:189], v[202:205], v[34:37]
	v_mfma_f32_16x16x32_bf16 v[22:25], v[178:181], v[210:213], v[22:25]
	v_mfma_f32_16x16x32_bf16 v[18:21], v[186:189], v[210:213], v[18:21]
	v_mfma_f32_16x16x32_bf16 v[6:9], v[178:181], v[218:221], v[6:9]
	v_mfma_f32_16x16x32_bf16 v[2:5], v[186:189], v[218:221], v[2:5]
	v_mfma_f32_16x16x32_bf16 v[54:57], v[182:185], v[198:201], v[54:57]
	v_mfma_f32_16x16x32_bf16 v[50:53], v[190:193], v[198:201], v[50:53]
	v_mfma_f32_16x16x32_bf16 v[38:41], v[182:185], v[206:209], v[38:41]
	v_mfma_f32_16x16x32_bf16 v[34:37], v[190:193], v[206:209], v[34:37]
	v_mfma_f32_16x16x32_bf16 v[22:25], v[182:185], v[214:217], v[22:25]
	v_mfma_f32_16x16x32_bf16 v[18:21], v[190:193], v[214:217], v[18:21]
	v_mfma_f32_16x16x32_bf16 v[6:9], v[182:185], v[222:225], v[6:9]
	v_mfma_f32_16x16x32_bf16 v[2:5], v[190:193], v[222:225], v[2:5]
	s_setprio 0
	s_barrier
	s_add_i32 s55, 0, 0x18000
	v_add_u32_e32 v138, s55, v152
	s_add_i32 s56, 0, 0x1c000
	ds_read_b128 v[148:151], v138
	ds_read_b128 v[160:163], v138 offset:1024
	ds_read_b128 v[164:167], v138 offset:2048
	ds_read_b128 v[168:171], v138 offset:3072
	v_add_u32_e32 v138, s56, v152
	ds_read_b128 v[178:181], v138
	ds_read_b128 v[182:185], v138 offset:1024
	ds_read_b128 v[186:189], v138 offset:2048
	ds_read_b128 v[190:193], v138 offset:3072
	s_add_u32 s28, s36, 0x40000
	s_addc_u32 s29, s37, 0
	s_mov_b32 m0, s41
	v_lshl_add_u64 v[232:233], s[28:29], 0, v[130:131]
	ds_read_b128 v[194:197], v156 offset:32768
	ds_read_b128 v[198:201], v156 offset:33792
	ds_read_b128 v[202:205], v156 offset:34816
	ds_read_b128 v[206:209], v156 offset:35840
	ds_read_b128 v[210:213], v156 offset:36864
	ds_read_b128 v[214:217], v156 offset:37888
	ds_read_b128 v[218:221], v156 offset:38912
	ds_read_b128 v[222:225], v156 offset:39936
	global_load_lds_dwordx4 v[232:233], off
	v_lshl_add_u64 v[232:233], s[28:29], 0, v[134:135]
	s_mov_b32 m0, s42
	s_nop 0
	global_load_lds_dwordx4 v[232:233], off
	s_waitcnt vmcnt(8)
	s_waitcnt lgkmcnt(0)
	s_barrier
	s_setprio 1
	s_waitcnt lgkmcnt(0)
	v_mfma_f32_16x16x32_bf16 v[126:129], v[148:151], v[194:197], v[126:129]
	v_mfma_f32_16x16x32_bf16 v[122:125], v[164:167], v[194:197], v[122:125]
	v_mfma_f32_16x16x32_bf16 v[110:113], v[148:151], v[202:205], v[110:113]
	v_mfma_f32_16x16x32_bf16 v[106:109], v[164:167], v[202:205], v[106:109]
	v_mfma_f32_16x16x32_bf16 v[94:97], v[148:151], v[210:213], v[94:97]
	v_mfma_f32_16x16x32_bf16 v[90:93], v[164:167], v[210:213], v[90:93]
	v_mfma_f32_16x16x32_bf16 v[78:81], v[148:151], v[218:221], v[78:81]
	v_mfma_f32_16x16x32_bf16 v[74:77], v[164:167], v[218:221], v[74:77]
	v_mfma_f32_16x16x32_bf16 v[126:129], v[160:163], v[198:201], v[126:129]
	v_mfma_f32_16x16x32_bf16 v[122:125], v[168:171], v[198:201], v[122:125]
	v_mfma_f32_16x16x32_bf16 v[110:113], v[160:163], v[206:209], v[110:113]
	v_mfma_f32_16x16x32_bf16 v[106:109], v[168:171], v[206:209], v[106:109]
	v_mfma_f32_16x16x32_bf16 v[94:97], v[160:163], v[214:217], v[94:97]
	v_mfma_f32_16x16x32_bf16 v[90:93], v[168:171], v[214:217], v[90:93]
	v_mfma_f32_16x16x32_bf16 v[78:81], v[160:163], v[222:225], v[78:81]
	v_mfma_f32_16x16x32_bf16 v[74:77], v[168:171], v[222:225], v[74:77]
	v_mfma_f32_16x16x32_bf16 v[118:121], v[178:181], v[194:197], v[118:121]
	v_mfma_f32_16x16x32_bf16 v[114:117], v[186:189], v[194:197], v[114:117]
	v_mfma_f32_16x16x32_bf16 v[102:105], v[178:181], v[202:205], v[102:105]
	v_mfma_f32_16x16x32_bf16 v[98:101], v[186:189], v[202:205], v[98:101]
	v_mfma_f32_16x16x32_bf16 v[86:89], v[178:181], v[210:213], v[86:89]
	v_mfma_f32_16x16x32_bf16 v[82:85], v[186:189], v[210:213], v[82:85]
	v_mfma_f32_16x16x32_bf16 v[70:73], v[178:181], v[218:221], v[70:73]
	v_mfma_f32_16x16x32_bf16 v[66:69], v[186:189], v[218:221], v[66:69]
	v_mfma_f32_16x16x32_bf16 v[118:121], v[182:185], v[198:201], v[118:121]
	v_mfma_f32_16x16x32_bf16 v[114:117], v[190:193], v[198:201], v[114:117]
	v_mfma_f32_16x16x32_bf16 v[102:105], v[182:185], v[206:209], v[102:105]
	v_mfma_f32_16x16x32_bf16 v[98:101], v[190:193], v[206:209], v[98:101]
	v_mfma_f32_16x16x32_bf16 v[86:89], v[182:185], v[214:217], v[86:89]
	v_mfma_f32_16x16x32_bf16 v[82:85], v[190:193], v[214:217], v[82:85]
	v_mfma_f32_16x16x32_bf16 v[70:73], v[182:185], v[222:225], v[70:73]
	v_mfma_f32_16x16x32_bf16 v[66:69], v[190:193], v[222:225], v[66:69]
	s_setprio 0
	s_barrier
	s_add_i32 s28, s55, s38
	v_lshl_add_u64 v[172:173], v[172:173], 0, s[12:13]
	s_mov_b32 m0, s28
	ds_read_b128 v[194:197], v156 offset:49152
	ds_read_b128 v[198:201], v156 offset:50176
	ds_read_b128 v[202:205], v156 offset:51200
	ds_read_b128 v[206:209], v156 offset:52224
	ds_read_b128 v[210:213], v156 offset:53248
	ds_read_b128 v[214:217], v156 offset:54272
	ds_read_b128 v[218:221], v156 offset:55296
	ds_read_b128 v[222:225], v156 offset:56320
	global_load_lds_dwordx4 v[172:173], off
	s_add_i32 m0, s28, 0x2000
	s_add_u32 s28, s34, 0x40080
	v_lshl_add_u64 v[172:173], v[226:227], 0, s[12:13]
	s_addc_u32 s29, s35, 0
	s_add_i32 s34, s56, s38
	global_load_lds_dwordx4 v[172:173], off
	v_lshl_add_u64 v[172:173], s[28:29], 0, v[132:133]
	s_mov_b32 m0, s34
	s_nop 0
	global_load_lds_dwordx4 v[172:173], off
	v_lshl_add_u64 v[172:173], s[28:29], 0, v[136:137]
	s_add_i32 m0, s34, 0x2000
	s_nop 0
	global_load_lds_dwordx4 v[172:173], off
	v_lshl_add_u64 v[172:173], v[228:229], 0, s[12:13]
	s_mov_b32 m0, s44
	s_nop 0
	global_load_lds_dwordx4 v[172:173], off
	v_lshl_add_u64 v[172:173], v[230:231], 0, s[12:13]
	s_mov_b32 m0, s45
	s_nop 0
	global_load_lds_dwordx4 v[172:173], off
	s_waitcnt vmcnt(8)
	s_waitcnt lgkmcnt(0)
	s_barrier
	s_setprio 1
	s_waitcnt lgkmcnt(0)
	v_mfma_f32_16x16x32_bf16 v[62:65], v[148:151], v[194:197], v[62:65]
	v_mfma_f32_16x16x32_bf16 v[58:61], v[164:167], v[194:197], v[58:61]
	v_mfma_f32_16x16x32_bf16 v[46:49], v[148:151], v[202:205], v[46:49]
	v_mfma_f32_16x16x32_bf16 v[42:45], v[164:167], v[202:205], v[42:45]
	v_mfma_f32_16x16x32_bf16 v[30:33], v[148:151], v[210:213], v[30:33]
	v_mfma_f32_16x16x32_bf16 v[26:29], v[164:167], v[210:213], v[26:29]
	v_mfma_f32_16x16x32_bf16 v[14:17], v[148:151], v[218:221], v[14:17]
	v_mfma_f32_16x16x32_bf16 v[10:13], v[164:167], v[218:221], v[10:13]
	v_mfma_f32_16x16x32_bf16 v[62:65], v[160:163], v[198:201], v[62:65]
	v_mfma_f32_16x16x32_bf16 v[58:61], v[168:171], v[198:201], v[58:61]
	v_mfma_f32_16x16x32_bf16 v[46:49], v[160:163], v[206:209], v[46:49]
	v_mfma_f32_16x16x32_bf16 v[42:45], v[168:171], v[206:209], v[42:45]
	v_mfma_f32_16x16x32_bf16 v[30:33], v[160:163], v[214:217], v[30:33]
	v_mfma_f32_16x16x32_bf16 v[26:29], v[168:171], v[214:217], v[26:29]
	v_mfma_f32_16x16x32_bf16 v[14:17], v[160:163], v[222:225], v[14:17]
	v_mfma_f32_16x16x32_bf16 v[10:13], v[168:171], v[222:225], v[10:13]
	v_mfma_f32_16x16x32_bf16 v[54:57], v[178:181], v[194:197], v[54:57]
	v_mfma_f32_16x16x32_bf16 v[50:53], v[186:189], v[194:197], v[50:53]
	v_mfma_f32_16x16x32_bf16 v[38:41], v[178:181], v[202:205], v[38:41]
	v_mfma_f32_16x16x32_bf16 v[34:37], v[186:189], v[202:205], v[34:37]
	v_mfma_f32_16x16x32_bf16 v[22:25], v[178:181], v[210:213], v[22:25]
	v_mfma_f32_16x16x32_bf16 v[18:21], v[186:189], v[210:213], v[18:21]
	v_mfma_f32_16x16x32_bf16 v[6:9], v[178:181], v[218:221], v[6:9]
	v_mfma_f32_16x16x32_bf16 v[2:5], v[186:189], v[218:221], v[2:5]
	v_mfma_f32_16x16x32_bf16 v[54:57], v[182:185], v[198:201], v[54:57]
	v_mfma_f32_16x16x32_bf16 v[50:53], v[190:193], v[198:201], v[50:53]
	v_mfma_f32_16x16x32_bf16 v[38:41], v[182:185], v[206:209], v[38:41]
	v_mfma_f32_16x16x32_bf16 v[34:37], v[190:193], v[206:209], v[34:37]
	v_mfma_f32_16x16x32_bf16 v[22:25], v[182:185], v[214:217], v[22:25]
	v_mfma_f32_16x16x32_bf16 v[18:21], v[190:193], v[214:217], v[18:21]
	v_mfma_f32_16x16x32_bf16 v[6:9], v[182:185], v[222:225], v[6:9]
	v_mfma_f32_16x16x32_bf16 v[2:5], v[190:193], v[222:225], v[2:5]
	s_setprio 0
	s_barrier
	s_add_i32 s54, s54, 2
	s_add_u32 s52, s52, 0x100
	s_addc_u32 s53, s53, 0
	s_cmp_gt_u32 s54, 13
	s_mov_b64 s[28:29], s[30:31]
	s_cbranch_scc0 .LBB0_1323

.LBB0_1495:
	s_ashr_i32 s25, s24, 31
	s_lshl_b64 s[26:27], s[24:25], 19
	s_add_u32 s26, s3, s26
	s_addc_u32 s27, s14, s27
	s_and_b64 s[28:29], s[4:5], exec
	s_cselect_b32 s25, s27, s35
	s_cselect_b32 s31, s26, s34
	s_ashr_i32 s23, s22, 31
	s_lshl_b64 s[28:29], s[22:23], 19
	s_add_u32 s28, s15, s28
	s_addc_u32 s29, s16, s29
	s_and_b64 s[38:39], s[4:5], exec
	s_cselect_b32 s23, s29, s37
	s_cselect_b32 s54, s28, s36
	s_add_u32 s55, s36, 0x100
	s_addc_u32 s56, s37, 0
	s_mov_b32 s57, -2
	s_waitcnt lgkmcnt(0)
	ds_read_b128 v[146:149], v153
	ds_read_b128 v[158:161], v153 offset:1024
	ds_read_b128 v[162:165], v153 offset:2048
	ds_read_b128 v[166:169], v153 offset:3072
	ds_read_b128 v[170:173], v154
	ds_read_b128 v[178:181], v154 offset:1024
	ds_read_b128 v[182:185], v154 offset:2048
	ds_read_b128 v[186:189], v154 offset:3072
	s_add_u32 s36, s34, 0x100
	s_addc_u32 s37, s35, 0
	s_cmp_eq_u32 s57, 12
	s_cselect_b32 s41, s25, s37
	s_cselect_b32 s40, s31, s36
	s_cselect_b32 s39, s23, s56
	s_cselect_b32 s38, s54, s55
	v_lshl_add_u64 v[222:223], s[34:35], 0, v[138:139]
	s_add_i32 m0, s42, 0xc000
	ds_read_b128 v[190:193], v155
	ds_read_b128 v[194:197], v155 offset:1024
	ds_read_b128 v[198:201], v155 offset:2048
	ds_read_b128 v[202:205], v155 offset:3072
	ds_read_b128 v[206:209], v155 offset:4096
	ds_read_b128 v[210:213], v155 offset:5120
	ds_read_b128 v[214:217], v155 offset:6144
	ds_read_b128 v[218:221], v155 offset:7168
	global_load_lds_dwordx4 v[222:223], off
	v_lshl_add_u64 v[222:223], s[34:35], 0, v[140:141]
	s_add_i32 m0, s42, 0xe000
	s_nop 0
	global_load_lds_dwordx4 v[222:223], off
	s_waitcnt vmcnt(8)
	s_waitcnt lgkmcnt(0)
	s_barrier
	s_setprio 1
	s_waitcnt lgkmcnt(0)
	v_mfma_f32_16x16x32_bf16 v[126:129], v[146:149], v[190:193], 0
	v_mfma_f32_16x16x32_bf16 v[122:125], v[162:165], v[190:193], 0
	v_mfma_f32_16x16x32_bf16 v[110:113], v[146:149], v[198:201], 0
	v_mfma_f32_16x16x32_bf16 v[106:109], v[162:165], v[198:201], 0
	v_mfma_f32_16x16x32_bf16 v[94:97], v[146:149], v[206:209], 0
	v_mfma_f32_16x16x32_bf16 v[90:93], v[162:165], v[206:209], 0
	v_mfma_f32_16x16x32_bf16 v[78:81], v[146:149], v[214:217], 0
	v_mfma_f32_16x16x32_bf16 v[74:77], v[162:165], v[214:217], 0
	v_mfma_f32_16x16x32_bf16 v[126:129], v[158:161], v[194:197], v[126:129]
	v_mfma_f32_16x16x32_bf16 v[122:125], v[166:169], v[194:197], v[122:125]
	v_mfma_f32_16x16x32_bf16 v[110:113], v[158:161], v[202:205], v[110:113]
	v_mfma_f32_16x16x32_bf16 v[106:109], v[166:169], v[202:205], v[106:109]
	v_mfma_f32_16x16x32_bf16 v[94:97], v[158:161], v[210:213], v[94:97]
	v_mfma_f32_16x16x32_bf16 v[90:93], v[166:169], v[210:213], v[90:93]
	v_mfma_f32_16x16x32_bf16 v[78:81], v[158:161], v[218:221], v[78:81]
	v_mfma_f32_16x16x32_bf16 v[74:77], v[166:169], v[218:221], v[74:77]
	v_mfma_f32_16x16x32_bf16 v[118:121], v[170:173], v[190:193], 0
	v_mfma_f32_16x16x32_bf16 v[114:117], v[182:185], v[190:193], 0
	v_mfma_f32_16x16x32_bf16 v[102:105], v[170:173], v[198:201], 0
	v_mfma_f32_16x16x32_bf16 v[98:101], v[182:185], v[198:201], 0
	v_mfma_f32_16x16x32_bf16 v[86:89], v[170:173], v[206:209], 0
	v_mfma_f32_16x16x32_bf16 v[82:85], v[182:185], v[206:209], 0
	v_mfma_f32_16x16x32_bf16 v[70:73], v[170:173], v[214:217], 0
	v_mfma_f32_16x16x32_bf16 v[66:69], v[182:185], v[214:217], 0
	v_mfma_f32_16x16x32_bf16 v[118:121], v[178:181], v[194:197], v[118:121]
	v_mfma_f32_16x16x32_bf16 v[114:117], v[186:189], v[194:197], v[114:117]
	v_mfma_f32_16x16x32_bf16 v[102:105], v[178:181], v[202:205], v[102:105]
	v_mfma_f32_16x16x32_bf16 v[98:101], v[186:189], v[202:205], v[98:101]
	v_mfma_f32_16x16x32_bf16 v[86:89], v[178:181], v[210:213], v[86:89]
	v_mfma_f32_16x16x32_bf16 v[82:85], v[186:189], v[210:213], v[82:85]
	v_mfma_f32_16x16x32_bf16 v[70:73], v[178:181], v[218:221], v[70:73]
	v_mfma_f32_16x16x32_bf16 v[66:69], v[186:189], v[218:221], v[66:69]
	s_setprio 0
	s_barrier
	s_add_i32 s34, s51, s17
	v_lshl_add_u64 v[222:223], s[38:39], 0, v[132:133]
	s_mov_b32 m0, s34
	ds_read_b128 v[190:193], v155 offset:16384
	ds_read_b128 v[194:197], v155 offset:17408
	ds_read_b128 v[198:201], v155 offset:18432
	ds_read_b128 v[202:205], v155 offset:19456
	ds_read_b128 v[206:209], v155 offset:20480
	ds_read_b128 v[210:213], v155 offset:21504
	ds_read_b128 v[214:217], v155 offset:22528
	ds_read_b128 v[218:221], v155 offset:23552
	global_load_lds_dwordx4 v[222:223], off
	s_add_i32 m0, s34, 0x2000
	s_add_u32 s34, s38, 0x40000
	v_lshl_add_u64 v[224:225], s[38:39], 0, v[136:137]
	s_addc_u32 s35, s39, 0
	s_add_i32 s58, s52, s17
	global_load_lds_dwordx4 v[224:225], off
	v_lshl_add_u64 v[226:227], s[34:35], 0, v[132:133]
	s_mov_b32 m0, s58
	v_lshl_add_u64 v[228:229], s[40:41], 0, v[134:135]
	global_load_lds_dwordx4 v[226:227], off
	v_lshl_add_u64 v[226:227], s[34:35], 0, v[136:137]
	s_add_i32 m0, s58, 0x2000
	s_nop 0
	global_load_lds_dwordx4 v[226:227], off
	v_lshl_add_u64 v[226:227], s[40:41], 0, v[130:131]
	s_mov_b32 m0, s42
	s_nop 0
	global_load_lds_dwordx4 v[226:227], off
	s_mov_b32 m0, s43
	s_nop 0
	global_load_lds_dwordx4 v[228:229], off
	s_waitcnt vmcnt(8)
	s_waitcnt lgkmcnt(0)
	s_barrier
	s_setprio 1
	s_waitcnt lgkmcnt(0)
	v_mfma_f32_16x16x32_bf16 v[62:65], v[146:149], v[190:193], 0
	v_mfma_f32_16x16x32_bf16 v[58:61], v[162:165], v[190:193], 0
	v_mfma_f32_16x16x32_bf16 v[46:49], v[146:149], v[198:201], 0
	v_mfma_f32_16x16x32_bf16 v[42:45], v[162:165], v[198:201], 0
	v_mfma_f32_16x16x32_bf16 v[30:33], v[146:149], v[206:209], 0
	v_mfma_f32_16x16x32_bf16 v[26:29], v[162:165], v[206:209], 0
	v_mfma_f32_16x16x32_bf16 v[14:17], v[146:149], v[214:217], 0
	v_mfma_f32_16x16x32_bf16 v[10:13], v[162:165], v[214:217], 0
	v_mfma_f32_16x16x32_bf16 v[62:65], v[158:161], v[194:197], v[62:65]
	v_mfma_f32_16x16x32_bf16 v[58:61], v[166:169], v[194:197], v[58:61]
	v_mfma_f32_16x16x32_bf16 v[46:49], v[158:161], v[202:205], v[46:49]
	v_mfma_f32_16x16x32_bf16 v[42:45], v[166:169], v[202:205], v[42:45]
	v_mfma_f32_16x16x32_bf16 v[30:33], v[158:161], v[210:213], v[30:33]
	v_mfma_f32_16x16x32_bf16 v[26:29], v[166:169], v[210:213], v[26:29]
	v_mfma_f32_16x16x32_bf16 v[14:17], v[158:161], v[218:221], v[14:17]
	v_mfma_f32_16x16x32_bf16 v[10:13], v[166:169], v[218:221], v[10:13]
	v_mfma_f32_16x16x32_bf16 v[54:57], v[170:173], v[190:193], 0
	v_mfma_f32_16x16x32_bf16 v[50:53], v[182:185], v[190:193], 0
	v_mfma_f32_16x16x32_bf16 v[38:41], v[170:173], v[198:201], 0
	v_mfma_f32_16x16x32_bf16 v[34:37], v[182:185], v[198:201], 0
	v_mfma_f32_16x16x32_bf16 v[22:25], v[170:173], v[206:209], 0
	v_mfma_f32_16x16x32_bf16 v[18:21], v[182:185], v[206:209], 0
	v_mfma_f32_16x16x32_bf16 v[6:9], v[170:173], v[214:217], 0
	v_mfma_f32_16x16x32_bf16 v[2:5], v[182:185], v[214:217], 0
	v_mfma_f32_16x16x32_bf16 v[54:57], v[178:181], v[194:197], v[54:57]
	v_mfma_f32_16x16x32_bf16 v[50:53], v[186:189], v[194:197], v[50:53]
	v_mfma_f32_16x16x32_bf16 v[38:41], v[178:181], v[202:205], v[38:41]
	v_mfma_f32_16x16x32_bf16 v[34:37], v[186:189], v[202:205], v[34:37]
	v_mfma_f32_16x16x32_bf16 v[22:25], v[178:181], v[210:213], v[22:25]
	v_mfma_f32_16x16x32_bf16 v[18:21], v[186:189], v[210:213], v[18:21]
	v_mfma_f32_16x16x32_bf16 v[6:9], v[178:181], v[218:221], v[6:9]
	v_mfma_f32_16x16x32_bf16 v[2:5], v[186:189], v[218:221], v[2:5]
	s_setprio 0
	s_barrier
	s_add_i32 s58, 0, 0x18000
	v_add_u32_e32 v157, s58, v151
	s_add_i32 s59, 0, 0x1c000
	ds_read_b128 v[146:149], v157
	ds_read_b128 v[158:161], v157 offset:1024
	ds_read_b128 v[162:165], v157 offset:2048
	ds_read_b128 v[166:169], v157 offset:3072
	v_add_u32_e32 v157, s59, v151
	ds_read_b128 v[170:173], v157
	ds_read_b128 v[178:181], v157 offset:1024
	ds_read_b128 v[182:185], v157 offset:2048
	ds_read_b128 v[186:189], v157 offset:3072
	s_add_u32 s34, s40, 0x40000
	s_addc_u32 s35, s41, 0
	s_mov_b32 m0, s44
	v_lshl_add_u64 v[230:231], s[34:35], 0, v[130:131]
	ds_read_b128 v[190:193], v155 offset:32768
	ds_read_b128 v[194:197], v155 offset:33792
	ds_read_b128 v[198:201], v155 offset:34816
	ds_read_b128 v[202:205], v155 offset:35840
	ds_read_b128 v[206:209], v155 offset:36864
	ds_read_b128 v[210:213], v155 offset:37888
	ds_read_b128 v[214:217], v155 offset:38912
	ds_read_b128 v[218:221], v155 offset:39936
	global_load_lds_dwordx4 v[230:231], off
	v_lshl_add_u64 v[230:231], s[34:35], 0, v[134:135]
	s_mov_b32 m0, s45
	s_nop 0
	global_load_lds_dwordx4 v[230:231], off
	s_waitcnt vmcnt(8)
	s_waitcnt lgkmcnt(0)
	s_barrier
	s_setprio 1
	s_waitcnt lgkmcnt(0)
	v_mfma_f32_16x16x32_bf16 v[126:129], v[146:149], v[190:193], v[126:129]
	v_mfma_f32_16x16x32_bf16 v[122:125], v[162:165], v[190:193], v[122:125]
	v_mfma_f32_16x16x32_bf16 v[110:113], v[146:149], v[198:201], v[110:113]
	v_mfma_f32_16x16x32_bf16 v[106:109], v[162:165], v[198:201], v[106:109]
	v_mfma_f32_16x16x32_bf16 v[94:97], v[146:149], v[206:209], v[94:97]
	v_mfma_f32_16x16x32_bf16 v[90:93], v[162:165], v[206:209], v[90:93]
	v_mfma_f32_16x16x32_bf16 v[78:81], v[146:149], v[214:217], v[78:81]
	v_mfma_f32_16x16x32_bf16 v[74:77], v[162:165], v[214:217], v[74:77]
	v_mfma_f32_16x16x32_bf16 v[126:129], v[158:161], v[194:197], v[126:129]
	v_mfma_f32_16x16x32_bf16 v[122:125], v[166:169], v[194:197], v[122:125]
	v_mfma_f32_16x16x32_bf16 v[110:113], v[158:161], v[202:205], v[110:113]
	v_mfma_f32_16x16x32_bf16 v[106:109], v[166:169], v[202:205], v[106:109]
	v_mfma_f32_16x16x32_bf16 v[94:97], v[158:161], v[210:213], v[94:97]
	v_mfma_f32_16x16x32_bf16 v[90:93], v[166:169], v[210:213], v[90:93]
	v_mfma_f32_16x16x32_bf16 v[78:81], v[158:161], v[218:221], v[78:81]
	v_mfma_f32_16x16x32_bf16 v[74:77], v[166:169], v[218:221], v[74:77]
	v_mfma_f32_16x16x32_bf16 v[118:121], v[170:173], v[190:193], v[118:121]
	v_mfma_f32_16x16x32_bf16 v[114:117], v[182:185], v[190:193], v[114:117]
	v_mfma_f32_16x16x32_bf16 v[102:105], v[170:173], v[198:201], v[102:105]
	v_mfma_f32_16x16x32_bf16 v[98:101], v[182:185], v[198:201], v[98:101]
	v_mfma_f32_16x16x32_bf16 v[86:89], v[170:173], v[206:209], v[86:89]
	v_mfma_f32_16x16x32_bf16 v[82:85], v[182:185], v[206:209], v[82:85]
	v_mfma_f32_16x16x32_bf16 v[70:73], v[170:173], v[214:217], v[70:73]
	v_mfma_f32_16x16x32_bf16 v[66:69], v[182:185], v[214:217], v[66:69]
	v_mfma_f32_16x16x32_bf16 v[118:121], v[178:181], v[194:197], v[118:121]
	v_mfma_f32_16x16x32_bf16 v[114:117], v[186:189], v[194:197], v[114:117]
	v_mfma_f32_16x16x32_bf16 v[102:105], v[178:181], v[202:205], v[102:105]
	v_mfma_f32_16x16x32_bf16 v[98:101], v[186:189], v[202:205], v[98:101]
	v_mfma_f32_16x16x32_bf16 v[86:89], v[178:181], v[210:213], v[86:89]
	v_mfma_f32_16x16x32_bf16 v[82:85], v[186:189], v[210:213], v[82:85]
	v_mfma_f32_16x16x32_bf16 v[70:73], v[178:181], v[218:221], v[70:73]
	v_mfma_f32_16x16x32_bf16 v[66:69], v[186:189], v[218:221], v[66:69]
	s_setprio 0
	s_barrier
	s_add_i32 s34, s58, s17
	v_lshl_add_u64 v[222:223], v[222:223], 0, s[18:19]
	s_mov_b32 m0, s34
	ds_read_b128 v[190:193], v155 offset:49152
	ds_read_b128 v[194:197], v155 offset:50176
	ds_read_b128 v[198:201], v155 offset:51200
	ds_read_b128 v[202:205], v155 offset:52224
	ds_read_b128 v[206:209], v155 offset:53248
	ds_read_b128 v[210:213], v155 offset:54272
	ds_read_b128 v[214:217], v155 offset:55296
	ds_read_b128 v[218:221], v155 offset:56320
	global_load_lds_dwordx4 v[222:223], off
	s_add_i32 m0, s34, 0x2000
	s_add_u32 s34, s38, 0x40080
	v_lshl_add_u64 v[222:223], v[224:225], 0, s[18:19]
	s_addc_u32 s35, s39, 0
	s_add_i32 s38, s59, s17
	global_load_lds_dwordx4 v[222:223], off
	v_lshl_add_u64 v[222:223], s[34:35], 0, v[132:133]
	s_mov_b32 m0, s38
	s_nop 0
	global_load_lds_dwordx4 v[222:223], off
	v_lshl_add_u64 v[222:223], s[34:35], 0, v[136:137]
	s_add_i32 m0, s38, 0x2000
	s_nop 0
	global_load_lds_dwordx4 v[222:223], off
	v_lshl_add_u64 v[222:223], v[226:227], 0, s[18:19]
	s_mov_b32 m0, s47
	s_nop 0
	global_load_lds_dwordx4 v[222:223], off
	v_lshl_add_u64 v[222:223], v[228:229], 0, s[18:19]
	s_mov_b32 m0, s48
	s_nop 0
	global_load_lds_dwordx4 v[222:223], off
	s_waitcnt vmcnt(8)
	s_waitcnt lgkmcnt(0)
	s_barrier
	s_setprio 1
	s_waitcnt lgkmcnt(0)
	v_mfma_f32_16x16x32_bf16 v[62:65], v[146:149], v[190:193], v[62:65]
	v_mfma_f32_16x16x32_bf16 v[58:61], v[162:165], v[190:193], v[58:61]
	v_mfma_f32_16x16x32_bf16 v[46:49], v[146:149], v[198:201], v[46:49]
	v_mfma_f32_16x16x32_bf16 v[42:45], v[162:165], v[198:201], v[42:45]
	v_mfma_f32_16x16x32_bf16 v[30:33], v[146:149], v[206:209], v[30:33]
	v_mfma_f32_16x16x32_bf16 v[26:29], v[162:165], v[206:209], v[26:29]
	v_mfma_f32_16x16x32_bf16 v[14:17], v[146:149], v[214:217], v[14:17]
	v_mfma_f32_16x16x32_bf16 v[10:13], v[162:165], v[214:217], v[10:13]
	v_mfma_f32_16x16x32_bf16 v[62:65], v[158:161], v[194:197], v[62:65]
	v_mfma_f32_16x16x32_bf16 v[58:61], v[166:169], v[194:197], v[58:61]
	v_mfma_f32_16x16x32_bf16 v[46:49], v[158:161], v[202:205], v[46:49]
	v_mfma_f32_16x16x32_bf16 v[42:45], v[166:169], v[202:205], v[42:45]
	v_mfma_f32_16x16x32_bf16 v[30:33], v[158:161], v[210:213], v[30:33]
	v_mfma_f32_16x16x32_bf16 v[26:29], v[166:169], v[210:213], v[26:29]
	v_mfma_f32_16x16x32_bf16 v[14:17], v[158:161], v[218:221], v[14:17]
	v_mfma_f32_16x16x32_bf16 v[10:13], v[166:169], v[218:221], v[10:13]
	v_mfma_f32_16x16x32_bf16 v[54:57], v[170:173], v[190:193], v[54:57]
	v_mfma_f32_16x16x32_bf16 v[50:53], v[182:185], v[190:193], v[50:53]
	v_mfma_f32_16x16x32_bf16 v[38:41], v[170:173], v[198:201], v[38:41]
	v_mfma_f32_16x16x32_bf16 v[34:37], v[182:185], v[198:201], v[34:37]
	v_mfma_f32_16x16x32_bf16 v[22:25], v[170:173], v[206:209], v[22:25]
	v_mfma_f32_16x16x32_bf16 v[18:21], v[182:185], v[206:209], v[18:21]
	v_mfma_f32_16x16x32_bf16 v[6:9], v[170:173], v[214:217], v[6:9]
	v_mfma_f32_16x16x32_bf16 v[2:5], v[182:185], v[214:217], v[2:5]
	v_mfma_f32_16x16x32_bf16 v[54:57], v[178:181], v[194:197], v[54:57]
	v_mfma_f32_16x16x32_bf16 v[50:53], v[186:189], v[194:197], v[50:53]
	v_mfma_f32_16x16x32_bf16 v[38:41], v[178:181], v[202:205], v[38:41]
	v_mfma_f32_16x16x32_bf16 v[34:37], v[186:189], v[202:205], v[34:37]
	v_mfma_f32_16x16x32_bf16 v[22:25], v[178:181], v[210:213], v[22:25]
	v_mfma_f32_16x16x32_bf16 v[18:21], v[186:189], v[210:213], v[18:21]
	v_mfma_f32_16x16x32_bf16 v[6:9], v[178:181], v[218:221], v[6:9]
	v_mfma_f32_16x16x32_bf16 v[2:5], v[186:189], v[218:221], v[2:5]
	s_setprio 0
	s_barrier
	s_add_i32 s57, s57, 2
	s_add_u32 s55, s55, 0x100
	s_addc_u32 s56, s56, 0
	s_cmp_gt_u32 s57, 13
	s_mov_b64 s[34:35], s[36:37]
	s_cbranch_scc0 .LBB0_1496
	s_branch .Lpeel_exit_1496
.LBB0_1496:
	ds_read_b128 v[146:149], v153
	ds_read_b128 v[158:161], v153 offset:1024
	ds_read_b128 v[162:165], v153 offset:2048
	ds_read_b128 v[166:169], v153 offset:3072
	ds_read_b128 v[170:173], v154
	ds_read_b128 v[178:181], v154 offset:1024
	ds_read_b128 v[182:185], v154 offset:2048
	ds_read_b128 v[186:189], v154 offset:3072
	s_add_u32 s36, s34, 0x100
	s_addc_u32 s37, s35, 0
	s_cmp_eq_u32 s57, 12
	s_cselect_b32 s41, s25, s37
	s_cselect_b32 s40, s31, s36
	s_cselect_b32 s39, s23, s56
	s_cselect_b32 s38, s54, s55
	v_lshl_add_u64 v[222:223], s[34:35], 0, v[138:139]
	s_add_i32 m0, s42, 0xc000
	ds_read_b128 v[190:193], v155
	ds_read_b128 v[194:197], v155 offset:1024
	ds_read_b128 v[198:201], v155 offset:2048
	ds_read_b128 v[202:205], v155 offset:3072
	ds_read_b128 v[206:209], v155 offset:4096
	ds_read_b128 v[210:213], v155 offset:5120
	ds_read_b128 v[214:217], v155 offset:6144
	ds_read_b128 v[218:221], v155 offset:7168
	global_load_lds_dwordx4 v[222:223], off
	v_lshl_add_u64 v[222:223], s[34:35], 0, v[140:141]
	s_add_i32 m0, s42, 0xe000
	s_nop 0
	global_load_lds_dwordx4 v[222:223], off
	s_waitcnt vmcnt(8)
	s_waitcnt lgkmcnt(0)
	s_barrier
	s_setprio 1
	s_waitcnt lgkmcnt(0)
	v_mfma_f32_16x16x32_bf16 v[126:129], v[146:149], v[190:193], v[126:129]
	v_mfma_f32_16x16x32_bf16 v[122:125], v[162:165], v[190:193], v[122:125]
	v_mfma_f32_16x16x32_bf16 v[110:113], v[146:149], v[198:201], v[110:113]
	v_mfma_f32_16x16x32_bf16 v[106:109], v[162:165], v[198:201], v[106:109]
	v_mfma_f32_16x16x32_bf16 v[94:97], v[146:149], v[206:209], v[94:97]
	v_mfma_f32_16x16x32_bf16 v[90:93], v[162:165], v[206:209], v[90:93]
	v_mfma_f32_16x16x32_bf16 v[78:81], v[146:149], v[214:217], v[78:81]
	v_mfma_f32_16x16x32_bf16 v[74:77], v[162:165], v[214:217], v[74:77]
	v_mfma_f32_16x16x32_bf16 v[126:129], v[158:161], v[194:197], v[126:129]
	v_mfma_f32_16x16x32_bf16 v[122:125], v[166:169], v[194:197], v[122:125]
	v_mfma_f32_16x16x32_bf16 v[110:113], v[158:161], v[202:205], v[110:113]
	v_mfma_f32_16x16x32_bf16 v[106:109], v[166:169], v[202:205], v[106:109]
	v_mfma_f32_16x16x32_bf16 v[94:97], v[158:161], v[210:213], v[94:97]
	v_mfma_f32_16x16x32_bf16 v[90:93], v[166:169], v[210:213], v[90:93]
	v_mfma_f32_16x16x32_bf16 v[78:81], v[158:161], v[218:221], v[78:81]
	v_mfma_f32_16x16x32_bf16 v[74:77], v[166:169], v[218:221], v[74:77]
	v_mfma_f32_16x16x32_bf16 v[118:121], v[170:173], v[190:193], v[118:121]
	v_mfma_f32_16x16x32_bf16 v[114:117], v[182:185], v[190:193], v[114:117]
	v_mfma_f32_16x16x32_bf16 v[102:105], v[170:173], v[198:201], v[102:105]
	v_mfma_f32_16x16x32_bf16 v[98:101], v[182:185], v[198:201], v[98:101]
	v_mfma_f32_16x16x32_bf16 v[86:89], v[170:173], v[206:209], v[86:89]
	v_mfma_f32_16x16x32_bf16 v[82:85], v[182:185], v[206:209], v[82:85]
	v_mfma_f32_16x16x32_bf16 v[70:73], v[170:173], v[214:217], v[70:73]
	v_mfma_f32_16x16x32_bf16 v[66:69], v[182:185], v[214:217], v[66:69]
	v_mfma_f32_16x16x32_bf16 v[118:121], v[178:181], v[194:197], v[118:121]
	v_mfma_f32_16x16x32_bf16 v[114:117], v[186:189], v[194:197], v[114:117]
	v_mfma_f32_16x16x32_bf16 v[102:105], v[178:181], v[202:205], v[102:105]
	v_mfma_f32_16x16x32_bf16 v[98:101], v[186:189], v[202:205], v[98:101]
	v_mfma_f32_16x16x32_bf16 v[86:89], v[178:181], v[210:213], v[86:89]
	v_mfma_f32_16x16x32_bf16 v[82:85], v[186:189], v[210:213], v[82:85]
	v_mfma_f32_16x16x32_bf16 v[70:73], v[178:181], v[218:221], v[70:73]
	v_mfma_f32_16x16x32_bf16 v[66:69], v[186:189], v[218:221], v[66:69]
	s_setprio 0
	s_barrier
	s_add_i32 s34, s51, s17
	v_lshl_add_u64 v[222:223], s[38:39], 0, v[132:133]
	s_mov_b32 m0, s34
	ds_read_b128 v[190:193], v155 offset:16384
	ds_read_b128 v[194:197], v155 offset:17408
	ds_read_b128 v[198:201], v155 offset:18432
	ds_read_b128 v[202:205], v155 offset:19456
	ds_read_b128 v[206:209], v155 offset:20480
	ds_read_b128 v[210:213], v155 offset:21504
	ds_read_b128 v[214:217], v155 offset:22528
	ds_read_b128 v[218:221], v155 offset:23552
	global_load_lds_dwordx4 v[222:223], off
	s_add_i32 m0, s34, 0x2000
	s_add_u32 s34, s38, 0x40000
	v_lshl_add_u64 v[224:225], s[38:39], 0, v[136:137]
	s_addc_u32 s35, s39, 0
	s_add_i32 s58, s52, s17
	global_load_lds_dwordx4 v[224:225], off
	v_lshl_add_u64 v[226:227], s[34:35], 0, v[132:133]
	s_mov_b32 m0, s58
	v_lshl_add_u64 v[228:229], s[40:41], 0, v[134:135]
	global_load_lds_dwordx4 v[226:227], off
	v_lshl_add_u64 v[226:227], s[34:35], 0, v[136:137]
	s_add_i32 m0, s58, 0x2000
	s_nop 0
	global_load_lds_dwordx4 v[226:227], off
	v_lshl_add_u64 v[226:227], s[40:41], 0, v[130:131]
	s_mov_b32 m0, s42
	s_nop 0
	global_load_lds_dwordx4 v[226:227], off
	s_mov_b32 m0, s43
	s_nop 0
	global_load_lds_dwordx4 v[228:229], off
	s_waitcnt vmcnt(8)
	s_waitcnt lgkmcnt(0)
	s_barrier
	s_setprio 1
	s_waitcnt lgkmcnt(0)
	v_mfma_f32_16x16x32_bf16 v[62:65], v[146:149], v[190:193], v[62:65]
	v_mfma_f32_16x16x32_bf16 v[58:61], v[162:165], v[190:193], v[58:61]
	v_mfma_f32_16x16x32_bf16 v[46:49], v[146:149], v[198:201], v[46:49]
	v_mfma_f32_16x16x32_bf16 v[42:45], v[162:165], v[198:201], v[42:45]
	v_mfma_f32_16x16x32_bf16 v[30:33], v[146:149], v[206:209], v[30:33]
	v_mfma_f32_16x16x32_bf16 v[26:29], v[162:165], v[206:209], v[26:29]
	v_mfma_f32_16x16x32_bf16 v[14:17], v[146:149], v[214:217], v[14:17]
	v_mfma_f32_16x16x32_bf16 v[10:13], v[162:165], v[214:217], v[10:13]
	v_mfma_f32_16x16x32_bf16 v[62:65], v[158:161], v[194:197], v[62:65]
	v_mfma_f32_16x16x32_bf16 v[58:61], v[166:169], v[194:197], v[58:61]
	v_mfma_f32_16x16x32_bf16 v[46:49], v[158:161], v[202:205], v[46:49]
	v_mfma_f32_16x16x32_bf16 v[42:45], v[166:169], v[202:205], v[42:45]
	v_mfma_f32_16x16x32_bf16 v[30:33], v[158:161], v[210:213], v[30:33]
	v_mfma_f32_16x16x32_bf16 v[26:29], v[166:169], v[210:213], v[26:29]
	v_mfma_f32_16x16x32_bf16 v[14:17], v[158:161], v[218:221], v[14:17]
	v_mfma_f32_16x16x32_bf16 v[10:13], v[166:169], v[218:221], v[10:13]
	v_mfma_f32_16x16x32_bf16 v[54:57], v[170:173], v[190:193], v[54:57]
	v_mfma_f32_16x16x32_bf16 v[50:53], v[182:185], v[190:193], v[50:53]
	v_mfma_f32_16x16x32_bf16 v[38:41], v[170:173], v[198:201], v[38:41]
	v_mfma_f32_16x16x32_bf16 v[34:37], v[182:185], v[198:201], v[34:37]
	v_mfma_f32_16x16x32_bf16 v[22:25], v[170:173], v[206:209], v[22:25]
	v_mfma_f32_16x16x32_bf16 v[18:21], v[182:185], v[206:209], v[18:21]
	v_mfma_f32_16x16x32_bf16 v[6:9], v[170:173], v[214:217], v[6:9]
	v_mfma_f32_16x16x32_bf16 v[2:5], v[182:185], v[214:217], v[2:5]
	v_mfma_f32_16x16x32_bf16 v[54:57], v[178:181], v[194:197], v[54:57]
	v_mfma_f32_16x16x32_bf16 v[50:53], v[186:189], v[194:197], v[50:53]
	v_mfma_f32_16x16x32_bf16 v[38:41], v[178:181], v[202:205], v[38:41]
	v_mfma_f32_16x16x32_bf16 v[34:37], v[186:189], v[202:205], v[34:37]
	v_mfma_f32_16x16x32_bf16 v[22:25], v[178:181], v[210:213], v[22:25]
	v_mfma_f32_16x16x32_bf16 v[18:21], v[186:189], v[210:213], v[18:21]
	v_mfma_f32_16x16x32_bf16 v[6:9], v[178:181], v[218:221], v[6:9]
	v_mfma_f32_16x16x32_bf16 v[2:5], v[186:189], v[218:221], v[2:5]
	s_setprio 0
	s_barrier
	s_add_i32 s58, 0, 0x18000
	v_add_u32_e32 v157, s58, v151
	s_add_i32 s59, 0, 0x1c000
	ds_read_b128 v[146:149], v157
	ds_read_b128 v[158:161], v157 offset:1024
	ds_read_b128 v[162:165], v157 offset:2048
	ds_read_b128 v[166:169], v157 offset:3072
	v_add_u32_e32 v157, s59, v151
	ds_read_b128 v[170:173], v157
	ds_read_b128 v[178:181], v157 offset:1024
	ds_read_b128 v[182:185], v157 offset:2048
	ds_read_b128 v[186:189], v157 offset:3072
	s_add_u32 s34, s40, 0x40000
	s_addc_u32 s35, s41, 0
	s_mov_b32 m0, s44
	v_lshl_add_u64 v[230:231], s[34:35], 0, v[130:131]
	ds_read_b128 v[190:193], v155 offset:32768
	ds_read_b128 v[194:197], v155 offset:33792
	ds_read_b128 v[198:201], v155 offset:34816
	ds_read_b128 v[202:205], v155 offset:35840
	ds_read_b128 v[206:209], v155 offset:36864
	ds_read_b128 v[210:213], v155 offset:37888
	ds_read_b128 v[214:217], v155 offset:38912
	ds_read_b128 v[218:221], v155 offset:39936
	global_load_lds_dwordx4 v[230:231], off
	v_lshl_add_u64 v[230:231], s[34:35], 0, v[134:135]
	s_mov_b32 m0, s45
	s_nop 0
	global_load_lds_dwordx4 v[230:231], off
	s_waitcnt vmcnt(8)
	s_waitcnt lgkmcnt(0)
	s_barrier
	s_setprio 1
	s_waitcnt lgkmcnt(0)
	v_mfma_f32_16x16x32_bf16 v[126:129], v[146:149], v[190:193], v[126:129]
	v_mfma_f32_16x16x32_bf16 v[122:125], v[162:165], v[190:193], v[122:125]
	v_mfma_f32_16x16x32_bf16 v[110:113], v[146:149], v[198:201], v[110:113]
	v_mfma_f32_16x16x32_bf16 v[106:109], v[162:165], v[198:201], v[106:109]
	v_mfma_f32_16x16x32_bf16 v[94:97], v[146:149], v[206:209], v[94:97]
	v_mfma_f32_16x16x32_bf16 v[90:93], v[162:165], v[206:209], v[90:93]
	v_mfma_f32_16x16x32_bf16 v[78:81], v[146:149], v[214:217], v[78:81]
	v_mfma_f32_16x16x32_bf16 v[74:77], v[162:165], v[214:217], v[74:77]
	v_mfma_f32_16x16x32_bf16 v[126:129], v[158:161], v[194:197], v[126:129]
	v_mfma_f32_16x16x32_bf16 v[122:125], v[166:169], v[194:197], v[122:125]
	v_mfma_f32_16x16x32_bf16 v[110:113], v[158:161], v[202:205], v[110:113]
	v_mfma_f32_16x16x32_bf16 v[106:109], v[166:169], v[202:205], v[106:109]
	v_mfma_f32_16x16x32_bf16 v[94:97], v[158:161], v[210:213], v[94:97]
	v_mfma_f32_16x16x32_bf16 v[90:93], v[166:169], v[210:213], v[90:93]
	v_mfma_f32_16x16x32_bf16 v[78:81], v[158:161], v[218:221], v[78:81]
	v_mfma_f32_16x16x32_bf16 v[74:77], v[166:169], v[218:221], v[74:77]
	v_mfma_f32_16x16x32_bf16 v[118:121], v[170:173], v[190:193], v[118:121]
	v_mfma_f32_16x16x32_bf16 v[114:117], v[182:185], v[190:193], v[114:117]
	v_mfma_f32_16x16x32_bf16 v[102:105], v[170:173], v[198:201], v[102:105]
	v_mfma_f32_16x16x32_bf16 v[98:101], v[182:185], v[198:201], v[98:101]
	v_mfma_f32_16x16x32_bf16 v[86:89], v[170:173], v[206:209], v[86:89]
	v_mfma_f32_16x16x32_bf16 v[82:85], v[182:185], v[206:209], v[82:85]
	v_mfma_f32_16x16x32_bf16 v[70:73], v[170:173], v[214:217], v[70:73]
	v_mfma_f32_16x16x32_bf16 v[66:69], v[182:185], v[214:217], v[66:69]
	v_mfma_f32_16x16x32_bf16 v[118:121], v[178:181], v[194:197], v[118:121]
	v_mfma_f32_16x16x32_bf16 v[114:117], v[186:189], v[194:197], v[114:117]
	v_mfma_f32_16x16x32_bf16 v[102:105], v[178:181], v[202:205], v[102:105]
	v_mfma_f32_16x16x32_bf16 v[98:101], v[186:189], v[202:205], v[98:101]
	v_mfma_f32_16x16x32_bf16 v[86:89], v[178:181], v[210:213], v[86:89]
	v_mfma_f32_16x16x32_bf16 v[82:85], v[186:189], v[210:213], v[82:85]
	v_mfma_f32_16x16x32_bf16 v[70:73], v[178:181], v[218:221], v[70:73]
	v_mfma_f32_16x16x32_bf16 v[66:69], v[186:189], v[218:221], v[66:69]
	s_setprio 0
	s_barrier
	s_add_i32 s34, s58, s17
	v_lshl_add_u64 v[222:223], v[222:223], 0, s[18:19]
	s_mov_b32 m0, s34
	ds_read_b128 v[190:193], v155 offset:49152
	ds_read_b128 v[194:197], v155 offset:50176
	ds_read_b128 v[198:201], v155 offset:51200
	ds_read_b128 v[202:205], v155 offset:52224
	ds_read_b128 v[206:209], v155 offset:53248
	ds_read_b128 v[210:213], v155 offset:54272
	ds_read_b128 v[214:217], v155 offset:55296
	ds_read_b128 v[218:221], v155 offset:56320
	global_load_lds_dwordx4 v[222:223], off
	s_add_i32 m0, s34, 0x2000
	s_add_u32 s34, s38, 0x40080
	v_lshl_add_u64 v[222:223], v[224:225], 0, s[18:19]
	s_addc_u32 s35, s39, 0
	s_add_i32 s38, s59, s17
	global_load_lds_dwordx4 v[222:223], off
	v_lshl_add_u64 v[222:223], s[34:35], 0, v[132:133]
	s_mov_b32 m0, s38
	s_nop 0
	global_load_lds_dwordx4 v[222:223], off
	v_lshl_add_u64 v[222:223], s[34:35], 0, v[136:137]
	s_add_i32 m0, s38, 0x2000
	s_nop 0
	global_load_lds_dwordx4 v[222:223], off
	v_lshl_add_u64 v[222:223], v[226:227], 0, s[18:19]
	s_mov_b32 m0, s47
	s_nop 0
	global_load_lds_dwordx4 v[222:223], off
	v_lshl_add_u64 v[222:223], v[228:229], 0, s[18:19]
	s_mov_b32 m0, s48
	s_nop 0
	global_load_lds_dwordx4 v[222:223], off
	s_waitcnt vmcnt(8)
	s_waitcnt lgkmcnt(0)
	s_barrier
	s_setprio 1
	s_waitcnt lgkmcnt(0)
	v_mfma_f32_16x16x32_bf16 v[62:65], v[146:149], v[190:193], v[62:65]
	v_mfma_f32_16x16x32_bf16 v[58:61], v[162:165], v[190:193], v[58:61]
	v_mfma_f32_16x16x32_bf16 v[46:49], v[146:149], v[198:201], v[46:49]
	v_mfma_f32_16x16x32_bf16 v[42:45], v[162:165], v[198:201], v[42:45]
	v_mfma_f32_16x16x32_bf16 v[30:33], v[146:149], v[206:209], v[30:33]
	v_mfma_f32_16x16x32_bf16 v[26:29], v[162:165], v[206:209], v[26:29]
	v_mfma_f32_16x16x32_bf16 v[14:17], v[146:149], v[214:217], v[14:17]
	v_mfma_f32_16x16x32_bf16 v[10:13], v[162:165], v[214:217], v[10:13]
	v_mfma_f32_16x16x32_bf16 v[62:65], v[158:161], v[194:197], v[62:65]
	v_mfma_f32_16x16x32_bf16 v[58:61], v[166:169], v[194:197], v[58:61]
	v_mfma_f32_16x16x32_bf16 v[46:49], v[158:161], v[202:205], v[46:49]
	v_mfma_f32_16x16x32_bf16 v[42:45], v[166:169], v[202:205], v[42:45]
	v_mfma_f32_16x16x32_bf16 v[30:33], v[158:161], v[210:213], v[30:33]
	v_mfma_f32_16x16x32_bf16 v[26:29], v[166:169], v[210:213], v[26:29]
	v_mfma_f32_16x16x32_bf16 v[14:17], v[158:161], v[218:221], v[14:17]
	v_mfma_f32_16x16x32_bf16 v[10:13], v[166:169], v[218:221], v[10:13]
	v_mfma_f32_16x16x32_bf16 v[54:57], v[170:173], v[190:193], v[54:57]
	v_mfma_f32_16x16x32_bf16 v[50:53], v[182:185], v[190:193], v[50:53]
	v_mfma_f32_16x16x32_bf16 v[38:41], v[170:173], v[198:201], v[38:41]
	v_mfma_f32_16x16x32_bf16 v[34:37], v[182:185], v[198:201], v[34:37]
	v_mfma_f32_16x16x32_bf16 v[22:25], v[170:173], v[206:209], v[22:25]
	v_mfma_f32_16x16x32_bf16 v[18:21], v[182:185], v[206:209], v[18:21]
	v_mfma_f32_16x16x32_bf16 v[6:9], v[170:173], v[214:217], v[6:9]
	v_mfma_f32_16x16x32_bf16 v[2:5], v[182:185], v[214:217], v[2:5]
	v_mfma_f32_16x16x32_bf16 v[54:57], v[178:181], v[194:197], v[54:57]
	v_mfma_f32_16x16x32_bf16 v[50:53], v[186:189], v[194:197], v[50:53]
	v_mfma_f32_16x16x32_bf16 v[38:41], v[178:181], v[202:205], v[38:41]
	v_mfma_f32_16x16x32_bf16 v[34:37], v[186:189], v[202:205], v[34:37]
	v_mfma_f32_16x16x32_bf16 v[22:25], v[178:181], v[210:213], v[22:25]
	v_mfma_f32_16x16x32_bf16 v[18:21], v[186:189], v[210:213], v[18:21]
	v_mfma_f32_16x16x32_bf16 v[6:9], v[178:181], v[218:221], v[6:9]
	v_mfma_f32_16x16x32_bf16 v[2:5], v[186:189], v[218:221], v[2:5]
	s_setprio 0
	s_barrier
	s_add_i32 s57, s57, 2
	s_add_u32 s55, s55, 0x100
	s_addc_u32 s56, s56, 0
	s_cmp_gt_u32 s57, 13
	s_mov_b64 s[34:35], s[36:37]
	s_cbranch_scc0 .LBB0_1496

.LBB0_1589:
	s_ashr_i32 s21, s20, 31
	s_lshl_b64 s[22:23], s[20:21], 19
	s_add_u32 s22, s14, s22
	s_addc_u32 s23, s15, s23
	s_and_b64 s[24:25], s[0:1], exec
	s_cselect_b32 s21, s23, s27
	s_cselect_b32 s49, s22, s26
	s_ashr_i32 s19, s18, 31
	s_lshl_b64 s[24:25], s[18:19], 19
	s_add_u32 s24, s16, s24
	s_addc_u32 s25, s17, s25
	s_and_b64 s[30:31], s[0:1], exec
	s_cselect_b32 s19, s25, s29
	s_cselect_b32 s50, s24, s28
	s_add_u32 s51, s28, 0x100
	s_addc_u32 s52, s29, 0
	s_mov_b32 s53, -2
	s_waitcnt vmcnt(0)
	ds_read_b128 v[146:149], v155
	ds_read_b128 v[160:163], v155 offset:1024
	ds_read_b128 v[164:167], v155 offset:2048
	ds_read_b128 v[168:171], v155 offset:3072
	ds_read_b128 v[178:181], v156
	ds_read_b128 v[182:185], v156 offset:1024
	ds_read_b128 v[186:189], v156 offset:2048
	ds_read_b128 v[190:193], v156 offset:3072
	s_add_u32 s28, s26, 0x100
	s_addc_u32 s29, s27, 0
	s_cmp_eq_u32 s53, 12
	s_cselect_b32 s35, s21, s29
	s_cselect_b32 s34, s49, s28
	s_cselect_b32 s31, s19, s52
	s_cselect_b32 s30, s50, s51
	v_lshl_add_u64 v[150:151], s[26:27], 0, v[138:139]
	s_add_i32 m0, s37, 0xc000
	ds_read_b128 v[194:197], v157
	ds_read_b128 v[198:201], v157 offset:1024
	ds_read_b128 v[202:205], v157 offset:2048
	ds_read_b128 v[206:209], v157 offset:3072
	ds_read_b128 v[210:213], v157 offset:4096
	ds_read_b128 v[214:217], v157 offset:5120
	ds_read_b128 v[218:221], v157 offset:6144
	ds_read_b128 v[222:225], v157 offset:7168
	global_load_lds_dwordx4 v[150:151], off
	v_lshl_add_u64 v[150:151], s[26:27], 0, v[140:141]
	s_add_i32 m0, s37, 0xe000
	s_nop 0
	global_load_lds_dwordx4 v[150:151], off
	s_waitcnt vmcnt(8)
	s_waitcnt lgkmcnt(0)
	s_barrier
	s_setprio 1
	s_waitcnt lgkmcnt(0)
	v_mfma_f32_16x16x32_bf16 v[126:129], v[146:149], v[194:197], 0
	v_mfma_f32_16x16x32_bf16 v[122:125], v[164:167], v[194:197], 0
	v_mfma_f32_16x16x32_bf16 v[110:113], v[146:149], v[202:205], 0
	v_mfma_f32_16x16x32_bf16 v[106:109], v[164:167], v[202:205], 0
	v_mfma_f32_16x16x32_bf16 v[94:97], v[146:149], v[210:213], 0
	v_mfma_f32_16x16x32_bf16 v[90:93], v[164:167], v[210:213], 0
	v_mfma_f32_16x16x32_bf16 v[78:81], v[146:149], v[218:221], 0
	v_mfma_f32_16x16x32_bf16 v[74:77], v[164:167], v[218:221], 0
	v_mfma_f32_16x16x32_bf16 v[126:129], v[160:163], v[198:201], v[126:129]
	v_mfma_f32_16x16x32_bf16 v[122:125], v[168:171], v[198:201], v[122:125]
	v_mfma_f32_16x16x32_bf16 v[110:113], v[160:163], v[206:209], v[110:113]
	v_mfma_f32_16x16x32_bf16 v[106:109], v[168:171], v[206:209], v[106:109]
	v_mfma_f32_16x16x32_bf16 v[94:97], v[160:163], v[214:217], v[94:97]
	v_mfma_f32_16x16x32_bf16 v[90:93], v[168:171], v[214:217], v[90:93]
	v_mfma_f32_16x16x32_bf16 v[78:81], v[160:163], v[222:225], v[78:81]
	v_mfma_f32_16x16x32_bf16 v[74:77], v[168:171], v[222:225], v[74:77]
	v_mfma_f32_16x16x32_bf16 v[118:121], v[178:181], v[194:197], 0
	v_mfma_f32_16x16x32_bf16 v[114:117], v[186:189], v[194:197], 0
	v_mfma_f32_16x16x32_bf16 v[102:105], v[178:181], v[202:205], 0
	v_mfma_f32_16x16x32_bf16 v[98:101], v[186:189], v[202:205], 0
	v_mfma_f32_16x16x32_bf16 v[86:89], v[178:181], v[210:213], 0
	v_mfma_f32_16x16x32_bf16 v[82:85], v[186:189], v[210:213], 0
	v_mfma_f32_16x16x32_bf16 v[70:73], v[178:181], v[218:221], 0
	v_mfma_f32_16x16x32_bf16 v[66:69], v[186:189], v[218:221], 0
	v_mfma_f32_16x16x32_bf16 v[118:121], v[182:185], v[198:201], v[118:121]
	v_mfma_f32_16x16x32_bf16 v[114:117], v[190:193], v[198:201], v[114:117]
	v_mfma_f32_16x16x32_bf16 v[102:105], v[182:185], v[206:209], v[102:105]
	v_mfma_f32_16x16x32_bf16 v[98:101], v[190:193], v[206:209], v[98:101]
	v_mfma_f32_16x16x32_bf16 v[86:89], v[182:185], v[214:217], v[86:89]
	v_mfma_f32_16x16x32_bf16 v[82:85], v[190:193], v[214:217], v[82:85]
	v_mfma_f32_16x16x32_bf16 v[70:73], v[182:185], v[222:225], v[70:73]
	v_mfma_f32_16x16x32_bf16 v[66:69], v[190:193], v[222:225], v[66:69]
	s_setprio 0
	s_barrier
	s_add_i32 s26, s45, s36
	v_lshl_add_u64 v[150:151], s[30:31], 0, v[132:133]
	s_mov_b32 m0, s26
	ds_read_b128 v[194:197], v157 offset:16384
	ds_read_b128 v[198:201], v157 offset:17408
	ds_read_b128 v[202:205], v157 offset:18432
	ds_read_b128 v[206:209], v157 offset:19456
	ds_read_b128 v[210:213], v157 offset:20480
	ds_read_b128 v[214:217], v157 offset:21504
	ds_read_b128 v[218:221], v157 offset:22528
	ds_read_b128 v[222:225], v157 offset:23552
	global_load_lds_dwordx4 v[150:151], off
	s_add_i32 m0, s26, 0x2000
	s_add_u32 s26, s30, 0x40000
	v_lshl_add_u64 v[172:173], s[30:31], 0, v[136:137]
	s_addc_u32 s27, s31, 0
	s_add_i32 s54, s46, s36
	global_load_lds_dwordx4 v[172:173], off
	v_lshl_add_u64 v[226:227], s[26:27], 0, v[132:133]
	s_mov_b32 m0, s54
	v_lshl_add_u64 v[228:229], s[34:35], 0, v[134:135]
	global_load_lds_dwordx4 v[226:227], off
	v_lshl_add_u64 v[226:227], s[26:27], 0, v[136:137]
	s_add_i32 m0, s54, 0x2000
	s_nop 0
	global_load_lds_dwordx4 v[226:227], off
	v_lshl_add_u64 v[226:227], s[34:35], 0, v[130:131]
	s_mov_b32 m0, s37
	s_nop 0
	global_load_lds_dwordx4 v[226:227], off
	s_mov_b32 m0, s38
	s_nop 0
	global_load_lds_dwordx4 v[228:229], off
	s_waitcnt vmcnt(8)
	s_waitcnt lgkmcnt(0)
	s_barrier
	s_setprio 1
	s_waitcnt lgkmcnt(0)
	v_mfma_f32_16x16x32_bf16 v[62:65], v[146:149], v[194:197], 0
	v_mfma_f32_16x16x32_bf16 v[58:61], v[164:167], v[194:197], 0
	v_mfma_f32_16x16x32_bf16 v[46:49], v[146:149], v[202:205], 0
	v_mfma_f32_16x16x32_bf16 v[42:45], v[164:167], v[202:205], 0
	v_mfma_f32_16x16x32_bf16 v[30:33], v[146:149], v[210:213], 0
	v_mfma_f32_16x16x32_bf16 v[26:29], v[164:167], v[210:213], 0
	v_mfma_f32_16x16x32_bf16 v[14:17], v[146:149], v[218:221], 0
	v_mfma_f32_16x16x32_bf16 v[10:13], v[164:167], v[218:221], 0
	v_mfma_f32_16x16x32_bf16 v[62:65], v[160:163], v[198:201], v[62:65]
	v_mfma_f32_16x16x32_bf16 v[58:61], v[168:171], v[198:201], v[58:61]
	v_mfma_f32_16x16x32_bf16 v[46:49], v[160:163], v[206:209], v[46:49]
	v_mfma_f32_16x16x32_bf16 v[42:45], v[168:171], v[206:209], v[42:45]
	v_mfma_f32_16x16x32_bf16 v[30:33], v[160:163], v[214:217], v[30:33]
	v_mfma_f32_16x16x32_bf16 v[26:29], v[168:171], v[214:217], v[26:29]
	v_mfma_f32_16x16x32_bf16 v[14:17], v[160:163], v[222:225], v[14:17]
	v_mfma_f32_16x16x32_bf16 v[10:13], v[168:171], v[222:225], v[10:13]
	v_mfma_f32_16x16x32_bf16 v[54:57], v[178:181], v[194:197], 0
	v_mfma_f32_16x16x32_bf16 v[50:53], v[186:189], v[194:197], 0
	v_mfma_f32_16x16x32_bf16 v[38:41], v[178:181], v[202:205], 0
	v_mfma_f32_16x16x32_bf16 v[34:37], v[186:189], v[202:205], 0
	v_mfma_f32_16x16x32_bf16 v[22:25], v[178:181], v[210:213], 0
	v_mfma_f32_16x16x32_bf16 v[18:21], v[186:189], v[210:213], 0
	v_mfma_f32_16x16x32_bf16 v[6:9], v[178:181], v[218:221], 0
	v_mfma_f32_16x16x32_bf16 v[2:5], v[186:189], v[218:221], 0
	v_mfma_f32_16x16x32_bf16 v[54:57], v[182:185], v[198:201], v[54:57]
	v_mfma_f32_16x16x32_bf16 v[50:53], v[190:193], v[198:201], v[50:53]
	v_mfma_f32_16x16x32_bf16 v[38:41], v[182:185], v[206:209], v[38:41]
	v_mfma_f32_16x16x32_bf16 v[34:37], v[190:193], v[206:209], v[34:37]
	v_mfma_f32_16x16x32_bf16 v[22:25], v[182:185], v[214:217], v[22:25]
	v_mfma_f32_16x16x32_bf16 v[18:21], v[190:193], v[214:217], v[18:21]
	v_mfma_f32_16x16x32_bf16 v[6:9], v[182:185], v[222:225], v[6:9]
	v_mfma_f32_16x16x32_bf16 v[2:5], v[190:193], v[222:225], v[2:5]
	s_setprio 0
	s_barrier
	s_add_i32 s54, 0, 0x18000
	s_add_i32 s55, 0, 0x1c000
	v_add_u32_e32 v168, s54, v153
	v_add_u32_e32 v177, s55, v153
	ds_read_b128 v[146:149], v168
	ds_read_b128 v[160:163], v168 offset:1024
	ds_read_b128 v[164:167], v168 offset:2048
	ds_read_b128 v[168:171], v168 offset:3072
	ds_read_b128 v[178:181], v177
	ds_read_b128 v[182:185], v177 offset:1024
	ds_read_b128 v[186:189], v177 offset:2048
	ds_read_b128 v[190:193], v177 offset:3072
	s_add_u32 s26, s34, 0x40000
	s_addc_u32 s27, s35, 0
	s_mov_b32 m0, s39
	v_lshl_add_u64 v[230:231], s[26:27], 0, v[130:131]
	ds_read_b128 v[194:197], v157 offset:32768
	ds_read_b128 v[198:201], v157 offset:33792
	ds_read_b128 v[202:205], v157 offset:34816
	ds_read_b128 v[206:209], v157 offset:35840
	ds_read_b128 v[210:213], v157 offset:36864
	ds_read_b128 v[214:217], v157 offset:37888
	ds_read_b128 v[218:221], v157 offset:38912
	ds_read_b128 v[222:225], v157 offset:39936
	global_load_lds_dwordx4 v[230:231], off
	v_lshl_add_u64 v[230:231], s[26:27], 0, v[134:135]
	s_mov_b32 m0, s40
	s_nop 0
	global_load_lds_dwordx4 v[230:231], off
	s_waitcnt vmcnt(8)
	s_waitcnt lgkmcnt(0)
	s_barrier
	s_setprio 1
	s_waitcnt lgkmcnt(0)
	v_mfma_f32_16x16x32_bf16 v[126:129], v[146:149], v[194:197], v[126:129]
	v_mfma_f32_16x16x32_bf16 v[122:125], v[164:167], v[194:197], v[122:125]
	v_mfma_f32_16x16x32_bf16 v[110:113], v[146:149], v[202:205], v[110:113]
	v_mfma_f32_16x16x32_bf16 v[106:109], v[164:167], v[202:205], v[106:109]
	v_mfma_f32_16x16x32_bf16 v[94:97], v[146:149], v[210:213], v[94:97]
	v_mfma_f32_16x16x32_bf16 v[90:93], v[164:167], v[210:213], v[90:93]
	v_mfma_f32_16x16x32_bf16 v[78:81], v[146:149], v[218:221], v[78:81]
	v_mfma_f32_16x16x32_bf16 v[74:77], v[164:167], v[218:221], v[74:77]
	v_mfma_f32_16x16x32_bf16 v[126:129], v[160:163], v[198:201], v[126:129]
	v_mfma_f32_16x16x32_bf16 v[122:125], v[168:171], v[198:201], v[122:125]
	v_mfma_f32_16x16x32_bf16 v[110:113], v[160:163], v[206:209], v[110:113]
	v_mfma_f32_16x16x32_bf16 v[106:109], v[168:171], v[206:209], v[106:109]
	v_mfma_f32_16x16x32_bf16 v[94:97], v[160:163], v[214:217], v[94:97]
	v_mfma_f32_16x16x32_bf16 v[90:93], v[168:171], v[214:217], v[90:93]
	v_mfma_f32_16x16x32_bf16 v[78:81], v[160:163], v[222:225], v[78:81]
	v_mfma_f32_16x16x32_bf16 v[74:77], v[168:171], v[222:225], v[74:77]
	v_mfma_f32_16x16x32_bf16 v[118:121], v[178:181], v[194:197], v[118:121]
	v_mfma_f32_16x16x32_bf16 v[114:117], v[186:189], v[194:197], v[114:117]
	v_mfma_f32_16x16x32_bf16 v[102:105], v[178:181], v[202:205], v[102:105]
	v_mfma_f32_16x16x32_bf16 v[98:101], v[186:189], v[202:205], v[98:101]
	v_mfma_f32_16x16x32_bf16 v[86:89], v[178:181], v[210:213], v[86:89]
	v_mfma_f32_16x16x32_bf16 v[82:85], v[186:189], v[210:213], v[82:85]
	v_mfma_f32_16x16x32_bf16 v[70:73], v[178:181], v[218:221], v[70:73]
	v_mfma_f32_16x16x32_bf16 v[66:69], v[186:189], v[218:221], v[66:69]
	v_mfma_f32_16x16x32_bf16 v[118:121], v[182:185], v[198:201], v[118:121]
	v_mfma_f32_16x16x32_bf16 v[114:117], v[190:193], v[198:201], v[114:117]
	v_mfma_f32_16x16x32_bf16 v[102:105], v[182:185], v[206:209], v[102:105]
	v_mfma_f32_16x16x32_bf16 v[98:101], v[190:193], v[206:209], v[98:101]
	v_mfma_f32_16x16x32_bf16 v[86:89], v[182:185], v[214:217], v[86:89]
	v_mfma_f32_16x16x32_bf16 v[82:85], v[190:193], v[214:217], v[82:85]
	v_mfma_f32_16x16x32_bf16 v[70:73], v[182:185], v[222:225], v[70:73]
	v_mfma_f32_16x16x32_bf16 v[66:69], v[190:193], v[222:225], v[66:69]
	s_setprio 0
	s_barrier
	s_add_i32 s26, s54, s36
	v_lshl_add_u64 v[150:151], v[150:151], 0, s[10:11]
	s_mov_b32 m0, s26
	ds_read_b128 v[194:197], v157 offset:49152
	ds_read_b128 v[198:201], v157 offset:50176
	ds_read_b128 v[202:205], v157 offset:51200
	ds_read_b128 v[206:209], v157 offset:52224
	ds_read_b128 v[210:213], v157 offset:53248
	ds_read_b128 v[214:217], v157 offset:54272
	ds_read_b128 v[218:221], v157 offset:55296
	ds_read_b128 v[222:225], v157 offset:56320
	global_load_lds_dwordx4 v[150:151], off
	s_add_i32 m0, s26, 0x2000
	s_add_u32 s26, s30, 0x40080
	v_lshl_add_u64 v[150:151], v[172:173], 0, s[10:11]
	s_addc_u32 s27, s31, 0
	s_add_i32 s30, s55, s36
	global_load_lds_dwordx4 v[150:151], off
	v_lshl_add_u64 v[150:151], s[26:27], 0, v[132:133]
	s_mov_b32 m0, s30
	s_nop 0
	global_load_lds_dwordx4 v[150:151], off
	v_lshl_add_u64 v[150:151], s[26:27], 0, v[136:137]
	s_add_i32 m0, s30, 0x2000
	s_nop 0
	global_load_lds_dwordx4 v[150:151], off
	v_lshl_add_u64 v[150:151], v[226:227], 0, s[10:11]
	s_mov_b32 m0, s42
	s_nop 0
	global_load_lds_dwordx4 v[150:151], off
	v_lshl_add_u64 v[150:151], v[228:229], 0, s[10:11]
	s_mov_b32 m0, s43
	s_nop 0
	global_load_lds_dwordx4 v[150:151], off
	s_waitcnt vmcnt(8)
	s_waitcnt lgkmcnt(0)
	s_barrier
	s_setprio 1
	s_waitcnt lgkmcnt(0)
	v_mfma_f32_16x16x32_bf16 v[62:65], v[146:149], v[194:197], v[62:65]
	v_mfma_f32_16x16x32_bf16 v[58:61], v[164:167], v[194:197], v[58:61]
	v_mfma_f32_16x16x32_bf16 v[46:49], v[146:149], v[202:205], v[46:49]
	v_mfma_f32_16x16x32_bf16 v[42:45], v[164:167], v[202:205], v[42:45]
	v_mfma_f32_16x16x32_bf16 v[30:33], v[146:149], v[210:213], v[30:33]
	v_mfma_f32_16x16x32_bf16 v[26:29], v[164:167], v[210:213], v[26:29]
	v_mfma_f32_16x16x32_bf16 v[14:17], v[146:149], v[218:221], v[14:17]
	v_mfma_f32_16x16x32_bf16 v[10:13], v[164:167], v[218:221], v[10:13]
	v_mfma_f32_16x16x32_bf16 v[62:65], v[160:163], v[198:201], v[62:65]
	v_mfma_f32_16x16x32_bf16 v[58:61], v[168:171], v[198:201], v[58:61]
	v_mfma_f32_16x16x32_bf16 v[46:49], v[160:163], v[206:209], v[46:49]
	v_mfma_f32_16x16x32_bf16 v[42:45], v[168:171], v[206:209], v[42:45]
	v_mfma_f32_16x16x32_bf16 v[30:33], v[160:163], v[214:217], v[30:33]
	v_mfma_f32_16x16x32_bf16 v[26:29], v[168:171], v[214:217], v[26:29]
	v_mfma_f32_16x16x32_bf16 v[14:17], v[160:163], v[222:225], v[14:17]
	v_mfma_f32_16x16x32_bf16 v[10:13], v[168:171], v[222:225], v[10:13]
	v_mfma_f32_16x16x32_bf16 v[54:57], v[178:181], v[194:197], v[54:57]
	v_mfma_f32_16x16x32_bf16 v[50:53], v[186:189], v[194:197], v[50:53]
	v_mfma_f32_16x16x32_bf16 v[38:41], v[178:181], v[202:205], v[38:41]
	v_mfma_f32_16x16x32_bf16 v[34:37], v[186:189], v[202:205], v[34:37]
	v_mfma_f32_16x16x32_bf16 v[22:25], v[178:181], v[210:213], v[22:25]
	v_mfma_f32_16x16x32_bf16 v[18:21], v[186:189], v[210:213], v[18:21]
	v_mfma_f32_16x16x32_bf16 v[6:9], v[178:181], v[218:221], v[6:9]
	v_mfma_f32_16x16x32_bf16 v[2:5], v[186:189], v[218:221], v[2:5]
	v_mfma_f32_16x16x32_bf16 v[54:57], v[182:185], v[198:201], v[54:57]
	v_mfma_f32_16x16x32_bf16 v[50:53], v[190:193], v[198:201], v[50:53]
	v_mfma_f32_16x16x32_bf16 v[38:41], v[182:185], v[206:209], v[38:41]
	v_mfma_f32_16x16x32_bf16 v[34:37], v[190:193], v[206:209], v[34:37]
	v_mfma_f32_16x16x32_bf16 v[22:25], v[182:185], v[214:217], v[22:25]
	v_mfma_f32_16x16x32_bf16 v[18:21], v[190:193], v[214:217], v[18:21]
	v_mfma_f32_16x16x32_bf16 v[6:9], v[182:185], v[222:225], v[6:9]
	v_mfma_f32_16x16x32_bf16 v[2:5], v[190:193], v[222:225], v[2:5]
	s_setprio 0
	s_barrier
	s_add_i32 s53, s53, 2
	s_add_u32 s51, s51, 0x100
	s_addc_u32 s52, s52, 0
	s_cmp_gt_u32 s53, 13
	s_mov_b64 s[26:27], s[28:29]
	s_cbranch_scc0 .LBB0_1590
	s_branch .Lpeel_exit_1590
.LBB0_1590:
	ds_read_b128 v[146:149], v155
	ds_read_b128 v[160:163], v155 offset:1024
	ds_read_b128 v[164:167], v155 offset:2048
	ds_read_b128 v[168:171], v155 offset:3072
	ds_read_b128 v[178:181], v156
	ds_read_b128 v[182:185], v156 offset:1024
	ds_read_b128 v[186:189], v156 offset:2048
	ds_read_b128 v[190:193], v156 offset:3072
	s_add_u32 s28, s26, 0x100
	s_addc_u32 s29, s27, 0
	s_cmp_eq_u32 s53, 12
	s_cselect_b32 s35, s21, s29
	s_cselect_b32 s34, s49, s28
	s_cselect_b32 s31, s19, s52
	s_cselect_b32 s30, s50, s51
	v_lshl_add_u64 v[150:151], s[26:27], 0, v[138:139]
	s_add_i32 m0, s37, 0xc000
	ds_read_b128 v[194:197], v157
	ds_read_b128 v[198:201], v157 offset:1024
	ds_read_b128 v[202:205], v157 offset:2048
	ds_read_b128 v[206:209], v157 offset:3072
	ds_read_b128 v[210:213], v157 offset:4096
	ds_read_b128 v[214:217], v157 offset:5120
	ds_read_b128 v[218:221], v157 offset:6144
	ds_read_b128 v[222:225], v157 offset:7168
	global_load_lds_dwordx4 v[150:151], off
	v_lshl_add_u64 v[150:151], s[26:27], 0, v[140:141]
	s_add_i32 m0, s37, 0xe000
	s_nop 0
	global_load_lds_dwordx4 v[150:151], off
	s_waitcnt vmcnt(8)
	s_waitcnt lgkmcnt(0)
	s_barrier
	s_setprio 1
	s_waitcnt lgkmcnt(0)
	v_mfma_f32_16x16x32_bf16 v[126:129], v[146:149], v[194:197], v[126:129]
	v_mfma_f32_16x16x32_bf16 v[122:125], v[164:167], v[194:197], v[122:125]
	v_mfma_f32_16x16x32_bf16 v[110:113], v[146:149], v[202:205], v[110:113]
	v_mfma_f32_16x16x32_bf16 v[106:109], v[164:167], v[202:205], v[106:109]
	v_mfma_f32_16x16x32_bf16 v[94:97], v[146:149], v[210:213], v[94:97]
	v_mfma_f32_16x16x32_bf16 v[90:93], v[164:167], v[210:213], v[90:93]
	v_mfma_f32_16x16x32_bf16 v[78:81], v[146:149], v[218:221], v[78:81]
	v_mfma_f32_16x16x32_bf16 v[74:77], v[164:167], v[218:221], v[74:77]
	v_mfma_f32_16x16x32_bf16 v[126:129], v[160:163], v[198:201], v[126:129]
	v_mfma_f32_16x16x32_bf16 v[122:125], v[168:171], v[198:201], v[122:125]
	v_mfma_f32_16x16x32_bf16 v[110:113], v[160:163], v[206:209], v[110:113]
	v_mfma_f32_16x16x32_bf16 v[106:109], v[168:171], v[206:209], v[106:109]
	v_mfma_f32_16x16x32_bf16 v[94:97], v[160:163], v[214:217], v[94:97]
	v_mfma_f32_16x16x32_bf16 v[90:93], v[168:171], v[214:217], v[90:93]
	v_mfma_f32_16x16x32_bf16 v[78:81], v[160:163], v[222:225], v[78:81]
	v_mfma_f32_16x16x32_bf16 v[74:77], v[168:171], v[222:225], v[74:77]
	v_mfma_f32_16x16x32_bf16 v[118:121], v[178:181], v[194:197], v[118:121]
	v_mfma_f32_16x16x32_bf16 v[114:117], v[186:189], v[194:197], v[114:117]
	v_mfma_f32_16x16x32_bf16 v[102:105], v[178:181], v[202:205], v[102:105]
	v_mfma_f32_16x16x32_bf16 v[98:101], v[186:189], v[202:205], v[98:101]
	v_mfma_f32_16x16x32_bf16 v[86:89], v[178:181], v[210:213], v[86:89]
	v_mfma_f32_16x16x32_bf16 v[82:85], v[186:189], v[210:213], v[82:85]
	v_mfma_f32_16x16x32_bf16 v[70:73], v[178:181], v[218:221], v[70:73]
	v_mfma_f32_16x16x32_bf16 v[66:69], v[186:189], v[218:221], v[66:69]
	v_mfma_f32_16x16x32_bf16 v[118:121], v[182:185], v[198:201], v[118:121]
	v_mfma_f32_16x16x32_bf16 v[114:117], v[190:193], v[198:201], v[114:117]
	v_mfma_f32_16x16x32_bf16 v[102:105], v[182:185], v[206:209], v[102:105]
	v_mfma_f32_16x16x32_bf16 v[98:101], v[190:193], v[206:209], v[98:101]
	v_mfma_f32_16x16x32_bf16 v[86:89], v[182:185], v[214:217], v[86:89]
	v_mfma_f32_16x16x32_bf16 v[82:85], v[190:193], v[214:217], v[82:85]
	v_mfma_f32_16x16x32_bf16 v[70:73], v[182:185], v[222:225], v[70:73]
	v_mfma_f32_16x16x32_bf16 v[66:69], v[190:193], v[222:225], v[66:69]
	s_setprio 0
	s_barrier
	s_add_i32 s26, s45, s36
	v_lshl_add_u64 v[150:151], s[30:31], 0, v[132:133]
	s_mov_b32 m0, s26
	ds_read_b128 v[194:197], v157 offset:16384
	ds_read_b128 v[198:201], v157 offset:17408
	ds_read_b128 v[202:205], v157 offset:18432
	ds_read_b128 v[206:209], v157 offset:19456
	ds_read_b128 v[210:213], v157 offset:20480
	ds_read_b128 v[214:217], v157 offset:21504
	ds_read_b128 v[218:221], v157 offset:22528
	ds_read_b128 v[222:225], v157 offset:23552
	global_load_lds_dwordx4 v[150:151], off
	s_add_i32 m0, s26, 0x2000
	s_add_u32 s26, s30, 0x40000
	v_lshl_add_u64 v[172:173], s[30:31], 0, v[136:137]
	s_addc_u32 s27, s31, 0
	s_add_i32 s54, s46, s36
	global_load_lds_dwordx4 v[172:173], off
	v_lshl_add_u64 v[226:227], s[26:27], 0, v[132:133]
	s_mov_b32 m0, s54
	v_lshl_add_u64 v[228:229], s[34:35], 0, v[134:135]
	global_load_lds_dwordx4 v[226:227], off
	v_lshl_add_u64 v[226:227], s[26:27], 0, v[136:137]
	s_add_i32 m0, s54, 0x2000
	s_nop 0
	global_load_lds_dwordx4 v[226:227], off
	v_lshl_add_u64 v[226:227], s[34:35], 0, v[130:131]
	s_mov_b32 m0, s37
	s_nop 0
	global_load_lds_dwordx4 v[226:227], off
	s_mov_b32 m0, s38
	s_nop 0
	global_load_lds_dwordx4 v[228:229], off
	s_waitcnt vmcnt(8)
	s_waitcnt lgkmcnt(0)
	s_barrier
	s_setprio 1
	s_waitcnt lgkmcnt(0)
	v_mfma_f32_16x16x32_bf16 v[62:65], v[146:149], v[194:197], v[62:65]
	v_mfma_f32_16x16x32_bf16 v[58:61], v[164:167], v[194:197], v[58:61]
	v_mfma_f32_16x16x32_bf16 v[46:49], v[146:149], v[202:205], v[46:49]
	v_mfma_f32_16x16x32_bf16 v[42:45], v[164:167], v[202:205], v[42:45]
	v_mfma_f32_16x16x32_bf16 v[30:33], v[146:149], v[210:213], v[30:33]
	v_mfma_f32_16x16x32_bf16 v[26:29], v[164:167], v[210:213], v[26:29]
	v_mfma_f32_16x16x32_bf16 v[14:17], v[146:149], v[218:221], v[14:17]
	v_mfma_f32_16x16x32_bf16 v[10:13], v[164:167], v[218:221], v[10:13]
	v_mfma_f32_16x16x32_bf16 v[62:65], v[160:163], v[198:201], v[62:65]
	v_mfma_f32_16x16x32_bf16 v[58:61], v[168:171], v[198:201], v[58:61]
	v_mfma_f32_16x16x32_bf16 v[46:49], v[160:163], v[206:209], v[46:49]
	v_mfma_f32_16x16x32_bf16 v[42:45], v[168:171], v[206:209], v[42:45]
	v_mfma_f32_16x16x32_bf16 v[30:33], v[160:163], v[214:217], v[30:33]
	v_mfma_f32_16x16x32_bf16 v[26:29], v[168:171], v[214:217], v[26:29]
	v_mfma_f32_16x16x32_bf16 v[14:17], v[160:163], v[222:225], v[14:17]
	v_mfma_f32_16x16x32_bf16 v[10:13], v[168:171], v[222:225], v[10:13]
	v_mfma_f32_16x16x32_bf16 v[54:57], v[178:181], v[194:197], v[54:57]
	v_mfma_f32_16x16x32_bf16 v[50:53], v[186:189], v[194:197], v[50:53]
	v_mfma_f32_16x16x32_bf16 v[38:41], v[178:181], v[202:205], v[38:41]
	v_mfma_f32_16x16x32_bf16 v[34:37], v[186:189], v[202:205], v[34:37]
	v_mfma_f32_16x16x32_bf16 v[22:25], v[178:181], v[210:213], v[22:25]
	v_mfma_f32_16x16x32_bf16 v[18:21], v[186:189], v[210:213], v[18:21]
	v_mfma_f32_16x16x32_bf16 v[6:9], v[178:181], v[218:221], v[6:9]
	v_mfma_f32_16x16x32_bf16 v[2:5], v[186:189], v[218:221], v[2:5]
	v_mfma_f32_16x16x32_bf16 v[54:57], v[182:185], v[198:201], v[54:57]
	v_mfma_f32_16x16x32_bf16 v[50:53], v[190:193], v[198:201], v[50:53]
	v_mfma_f32_16x16x32_bf16 v[38:41], v[182:185], v[206:209], v[38:41]
	v_mfma_f32_16x16x32_bf16 v[34:37], v[190:193], v[206:209], v[34:37]
	v_mfma_f32_16x16x32_bf16 v[22:25], v[182:185], v[214:217], v[22:25]
	v_mfma_f32_16x16x32_bf16 v[18:21], v[190:193], v[214:217], v[18:21]
	v_mfma_f32_16x16x32_bf16 v[6:9], v[182:185], v[222:225], v[6:9]
	v_mfma_f32_16x16x32_bf16 v[2:5], v[190:193], v[222:225], v[2:5]
	s_setprio 0
	s_barrier
	s_add_i32 s54, 0, 0x18000
	s_add_i32 s55, 0, 0x1c000
	v_add_u32_e32 v168, s54, v153
	v_add_u32_e32 v177, s55, v153
	ds_read_b128 v[146:149], v168
	ds_read_b128 v[160:163], v168 offset:1024
	ds_read_b128 v[164:167], v168 offset:2048
	ds_read_b128 v[168:171], v168 offset:3072
	ds_read_b128 v[178:181], v177
	ds_read_b128 v[182:185], v177 offset:1024
	ds_read_b128 v[186:189], v177 offset:2048
	ds_read_b128 v[190:193], v177 offset:3072
	s_add_u32 s26, s34, 0x40000
	s_addc_u32 s27, s35, 0
	s_mov_b32 m0, s39
	v_lshl_add_u64 v[230:231], s[26:27], 0, v[130:131]
	ds_read_b128 v[194:197], v157 offset:32768
	ds_read_b128 v[198:201], v157 offset:33792
	ds_read_b128 v[202:205], v157 offset:34816
	ds_read_b128 v[206:209], v157 offset:35840
	ds_read_b128 v[210:213], v157 offset:36864
	ds_read_b128 v[214:217], v157 offset:37888
	ds_read_b128 v[218:221], v157 offset:38912
	ds_read_b128 v[222:225], v157 offset:39936
	global_load_lds_dwordx4 v[230:231], off
	v_lshl_add_u64 v[230:231], s[26:27], 0, v[134:135]
	s_mov_b32 m0, s40
	s_nop 0
	global_load_lds_dwordx4 v[230:231], off
	s_waitcnt vmcnt(8)
	s_waitcnt lgkmcnt(0)
	s_barrier
	s_setprio 1
	s_waitcnt lgkmcnt(0)
	v_mfma_f32_16x16x32_bf16 v[126:129], v[146:149], v[194:197], v[126:129]
	v_mfma_f32_16x16x32_bf16 v[122:125], v[164:167], v[194:197], v[122:125]
	v_mfma_f32_16x16x32_bf16 v[110:113], v[146:149], v[202:205], v[110:113]
	v_mfma_f32_16x16x32_bf16 v[106:109], v[164:167], v[202:205], v[106:109]
	v_mfma_f32_16x16x32_bf16 v[94:97], v[146:149], v[210:213], v[94:97]
	v_mfma_f32_16x16x32_bf16 v[90:93], v[164:167], v[210:213], v[90:93]
	v_mfma_f32_16x16x32_bf16 v[78:81], v[146:149], v[218:221], v[78:81]
	v_mfma_f32_16x16x32_bf16 v[74:77], v[164:167], v[218:221], v[74:77]
	v_mfma_f32_16x16x32_bf16 v[126:129], v[160:163], v[198:201], v[126:129]
	v_mfma_f32_16x16x32_bf16 v[122:125], v[168:171], v[198:201], v[122:125]
	v_mfma_f32_16x16x32_bf16 v[110:113], v[160:163], v[206:209], v[110:113]
	v_mfma_f32_16x16x32_bf16 v[106:109], v[168:171], v[206:209], v[106:109]
	v_mfma_f32_16x16x32_bf16 v[94:97], v[160:163], v[214:217], v[94:97]
	v_mfma_f32_16x16x32_bf16 v[90:93], v[168:171], v[214:217], v[90:93]
	v_mfma_f32_16x16x32_bf16 v[78:81], v[160:163], v[222:225], v[78:81]
	v_mfma_f32_16x16x32_bf16 v[74:77], v[168:171], v[222:225], v[74:77]
	v_mfma_f32_16x16x32_bf16 v[118:121], v[178:181], v[194:197], v[118:121]
	v_mfma_f32_16x16x32_bf16 v[114:117], v[186:189], v[194:197], v[114:117]
	v_mfma_f32_16x16x32_bf16 v[102:105], v[178:181], v[202:205], v[102:105]
	v_mfma_f32_16x16x32_bf16 v[98:101], v[186:189], v[202:205], v[98:101]
	v_mfma_f32_16x16x32_bf16 v[86:89], v[178:181], v[210:213], v[86:89]
	v_mfma_f32_16x16x32_bf16 v[82:85], v[186:189], v[210:213], v[82:85]
	v_mfma_f32_16x16x32_bf16 v[70:73], v[178:181], v[218:221], v[70:73]
	v_mfma_f32_16x16x32_bf16 v[66:69], v[186:189], v[218:221], v[66:69]
	v_mfma_f32_16x16x32_bf16 v[118:121], v[182:185], v[198:201], v[118:121]
	v_mfma_f32_16x16x32_bf16 v[114:117], v[190:193], v[198:201], v[114:117]
	v_mfma_f32_16x16x32_bf16 v[102:105], v[182:185], v[206:209], v[102:105]
	v_mfma_f32_16x16x32_bf16 v[98:101], v[190:193], v[206:209], v[98:101]
	v_mfma_f32_16x16x32_bf16 v[86:89], v[182:185], v[214:217], v[86:89]
	v_mfma_f32_16x16x32_bf16 v[82:85], v[190:193], v[214:217], v[82:85]
	v_mfma_f32_16x16x32_bf16 v[70:73], v[182:185], v[222:225], v[70:73]
	v_mfma_f32_16x16x32_bf16 v[66:69], v[190:193], v[222:225], v[66:69]
	s_setprio 0
	s_barrier
	s_add_i32 s26, s54, s36
	v_lshl_add_u64 v[150:151], v[150:151], 0, s[10:11]
	s_mov_b32 m0, s26
	ds_read_b128 v[194:197], v157 offset:49152
	ds_read_b128 v[198:201], v157 offset:50176
	ds_read_b128 v[202:205], v157 offset:51200
	ds_read_b128 v[206:209], v157 offset:52224
	ds_read_b128 v[210:213], v157 offset:53248
	ds_read_b128 v[214:217], v157 offset:54272
	ds_read_b128 v[218:221], v157 offset:55296
	ds_read_b128 v[222:225], v157 offset:56320
	global_load_lds_dwordx4 v[150:151], off
	s_add_i32 m0, s26, 0x2000
	s_add_u32 s26, s30, 0x40080
	v_lshl_add_u64 v[150:151], v[172:173], 0, s[10:11]
	s_addc_u32 s27, s31, 0
	s_add_i32 s30, s55, s36
	global_load_lds_dwordx4 v[150:151], off
	v_lshl_add_u64 v[150:151], s[26:27], 0, v[132:133]
	s_mov_b32 m0, s30
	s_nop 0
	global_load_lds_dwordx4 v[150:151], off
	v_lshl_add_u64 v[150:151], s[26:27], 0, v[136:137]
	s_add_i32 m0, s30, 0x2000
	s_nop 0
	global_load_lds_dwordx4 v[150:151], off
	v_lshl_add_u64 v[150:151], v[226:227], 0, s[10:11]
	s_mov_b32 m0, s42
	s_nop 0
	global_load_lds_dwordx4 v[150:151], off
	v_lshl_add_u64 v[150:151], v[228:229], 0, s[10:11]
	s_mov_b32 m0, s43
	s_nop 0
	global_load_lds_dwordx4 v[150:151], off
	s_waitcnt vmcnt(8)
	s_waitcnt lgkmcnt(0)
	s_barrier
	s_setprio 1
	s_waitcnt lgkmcnt(0)
	v_mfma_f32_16x16x32_bf16 v[62:65], v[146:149], v[194:197], v[62:65]
	v_mfma_f32_16x16x32_bf16 v[58:61], v[164:167], v[194:197], v[58:61]
	v_mfma_f32_16x16x32_bf16 v[46:49], v[146:149], v[202:205], v[46:49]
	v_mfma_f32_16x16x32_bf16 v[42:45], v[164:167], v[202:205], v[42:45]
	v_mfma_f32_16x16x32_bf16 v[30:33], v[146:149], v[210:213], v[30:33]
	v_mfma_f32_16x16x32_bf16 v[26:29], v[164:167], v[210:213], v[26:29]
	v_mfma_f32_16x16x32_bf16 v[14:17], v[146:149], v[218:221], v[14:17]
	v_mfma_f32_16x16x32_bf16 v[10:13], v[164:167], v[218:221], v[10:13]
	v_mfma_f32_16x16x32_bf16 v[62:65], v[160:163], v[198:201], v[62:65]
	v_mfma_f32_16x16x32_bf16 v[58:61], v[168:171], v[198:201], v[58:61]
	v_mfma_f32_16x16x32_bf16 v[46:49], v[160:163], v[206:209], v[46:49]
	v_mfma_f32_16x16x32_bf16 v[42:45], v[168:171], v[206:209], v[42:45]
	v_mfma_f32_16x16x32_bf16 v[30:33], v[160:163], v[214:217], v[30:33]
	v_mfma_f32_16x16x32_bf16 v[26:29], v[168:171], v[214:217], v[26:29]
	v_mfma_f32_16x16x32_bf16 v[14:17], v[160:163], v[222:225], v[14:17]
	v_mfma_f32_16x16x32_bf16 v[10:13], v[168:171], v[222:225], v[10:13]
	v_mfma_f32_16x16x32_bf16 v[54:57], v[178:181], v[194:197], v[54:57]
	v_mfma_f32_16x16x32_bf16 v[50:53], v[186:189], v[194:197], v[50:53]
	v_mfma_f32_16x16x32_bf16 v[38:41], v[178:181], v[202:205], v[38:41]
	v_mfma_f32_16x16x32_bf16 v[34:37], v[186:189], v[202:205], v[34:37]
	v_mfma_f32_16x16x32_bf16 v[22:25], v[178:181], v[210:213], v[22:25]
	v_mfma_f32_16x16x32_bf16 v[18:21], v[186:189], v[210:213], v[18:21]
	v_mfma_f32_16x16x32_bf16 v[6:9], v[178:181], v[218:221], v[6:9]
	v_mfma_f32_16x16x32_bf16 v[2:5], v[186:189], v[218:221], v[2:5]
	v_mfma_f32_16x16x32_bf16 v[54:57], v[182:185], v[198:201], v[54:57]
	v_mfma_f32_16x16x32_bf16 v[50:53], v[190:193], v[198:201], v[50:53]
	v_mfma_f32_16x16x32_bf16 v[38:41], v[182:185], v[206:209], v[38:41]
	v_mfma_f32_16x16x32_bf16 v[34:37], v[190:193], v[206:209], v[34:37]
	v_mfma_f32_16x16x32_bf16 v[22:25], v[182:185], v[214:217], v[22:25]
	v_mfma_f32_16x16x32_bf16 v[18:21], v[190:193], v[214:217], v[18:21]
	v_mfma_f32_16x16x32_bf16 v[6:9], v[182:185], v[222:225], v[6:9]
	v_mfma_f32_16x16x32_bf16 v[2:5], v[190:193], v[222:225], v[2:5]
	s_setprio 0
	s_barrier
	s_add_i32 s53, s53, 2
	s_add_u32 s51, s51, 0x100
	s_addc_u32 s52, s52, 0
	s_cmp_gt_u32 s53, 13
	s_mov_b64 s[26:27], s[28:29]
	s_cbranch_scc0 .LBB0_1590

.LBB0_1683:
	s_add_u32 s49, s28, 0x100
	s_addc_u32 s50, s29, 0
	s_mov_b32 s51, -2
	s_waitcnt lgkmcnt(0)
	ds_read_b128 v[144:147], v151
	ds_read_b128 v[156:159], v151 offset:1024
	ds_read_b128 v[160:163], v151 offset:2048
	ds_read_b128 v[164:167], v151 offset:3072
	ds_read_b128 v[168:171], v152
	ds_read_b128 v[176:179], v152 offset:1024
	ds_read_b128 v[180:183], v152 offset:2048
	ds_read_b128 v[184:187], v152 offset:3072
	s_add_u32 s28, s26, 0x100
	s_addc_u32 s29, s27, 0
	s_cmp_eq_u32 s51, 40
	s_cselect_b32 s35, s7, s29
	s_cselect_b32 s34, s6, s28
	s_cselect_b32 s31, s25, s50
	s_cselect_b32 s30, s24, s49
	v_lshl_add_u64 v[172:173], s[26:27], 0, v[136:137]
	s_add_i32 m0, s16, 0xc000
	ds_read_b128 v[188:191], v153
	ds_read_b128 v[192:195], v153 offset:1024
	ds_read_b128 v[196:199], v153 offset:2048
	ds_read_b128 v[200:203], v153 offset:3072
	ds_read_b128 v[204:207], v153 offset:4096
	ds_read_b128 v[208:211], v153 offset:5120
	ds_read_b128 v[212:215], v153 offset:6144
	ds_read_b128 v[216:219], v153 offset:7168
	global_load_lds_dwordx4 v[172:173], off
	v_lshl_add_u64 v[172:173], s[26:27], 0, v[138:139]
	s_add_i32 m0, s16, 0xe000
	s_nop 0
	global_load_lds_dwordx4 v[172:173], off
	s_waitcnt vmcnt(8)
	s_waitcnt lgkmcnt(0)
	s_barrier
	s_setprio 1
	s_waitcnt lgkmcnt(0)
	v_mfma_f32_16x16x32_bf16 v[124:127], v[144:147], v[188:191], 0
	v_mfma_f32_16x16x32_bf16 v[120:123], v[160:163], v[188:191], 0
	v_mfma_f32_16x16x32_bf16 v[108:111], v[144:147], v[196:199], 0
	v_mfma_f32_16x16x32_bf16 v[104:107], v[160:163], v[196:199], 0
	v_mfma_f32_16x16x32_bf16 v[92:95], v[144:147], v[204:207], 0
	v_mfma_f32_16x16x32_bf16 v[88:91], v[160:163], v[204:207], 0
	v_mfma_f32_16x16x32_bf16 v[76:79], v[144:147], v[212:215], 0
	v_mfma_f32_16x16x32_bf16 v[72:75], v[160:163], v[212:215], 0
	v_mfma_f32_16x16x32_bf16 v[124:127], v[156:159], v[192:195], v[124:127]
	v_mfma_f32_16x16x32_bf16 v[120:123], v[164:167], v[192:195], v[120:123]
	v_mfma_f32_16x16x32_bf16 v[108:111], v[156:159], v[200:203], v[108:111]
	v_mfma_f32_16x16x32_bf16 v[104:107], v[164:167], v[200:203], v[104:107]
	v_mfma_f32_16x16x32_bf16 v[92:95], v[156:159], v[208:211], v[92:95]
	v_mfma_f32_16x16x32_bf16 v[88:91], v[164:167], v[208:211], v[88:91]
	v_mfma_f32_16x16x32_bf16 v[76:79], v[156:159], v[216:219], v[76:79]
	v_mfma_f32_16x16x32_bf16 v[72:75], v[164:167], v[216:219], v[72:75]
	v_mfma_f32_16x16x32_bf16 v[116:119], v[168:171], v[188:191], 0
	v_mfma_f32_16x16x32_bf16 v[112:115], v[180:183], v[188:191], 0
	v_mfma_f32_16x16x32_bf16 v[100:103], v[168:171], v[196:199], 0
	v_mfma_f32_16x16x32_bf16 v[96:99], v[180:183], v[196:199], 0
	v_mfma_f32_16x16x32_bf16 v[84:87], v[168:171], v[204:207], 0
	v_mfma_f32_16x16x32_bf16 v[80:83], v[180:183], v[204:207], 0
	v_mfma_f32_16x16x32_bf16 v[68:71], v[168:171], v[212:215], 0
	v_mfma_f32_16x16x32_bf16 v[64:67], v[180:183], v[212:215], 0
	v_mfma_f32_16x16x32_bf16 v[116:119], v[176:179], v[192:195], v[116:119]
	v_mfma_f32_16x16x32_bf16 v[112:115], v[184:187], v[192:195], v[112:115]
	v_mfma_f32_16x16x32_bf16 v[100:103], v[176:179], v[200:203], v[100:103]
	v_mfma_f32_16x16x32_bf16 v[96:99], v[184:187], v[200:203], v[96:99]
	v_mfma_f32_16x16x32_bf16 v[84:87], v[176:179], v[208:211], v[84:87]
	v_mfma_f32_16x16x32_bf16 v[80:83], v[184:187], v[208:211], v[80:83]
	v_mfma_f32_16x16x32_bf16 v[68:71], v[176:179], v[216:219], v[68:71]
	v_mfma_f32_16x16x32_bf16 v[64:67], v[184:187], v[216:219], v[64:67]
	s_setprio 0
	s_barrier
	s_add_i32 s26, s43, s15
	v_lshl_add_u64 v[172:173], s[30:31], 0, v[130:131]
	s_mov_b32 m0, s26
	ds_read_b128 v[188:191], v153 offset:16384
	ds_read_b128 v[192:195], v153 offset:17408
	ds_read_b128 v[196:199], v153 offset:18432
	ds_read_b128 v[200:203], v153 offset:19456
	ds_read_b128 v[204:207], v153 offset:20480
	ds_read_b128 v[208:211], v153 offset:21504
	ds_read_b128 v[212:215], v153 offset:22528
	ds_read_b128 v[216:219], v153 offset:23552
	global_load_lds_dwordx4 v[172:173], off
	s_add_i32 m0, s26, 0x2000
	s_add_u32 s26, s30, 0xb0000
	v_lshl_add_u64 v[220:221], s[30:31], 0, v[134:135]
	s_addc_u32 s27, s31, 0
	s_add_i32 s52, s44, s15
	global_load_lds_dwordx4 v[220:221], off
	v_lshl_add_u64 v[222:223], s[26:27], 0, v[130:131]
	s_mov_b32 m0, s52
	v_lshl_add_u64 v[224:225], s[34:35], 0, v[132:133]
	global_load_lds_dwordx4 v[222:223], off
	v_lshl_add_u64 v[222:223], s[26:27], 0, v[134:135]
	s_add_i32 m0, s52, 0x2000
	s_nop 0
	global_load_lds_dwordx4 v[222:223], off
	v_lshl_add_u64 v[222:223], s[34:35], 0, v[128:129]
	s_mov_b32 m0, s16
	s_nop 0
	global_load_lds_dwordx4 v[222:223], off
	s_mov_b32 m0, s17
	s_nop 0
	global_load_lds_dwordx4 v[224:225], off
	s_waitcnt vmcnt(8)
	s_waitcnt lgkmcnt(0)
	s_barrier
	s_setprio 1
	s_waitcnt lgkmcnt(0)
	v_mfma_f32_16x16x32_bf16 v[60:63], v[144:147], v[188:191], 0
	v_mfma_f32_16x16x32_bf16 v[56:59], v[160:163], v[188:191], 0
	v_mfma_f32_16x16x32_bf16 v[44:47], v[144:147], v[196:199], 0
	v_mfma_f32_16x16x32_bf16 v[40:43], v[160:163], v[196:199], 0
	v_mfma_f32_16x16x32_bf16 v[28:31], v[144:147], v[204:207], 0
	v_mfma_f32_16x16x32_bf16 v[24:27], v[160:163], v[204:207], 0
	v_mfma_f32_16x16x32_bf16 v[12:15], v[144:147], v[212:215], 0
	v_mfma_f32_16x16x32_bf16 v[8:11], v[160:163], v[212:215], 0
	v_mfma_f32_16x16x32_bf16 v[60:63], v[156:159], v[192:195], v[60:63]
	v_mfma_f32_16x16x32_bf16 v[56:59], v[164:167], v[192:195], v[56:59]
	v_mfma_f32_16x16x32_bf16 v[44:47], v[156:159], v[200:203], v[44:47]
	v_mfma_f32_16x16x32_bf16 v[40:43], v[164:167], v[200:203], v[40:43]
	v_mfma_f32_16x16x32_bf16 v[28:31], v[156:159], v[208:211], v[28:31]
	v_mfma_f32_16x16x32_bf16 v[24:27], v[164:167], v[208:211], v[24:27]
	v_mfma_f32_16x16x32_bf16 v[12:15], v[156:159], v[216:219], v[12:15]
	v_mfma_f32_16x16x32_bf16 v[8:11], v[164:167], v[216:219], v[8:11]
	v_mfma_f32_16x16x32_bf16 v[52:55], v[168:171], v[188:191], 0
	v_mfma_f32_16x16x32_bf16 v[48:51], v[180:183], v[188:191], 0
	v_mfma_f32_16x16x32_bf16 v[36:39], v[168:171], v[196:199], 0
	v_mfma_f32_16x16x32_bf16 v[32:35], v[180:183], v[196:199], 0
	v_mfma_f32_16x16x32_bf16 v[20:23], v[168:171], v[204:207], 0
	v_mfma_f32_16x16x32_bf16 v[16:19], v[180:183], v[204:207], 0
	v_mfma_f32_16x16x32_bf16 v[4:7], v[168:171], v[212:215], 0
	v_mfma_f32_16x16x32_bf16 v[0:3], v[180:183], v[212:215], 0
	v_mfma_f32_16x16x32_bf16 v[52:55], v[176:179], v[192:195], v[52:55]
	v_mfma_f32_16x16x32_bf16 v[48:51], v[184:187], v[192:195], v[48:51]
	v_mfma_f32_16x16x32_bf16 v[36:39], v[176:179], v[200:203], v[36:39]
	v_mfma_f32_16x16x32_bf16 v[32:35], v[184:187], v[200:203], v[32:35]
	v_mfma_f32_16x16x32_bf16 v[20:23], v[176:179], v[208:211], v[20:23]
	v_mfma_f32_16x16x32_bf16 v[16:19], v[184:187], v[208:211], v[16:19]
	v_mfma_f32_16x16x32_bf16 v[4:7], v[176:179], v[216:219], v[4:7]
	v_mfma_f32_16x16x32_bf16 v[0:3], v[184:187], v[216:219], v[0:3]
	s_setprio 0
	s_barrier
	s_add_i32 s52, 0, 0x18000
	v_add_u32_e32 v155, s52, v149
	s_add_i32 s53, 0, 0x1c000
	ds_read_b128 v[144:147], v155
	ds_read_b128 v[156:159], v155 offset:1024
	ds_read_b128 v[160:163], v155 offset:2048
	ds_read_b128 v[164:167], v155 offset:3072
	v_add_u32_e32 v155, s53, v149
	ds_read_b128 v[168:171], v155
	ds_read_b128 v[176:179], v155 offset:1024
	ds_read_b128 v[180:183], v155 offset:2048
	ds_read_b128 v[184:187], v155 offset:3072
	s_add_u32 s26, s34, 0xb0000
	s_addc_u32 s27, s35, 0
	s_mov_b32 m0, s36
	v_lshl_add_u64 v[226:227], s[26:27], 0, v[128:129]
	ds_read_b128 v[188:191], v153 offset:32768
	ds_read_b128 v[192:195], v153 offset:33792
	ds_read_b128 v[196:199], v153 offset:34816
	ds_read_b128 v[200:203], v153 offset:35840
	ds_read_b128 v[204:207], v153 offset:36864
	ds_read_b128 v[208:211], v153 offset:37888
	ds_read_b128 v[212:215], v153 offset:38912
	ds_read_b128 v[216:219], v153 offset:39936
	global_load_lds_dwordx4 v[226:227], off
	v_lshl_add_u64 v[226:227], s[26:27], 0, v[132:133]
	s_mov_b32 m0, s37
	s_nop 0
	global_load_lds_dwordx4 v[226:227], off
	s_waitcnt vmcnt(8)
	s_waitcnt lgkmcnt(0)
	s_barrier
	s_setprio 1
	s_waitcnt lgkmcnt(0)
	v_mfma_f32_16x16x32_bf16 v[124:127], v[144:147], v[188:191], v[124:127]
	v_mfma_f32_16x16x32_bf16 v[120:123], v[160:163], v[188:191], v[120:123]
	v_mfma_f32_16x16x32_bf16 v[108:111], v[144:147], v[196:199], v[108:111]
	v_mfma_f32_16x16x32_bf16 v[104:107], v[160:163], v[196:199], v[104:107]
	v_mfma_f32_16x16x32_bf16 v[92:95], v[144:147], v[204:207], v[92:95]
	v_mfma_f32_16x16x32_bf16 v[88:91], v[160:163], v[204:207], v[88:91]
	v_mfma_f32_16x16x32_bf16 v[76:79], v[144:147], v[212:215], v[76:79]
	v_mfma_f32_16x16x32_bf16 v[72:75], v[160:163], v[212:215], v[72:75]
	v_mfma_f32_16x16x32_bf16 v[124:127], v[156:159], v[192:195], v[124:127]
	v_mfma_f32_16x16x32_bf16 v[120:123], v[164:167], v[192:195], v[120:123]
	v_mfma_f32_16x16x32_bf16 v[108:111], v[156:159], v[200:203], v[108:111]
	v_mfma_f32_16x16x32_bf16 v[104:107], v[164:167], v[200:203], v[104:107]
	v_mfma_f32_16x16x32_bf16 v[92:95], v[156:159], v[208:211], v[92:95]
	v_mfma_f32_16x16x32_bf16 v[88:91], v[164:167], v[208:211], v[88:91]
	v_mfma_f32_16x16x32_bf16 v[76:79], v[156:159], v[216:219], v[76:79]
	v_mfma_f32_16x16x32_bf16 v[72:75], v[164:167], v[216:219], v[72:75]
	v_mfma_f32_16x16x32_bf16 v[116:119], v[168:171], v[188:191], v[116:119]
	v_mfma_f32_16x16x32_bf16 v[112:115], v[180:183], v[188:191], v[112:115]
	v_mfma_f32_16x16x32_bf16 v[100:103], v[168:171], v[196:199], v[100:103]
	v_mfma_f32_16x16x32_bf16 v[96:99], v[180:183], v[196:199], v[96:99]
	v_mfma_f32_16x16x32_bf16 v[84:87], v[168:171], v[204:207], v[84:87]
	v_mfma_f32_16x16x32_bf16 v[80:83], v[180:183], v[204:207], v[80:83]
	v_mfma_f32_16x16x32_bf16 v[68:71], v[168:171], v[212:215], v[68:71]
	v_mfma_f32_16x16x32_bf16 v[64:67], v[180:183], v[212:215], v[64:67]
	v_mfma_f32_16x16x32_bf16 v[116:119], v[176:179], v[192:195], v[116:119]
	v_mfma_f32_16x16x32_bf16 v[112:115], v[184:187], v[192:195], v[112:115]
	v_mfma_f32_16x16x32_bf16 v[100:103], v[176:179], v[200:203], v[100:103]
	v_mfma_f32_16x16x32_bf16 v[96:99], v[184:187], v[200:203], v[96:99]
	v_mfma_f32_16x16x32_bf16 v[84:87], v[176:179], v[208:211], v[84:87]
	v_mfma_f32_16x16x32_bf16 v[80:83], v[184:187], v[208:211], v[80:83]
	v_mfma_f32_16x16x32_bf16 v[68:71], v[176:179], v[216:219], v[68:71]
	v_mfma_f32_16x16x32_bf16 v[64:67], v[184:187], v[216:219], v[64:67]
	s_setprio 0
	s_barrier
	s_add_i32 s26, s52, s15
	v_lshl_add_u64 v[172:173], v[172:173], 0, s[20:21]
	s_mov_b32 m0, s26
	ds_read_b128 v[188:191], v153 offset:49152
	ds_read_b128 v[192:195], v153 offset:50176
	ds_read_b128 v[196:199], v153 offset:51200
	ds_read_b128 v[200:203], v153 offset:52224
	ds_read_b128 v[204:207], v153 offset:53248
	ds_read_b128 v[208:211], v153 offset:54272
	ds_read_b128 v[212:215], v153 offset:55296
	ds_read_b128 v[216:219], v153 offset:56320
	global_load_lds_dwordx4 v[172:173], off
	s_add_i32 m0, s26, 0x2000
	s_add_u32 s26, s30, 0xb0080
	v_lshl_add_u64 v[172:173], v[220:221], 0, s[20:21]
	s_addc_u32 s27, s31, 0
	s_add_i32 s30, s53, s15
	global_load_lds_dwordx4 v[172:173], off
	v_lshl_add_u64 v[172:173], s[26:27], 0, v[130:131]
	s_mov_b32 m0, s30
	s_nop 0
	global_load_lds_dwordx4 v[172:173], off
	v_lshl_add_u64 v[172:173], s[26:27], 0, v[134:135]
	s_add_i32 m0, s30, 0x2000
	s_nop 0
	global_load_lds_dwordx4 v[172:173], off
	v_lshl_add_u64 v[172:173], v[222:223], 0, s[20:21]
	s_mov_b32 m0, s39
	s_nop 0
	global_load_lds_dwordx4 v[172:173], off
	v_lshl_add_u64 v[172:173], v[224:225], 0, s[20:21]
	s_mov_b32 m0, s40
	s_nop 0
	global_load_lds_dwordx4 v[172:173], off
	s_waitcnt vmcnt(8)
	s_waitcnt lgkmcnt(0)
	s_barrier
	s_setprio 1
	s_waitcnt lgkmcnt(0)
	v_mfma_f32_16x16x32_bf16 v[60:63], v[144:147], v[188:191], v[60:63]
	v_mfma_f32_16x16x32_bf16 v[56:59], v[160:163], v[188:191], v[56:59]
	v_mfma_f32_16x16x32_bf16 v[44:47], v[144:147], v[196:199], v[44:47]
	v_mfma_f32_16x16x32_bf16 v[40:43], v[160:163], v[196:199], v[40:43]
	v_mfma_f32_16x16x32_bf16 v[28:31], v[144:147], v[204:207], v[28:31]
	v_mfma_f32_16x16x32_bf16 v[24:27], v[160:163], v[204:207], v[24:27]
	v_mfma_f32_16x16x32_bf16 v[12:15], v[144:147], v[212:215], v[12:15]
	v_mfma_f32_16x16x32_bf16 v[8:11], v[160:163], v[212:215], v[8:11]
	v_mfma_f32_16x16x32_bf16 v[60:63], v[156:159], v[192:195], v[60:63]
	v_mfma_f32_16x16x32_bf16 v[56:59], v[164:167], v[192:195], v[56:59]
	v_mfma_f32_16x16x32_bf16 v[44:47], v[156:159], v[200:203], v[44:47]
	v_mfma_f32_16x16x32_bf16 v[40:43], v[164:167], v[200:203], v[40:43]
	v_mfma_f32_16x16x32_bf16 v[28:31], v[156:159], v[208:211], v[28:31]
	v_mfma_f32_16x16x32_bf16 v[24:27], v[164:167], v[208:211], v[24:27]
	v_mfma_f32_16x16x32_bf16 v[12:15], v[156:159], v[216:219], v[12:15]
	v_mfma_f32_16x16x32_bf16 v[8:11], v[164:167], v[216:219], v[8:11]
	v_mfma_f32_16x16x32_bf16 v[52:55], v[168:171], v[188:191], v[52:55]
	v_mfma_f32_16x16x32_bf16 v[48:51], v[180:183], v[188:191], v[48:51]
	v_mfma_f32_16x16x32_bf16 v[36:39], v[168:171], v[196:199], v[36:39]
	v_mfma_f32_16x16x32_bf16 v[32:35], v[180:183], v[196:199], v[32:35]
	v_mfma_f32_16x16x32_bf16 v[20:23], v[168:171], v[204:207], v[20:23]
	v_mfma_f32_16x16x32_bf16 v[16:19], v[180:183], v[204:207], v[16:19]
	v_mfma_f32_16x16x32_bf16 v[4:7], v[168:171], v[212:215], v[4:7]
	v_mfma_f32_16x16x32_bf16 v[0:3], v[180:183], v[212:215], v[0:3]
	v_mfma_f32_16x16x32_bf16 v[52:55], v[176:179], v[192:195], v[52:55]
	v_mfma_f32_16x16x32_bf16 v[48:51], v[184:187], v[192:195], v[48:51]
	v_mfma_f32_16x16x32_bf16 v[36:39], v[176:179], v[200:203], v[36:39]
	v_mfma_f32_16x16x32_bf16 v[32:35], v[184:187], v[200:203], v[32:35]
	v_mfma_f32_16x16x32_bf16 v[20:23], v[176:179], v[208:211], v[20:23]
	v_mfma_f32_16x16x32_bf16 v[16:19], v[184:187], v[208:211], v[16:19]
	v_mfma_f32_16x16x32_bf16 v[4:7], v[176:179], v[216:219], v[4:7]
	v_mfma_f32_16x16x32_bf16 v[0:3], v[184:187], v[216:219], v[0:3]
	s_setprio 0
	s_barrier
	s_add_i32 s51, s51, 2
	s_add_u32 s49, s49, 0x100
	s_addc_u32 s50, s50, 0
	s_cmp_gt_u32 s51, 41
	s_mov_b64 s[26:27], s[28:29]
	s_cbranch_scc0 .LBB0_1684
	s_branch .Lpeel_exit_1684
.LBB0_1684:
	ds_read_b128 v[144:147], v151
	ds_read_b128 v[156:159], v151 offset:1024
	ds_read_b128 v[160:163], v151 offset:2048
	ds_read_b128 v[164:167], v151 offset:3072
	ds_read_b128 v[168:171], v152
	ds_read_b128 v[176:179], v152 offset:1024
	ds_read_b128 v[180:183], v152 offset:2048
	ds_read_b128 v[184:187], v152 offset:3072
	s_add_u32 s28, s26, 0x100
	s_addc_u32 s29, s27, 0
	s_cmp_eq_u32 s51, 40
	s_cselect_b32 s35, s7, s29
	s_cselect_b32 s34, s6, s28
	s_cselect_b32 s31, s25, s50
	s_cselect_b32 s30, s24, s49
	v_lshl_add_u64 v[172:173], s[26:27], 0, v[136:137]
	s_add_i32 m0, s16, 0xc000
	ds_read_b128 v[188:191], v153
	ds_read_b128 v[192:195], v153 offset:1024
	ds_read_b128 v[196:199], v153 offset:2048
	ds_read_b128 v[200:203], v153 offset:3072
	ds_read_b128 v[204:207], v153 offset:4096
	ds_read_b128 v[208:211], v153 offset:5120
	ds_read_b128 v[212:215], v153 offset:6144
	ds_read_b128 v[216:219], v153 offset:7168
	global_load_lds_dwordx4 v[172:173], off
	v_lshl_add_u64 v[172:173], s[26:27], 0, v[138:139]
	s_add_i32 m0, s16, 0xe000
	s_nop 0
	global_load_lds_dwordx4 v[172:173], off
	s_waitcnt vmcnt(8)
	s_waitcnt lgkmcnt(0)
	s_barrier
	s_setprio 1
	s_waitcnt lgkmcnt(0)
	v_mfma_f32_16x16x32_bf16 v[124:127], v[144:147], v[188:191], v[124:127]
	v_mfma_f32_16x16x32_bf16 v[120:123], v[160:163], v[188:191], v[120:123]
	v_mfma_f32_16x16x32_bf16 v[108:111], v[144:147], v[196:199], v[108:111]
	v_mfma_f32_16x16x32_bf16 v[104:107], v[160:163], v[196:199], v[104:107]
	v_mfma_f32_16x16x32_bf16 v[92:95], v[144:147], v[204:207], v[92:95]
	v_mfma_f32_16x16x32_bf16 v[88:91], v[160:163], v[204:207], v[88:91]
	v_mfma_f32_16x16x32_bf16 v[76:79], v[144:147], v[212:215], v[76:79]
	v_mfma_f32_16x16x32_bf16 v[72:75], v[160:163], v[212:215], v[72:75]
	v_mfma_f32_16x16x32_bf16 v[124:127], v[156:159], v[192:195], v[124:127]
	v_mfma_f32_16x16x32_bf16 v[120:123], v[164:167], v[192:195], v[120:123]
	v_mfma_f32_16x16x32_bf16 v[108:111], v[156:159], v[200:203], v[108:111]
	v_mfma_f32_16x16x32_bf16 v[104:107], v[164:167], v[200:203], v[104:107]
	v_mfma_f32_16x16x32_bf16 v[92:95], v[156:159], v[208:211], v[92:95]
	v_mfma_f32_16x16x32_bf16 v[88:91], v[164:167], v[208:211], v[88:91]
	v_mfma_f32_16x16x32_bf16 v[76:79], v[156:159], v[216:219], v[76:79]
	v_mfma_f32_16x16x32_bf16 v[72:75], v[164:167], v[216:219], v[72:75]
	v_mfma_f32_16x16x32_bf16 v[116:119], v[168:171], v[188:191], v[116:119]
	v_mfma_f32_16x16x32_bf16 v[112:115], v[180:183], v[188:191], v[112:115]
	v_mfma_f32_16x16x32_bf16 v[100:103], v[168:171], v[196:199], v[100:103]
	v_mfma_f32_16x16x32_bf16 v[96:99], v[180:183], v[196:199], v[96:99]
	v_mfma_f32_16x16x32_bf16 v[84:87], v[168:171], v[204:207], v[84:87]
	v_mfma_f32_16x16x32_bf16 v[80:83], v[180:183], v[204:207], v[80:83]
	v_mfma_f32_16x16x32_bf16 v[68:71], v[168:171], v[212:215], v[68:71]
	v_mfma_f32_16x16x32_bf16 v[64:67], v[180:183], v[212:215], v[64:67]
	v_mfma_f32_16x16x32_bf16 v[116:119], v[176:179], v[192:195], v[116:119]
	v_mfma_f32_16x16x32_bf16 v[112:115], v[184:187], v[192:195], v[112:115]
	v_mfma_f32_16x16x32_bf16 v[100:103], v[176:179], v[200:203], v[100:103]
	v_mfma_f32_16x16x32_bf16 v[96:99], v[184:187], v[200:203], v[96:99]
	v_mfma_f32_16x16x32_bf16 v[84:87], v[176:179], v[208:211], v[84:87]
	v_mfma_f32_16x16x32_bf16 v[80:83], v[184:187], v[208:211], v[80:83]
	v_mfma_f32_16x16x32_bf16 v[68:71], v[176:179], v[216:219], v[68:71]
	v_mfma_f32_16x16x32_bf16 v[64:67], v[184:187], v[216:219], v[64:67]
	s_setprio 0
	s_barrier
	s_add_i32 s26, s43, s15
	v_lshl_add_u64 v[172:173], s[30:31], 0, v[130:131]
	s_mov_b32 m0, s26
	ds_read_b128 v[188:191], v153 offset:16384
	ds_read_b128 v[192:195], v153 offset:17408
	ds_read_b128 v[196:199], v153 offset:18432
	ds_read_b128 v[200:203], v153 offset:19456
	ds_read_b128 v[204:207], v153 offset:20480
	ds_read_b128 v[208:211], v153 offset:21504
	ds_read_b128 v[212:215], v153 offset:22528
	ds_read_b128 v[216:219], v153 offset:23552
	global_load_lds_dwordx4 v[172:173], off
	s_add_i32 m0, s26, 0x2000
	s_add_u32 s26, s30, 0xb0000
	v_lshl_add_u64 v[220:221], s[30:31], 0, v[134:135]
	s_addc_u32 s27, s31, 0
	s_add_i32 s52, s44, s15
	global_load_lds_dwordx4 v[220:221], off
	v_lshl_add_u64 v[222:223], s[26:27], 0, v[130:131]
	s_mov_b32 m0, s52
	v_lshl_add_u64 v[224:225], s[34:35], 0, v[132:133]
	global_load_lds_dwordx4 v[222:223], off
	v_lshl_add_u64 v[222:223], s[26:27], 0, v[134:135]
	s_add_i32 m0, s52, 0x2000
	s_nop 0
	global_load_lds_dwordx4 v[222:223], off
	v_lshl_add_u64 v[222:223], s[34:35], 0, v[128:129]
	s_mov_b32 m0, s16
	s_nop 0
	global_load_lds_dwordx4 v[222:223], off
	s_mov_b32 m0, s17
	s_nop 0
	global_load_lds_dwordx4 v[224:225], off
	s_waitcnt vmcnt(8)
	s_waitcnt lgkmcnt(0)
	s_barrier
	s_setprio 1
	s_waitcnt lgkmcnt(0)
	v_mfma_f32_16x16x32_bf16 v[60:63], v[144:147], v[188:191], v[60:63]
	v_mfma_f32_16x16x32_bf16 v[56:59], v[160:163], v[188:191], v[56:59]
	v_mfma_f32_16x16x32_bf16 v[44:47], v[144:147], v[196:199], v[44:47]
	v_mfma_f32_16x16x32_bf16 v[40:43], v[160:163], v[196:199], v[40:43]
	v_mfma_f32_16x16x32_bf16 v[28:31], v[144:147], v[204:207], v[28:31]
	v_mfma_f32_16x16x32_bf16 v[24:27], v[160:163], v[204:207], v[24:27]
	v_mfma_f32_16x16x32_bf16 v[12:15], v[144:147], v[212:215], v[12:15]
	v_mfma_f32_16x16x32_bf16 v[8:11], v[160:163], v[212:215], v[8:11]
	v_mfma_f32_16x16x32_bf16 v[60:63], v[156:159], v[192:195], v[60:63]
	v_mfma_f32_16x16x32_bf16 v[56:59], v[164:167], v[192:195], v[56:59]
	v_mfma_f32_16x16x32_bf16 v[44:47], v[156:159], v[200:203], v[44:47]
	v_mfma_f32_16x16x32_bf16 v[40:43], v[164:167], v[200:203], v[40:43]
	v_mfma_f32_16x16x32_bf16 v[28:31], v[156:159], v[208:211], v[28:31]
	v_mfma_f32_16x16x32_bf16 v[24:27], v[164:167], v[208:211], v[24:27]
	v_mfma_f32_16x16x32_bf16 v[12:15], v[156:159], v[216:219], v[12:15]
	v_mfma_f32_16x16x32_bf16 v[8:11], v[164:167], v[216:219], v[8:11]
	v_mfma_f32_16x16x32_bf16 v[52:55], v[168:171], v[188:191], v[52:55]
	v_mfma_f32_16x16x32_bf16 v[48:51], v[180:183], v[188:191], v[48:51]
	v_mfma_f32_16x16x32_bf16 v[36:39], v[168:171], v[196:199], v[36:39]
	v_mfma_f32_16x16x32_bf16 v[32:35], v[180:183], v[196:199], v[32:35]
	v_mfma_f32_16x16x32_bf16 v[20:23], v[168:171], v[204:207], v[20:23]
	v_mfma_f32_16x16x32_bf16 v[16:19], v[180:183], v[204:207], v[16:19]
	v_mfma_f32_16x16x32_bf16 v[4:7], v[168:171], v[212:215], v[4:7]
	v_mfma_f32_16x16x32_bf16 v[0:3], v[180:183], v[212:215], v[0:3]
	v_mfma_f32_16x16x32_bf16 v[52:55], v[176:179], v[192:195], v[52:55]
	v_mfma_f32_16x16x32_bf16 v[48:51], v[184:187], v[192:195], v[48:51]
	v_mfma_f32_16x16x32_bf16 v[36:39], v[176:179], v[200:203], v[36:39]
	v_mfma_f32_16x16x32_bf16 v[32:35], v[184:187], v[200:203], v[32:35]
	v_mfma_f32_16x16x32_bf16 v[20:23], v[176:179], v[208:211], v[20:23]
	v_mfma_f32_16x16x32_bf16 v[16:19], v[184:187], v[208:211], v[16:19]
	v_mfma_f32_16x16x32_bf16 v[4:7], v[176:179], v[216:219], v[4:7]
	v_mfma_f32_16x16x32_bf16 v[0:3], v[184:187], v[216:219], v[0:3]
	s_setprio 0
	s_barrier
	s_add_i32 s52, 0, 0x18000
	v_add_u32_e32 v155, s52, v149
	s_add_i32 s53, 0, 0x1c000
	ds_read_b128 v[144:147], v155
	ds_read_b128 v[156:159], v155 offset:1024
	ds_read_b128 v[160:163], v155 offset:2048
	ds_read_b128 v[164:167], v155 offset:3072
	v_add_u32_e32 v155, s53, v149
	ds_read_b128 v[168:171], v155
	ds_read_b128 v[176:179], v155 offset:1024
	ds_read_b128 v[180:183], v155 offset:2048
	ds_read_b128 v[184:187], v155 offset:3072
	s_add_u32 s26, s34, 0xb0000
	s_addc_u32 s27, s35, 0
	s_mov_b32 m0, s36
	v_lshl_add_u64 v[226:227], s[26:27], 0, v[128:129]
	ds_read_b128 v[188:191], v153 offset:32768
	ds_read_b128 v[192:195], v153 offset:33792
	ds_read_b128 v[196:199], v153 offset:34816
	ds_read_b128 v[200:203], v153 offset:35840
	ds_read_b128 v[204:207], v153 offset:36864
	ds_read_b128 v[208:211], v153 offset:37888
	ds_read_b128 v[212:215], v153 offset:38912
	ds_read_b128 v[216:219], v153 offset:39936
	global_load_lds_dwordx4 v[226:227], off
	v_lshl_add_u64 v[226:227], s[26:27], 0, v[132:133]
	s_mov_b32 m0, s37
	s_nop 0
	global_load_lds_dwordx4 v[226:227], off
	s_waitcnt vmcnt(8)
	s_waitcnt lgkmcnt(0)
	s_barrier
	s_setprio 1
	s_waitcnt lgkmcnt(0)
	v_mfma_f32_16x16x32_bf16 v[124:127], v[144:147], v[188:191], v[124:127]
	v_mfma_f32_16x16x32_bf16 v[120:123], v[160:163], v[188:191], v[120:123]
	v_mfma_f32_16x16x32_bf16 v[108:111], v[144:147], v[196:199], v[108:111]
	v_mfma_f32_16x16x32_bf16 v[104:107], v[160:163], v[196:199], v[104:107]
	v_mfma_f32_16x16x32_bf16 v[92:95], v[144:147], v[204:207], v[92:95]
	v_mfma_f32_16x16x32_bf16 v[88:91], v[160:163], v[204:207], v[88:91]
	v_mfma_f32_16x16x32_bf16 v[76:79], v[144:147], v[212:215], v[76:79]
	v_mfma_f32_16x16x32_bf16 v[72:75], v[160:163], v[212:215], v[72:75]
	v_mfma_f32_16x16x32_bf16 v[124:127], v[156:159], v[192:195], v[124:127]
	v_mfma_f32_16x16x32_bf16 v[120:123], v[164:167], v[192:195], v[120:123]
	v_mfma_f32_16x16x32_bf16 v[108:111], v[156:159], v[200:203], v[108:111]
	v_mfma_f32_16x16x32_bf16 v[104:107], v[164:167], v[200:203], v[104:107]
	v_mfma_f32_16x16x32_bf16 v[92:95], v[156:159], v[208:211], v[92:95]
	v_mfma_f32_16x16x32_bf16 v[88:91], v[164:167], v[208:211], v[88:91]
	v_mfma_f32_16x16x32_bf16 v[76:79], v[156:159], v[216:219], v[76:79]
	v_mfma_f32_16x16x32_bf16 v[72:75], v[164:167], v[216:219], v[72:75]
	v_mfma_f32_16x16x32_bf16 v[116:119], v[168:171], v[188:191], v[116:119]
	v_mfma_f32_16x16x32_bf16 v[112:115], v[180:183], v[188:191], v[112:115]
	v_mfma_f32_16x16x32_bf16 v[100:103], v[168:171], v[196:199], v[100:103]
	v_mfma_f32_16x16x32_bf16 v[96:99], v[180:183], v[196:199], v[96:99]
	v_mfma_f32_16x16x32_bf16 v[84:87], v[168:171], v[204:207], v[84:87]
	v_mfma_f32_16x16x32_bf16 v[80:83], v[180:183], v[204:207], v[80:83]
	v_mfma_f32_16x16x32_bf16 v[68:71], v[168:171], v[212:215], v[68:71]
	v_mfma_f32_16x16x32_bf16 v[64:67], v[180:183], v[212:215], v[64:67]
	v_mfma_f32_16x16x32_bf16 v[116:119], v[176:179], v[192:195], v[116:119]
	v_mfma_f32_16x16x32_bf16 v[112:115], v[184:187], v[192:195], v[112:115]
	v_mfma_f32_16x16x32_bf16 v[100:103], v[176:179], v[200:203], v[100:103]
	v_mfma_f32_16x16x32_bf16 v[96:99], v[184:187], v[200:203], v[96:99]
	v_mfma_f32_16x16x32_bf16 v[84:87], v[176:179], v[208:211], v[84:87]
	v_mfma_f32_16x16x32_bf16 v[80:83], v[184:187], v[208:211], v[80:83]
	v_mfma_f32_16x16x32_bf16 v[68:71], v[176:179], v[216:219], v[68:71]
	v_mfma_f32_16x16x32_bf16 v[64:67], v[184:187], v[216:219], v[64:67]
	s_setprio 0
	s_barrier
	s_add_i32 s26, s52, s15
	v_lshl_add_u64 v[172:173], v[172:173], 0, s[20:21]
	s_mov_b32 m0, s26
	ds_read_b128 v[188:191], v153 offset:49152
	ds_read_b128 v[192:195], v153 offset:50176
	ds_read_b128 v[196:199], v153 offset:51200
	ds_read_b128 v[200:203], v153 offset:52224
	ds_read_b128 v[204:207], v153 offset:53248
	ds_read_b128 v[208:211], v153 offset:54272
	ds_read_b128 v[212:215], v153 offset:55296
	ds_read_b128 v[216:219], v153 offset:56320
	global_load_lds_dwordx4 v[172:173], off
	s_add_i32 m0, s26, 0x2000
	s_add_u32 s26, s30, 0xb0080
	v_lshl_add_u64 v[172:173], v[220:221], 0, s[20:21]
	s_addc_u32 s27, s31, 0
	s_add_i32 s30, s53, s15
	global_load_lds_dwordx4 v[172:173], off
	v_lshl_add_u64 v[172:173], s[26:27], 0, v[130:131]
	s_mov_b32 m0, s30
	s_nop 0
	global_load_lds_dwordx4 v[172:173], off
	v_lshl_add_u64 v[172:173], s[26:27], 0, v[134:135]
	s_add_i32 m0, s30, 0x2000
	s_nop 0
	global_load_lds_dwordx4 v[172:173], off
	v_lshl_add_u64 v[172:173], v[222:223], 0, s[20:21]
	s_mov_b32 m0, s39
	s_nop 0
	global_load_lds_dwordx4 v[172:173], off
	v_lshl_add_u64 v[172:173], v[224:225], 0, s[20:21]
	s_mov_b32 m0, s40
	s_nop 0
	global_load_lds_dwordx4 v[172:173], off
	s_waitcnt vmcnt(8)
	s_waitcnt lgkmcnt(0)
	s_barrier
	s_setprio 1
	s_waitcnt lgkmcnt(0)
	v_mfma_f32_16x16x32_bf16 v[60:63], v[144:147], v[188:191], v[60:63]
	v_mfma_f32_16x16x32_bf16 v[56:59], v[160:163], v[188:191], v[56:59]
	v_mfma_f32_16x16x32_bf16 v[44:47], v[144:147], v[196:199], v[44:47]
	v_mfma_f32_16x16x32_bf16 v[40:43], v[160:163], v[196:199], v[40:43]
	v_mfma_f32_16x16x32_bf16 v[28:31], v[144:147], v[204:207], v[28:31]
	v_mfma_f32_16x16x32_bf16 v[24:27], v[160:163], v[204:207], v[24:27]
	v_mfma_f32_16x16x32_bf16 v[12:15], v[144:147], v[212:215], v[12:15]
	v_mfma_f32_16x16x32_bf16 v[8:11], v[160:163], v[212:215], v[8:11]
	v_mfma_f32_16x16x32_bf16 v[60:63], v[156:159], v[192:195], v[60:63]
	v_mfma_f32_16x16x32_bf16 v[56:59], v[164:167], v[192:195], v[56:59]
	v_mfma_f32_16x16x32_bf16 v[44:47], v[156:159], v[200:203], v[44:47]
	v_mfma_f32_16x16x32_bf16 v[40:43], v[164:167], v[200:203], v[40:43]
	v_mfma_f32_16x16x32_bf16 v[28:31], v[156:159], v[208:211], v[28:31]
	v_mfma_f32_16x16x32_bf16 v[24:27], v[164:167], v[208:211], v[24:27]
	v_mfma_f32_16x16x32_bf16 v[12:15], v[156:159], v[216:219], v[12:15]
	v_mfma_f32_16x16x32_bf16 v[8:11], v[164:167], v[216:219], v[8:11]
	v_mfma_f32_16x16x32_bf16 v[52:55], v[168:171], v[188:191], v[52:55]
	v_mfma_f32_16x16x32_bf16 v[48:51], v[180:183], v[188:191], v[48:51]
	v_mfma_f32_16x16x32_bf16 v[36:39], v[168:171], v[196:199], v[36:39]
	v_mfma_f32_16x16x32_bf16 v[32:35], v[180:183], v[196:199], v[32:35]
	v_mfma_f32_16x16x32_bf16 v[20:23], v[168:171], v[204:207], v[20:23]
	v_mfma_f32_16x16x32_bf16 v[16:19], v[180:183], v[204:207], v[16:19]
	v_mfma_f32_16x16x32_bf16 v[4:7], v[168:171], v[212:215], v[4:7]
	v_mfma_f32_16x16x32_bf16 v[0:3], v[180:183], v[212:215], v[0:3]
	v_mfma_f32_16x16x32_bf16 v[52:55], v[176:179], v[192:195], v[52:55]
	v_mfma_f32_16x16x32_bf16 v[48:51], v[184:187], v[192:195], v[48:51]
	v_mfma_f32_16x16x32_bf16 v[36:39], v[176:179], v[200:203], v[36:39]
	v_mfma_f32_16x16x32_bf16 v[32:35], v[184:187], v[200:203], v[32:35]
	v_mfma_f32_16x16x32_bf16 v[20:23], v[176:179], v[208:211], v[20:23]
	v_mfma_f32_16x16x32_bf16 v[16:19], v[184:187], v[208:211], v[16:19]
	v_mfma_f32_16x16x32_bf16 v[4:7], v[176:179], v[216:219], v[4:7]
	v_mfma_f32_16x16x32_bf16 v[0:3], v[184:187], v[216:219], v[0:3]
	s_setprio 0
	s_barrier
	s_add_i32 s51, s51, 2
	s_add_u32 s49, s49, 0x100
	s_addc_u32 s50, s50, 0
	s_cmp_gt_u32 s51, 41
	s_mov_b64 s[26:27], s[28:29]
	s_cbranch_scc0 .LBB0_1684
